# GEMM K-loops: LDS-DMA piece issued after the first MFMA of each group (address and M0 formed in the previous group's last gaps)
# baseline (speedup 1.0000x reference)
; template <class Epi>
; DI void gemm_tile256(const u16* __restrict__ Ag, long lda, const u16* __restrict__ Bg, long ldb, int nk, char* shm, Epi&& epi) {
;   const int tid = RTID, wid = tid >> 6, lane = tid & 63, wr = wid >> 2, wc = wid & 3, fr = lane & 15, fq = lane >> 4;
;   f32x4 acc[8][4];
; #pragma unroll
;   for (int m = 0; m < 8; ++m)
; #pragma unroll
;     for (int n = 0; n < 4; ++n) acc[m][n] = f32x4{0.f, 0.f, 0.f, 0.f};
;   const int q0 = tid, q1 = 512 + tid;
;   const int r0 = q0 >> 2, r1 = q1 >> 2, c0 = (q0 & 3) ^ ((r0 >> 2) & 3), c1 = (q1 & 3) ^ ((r1 >> 2) & 3);
;   const u16* a0 = Ag + (long)r0 * lda + c0 * 8; const u16* a1 = Ag + (long)r1 * lda + c1 * 8;
;   const u16* b0 = Bg + (long)r0 * ldb + c0 * 8; const u16* b1 = Bg + (long)r1 * ldb + c1 * 8;
;   auto stage = [&](int j) {
;     char* SA = shm + (j & 3) * 32768; char* SB = SA + 16384;
;     __builtin_amdgcn_global_load_lds((const unsigned*)(a0 + j * 32), (__attribute__((address_space(3))) unsigned*)(SA + q0 * 16), 16, 0, 0);
;     __builtin_amdgcn_global_load_lds((const unsigned*)(a1 + j * 32), (__attribute__((address_space(3))) unsigned*)(SA + q1 * 16), 16, 0, 0);
;     __builtin_amdgcn_global_load_lds((const unsigned*)(b0 + j * 32), (__attribute__((address_space(3))) unsigned*)(SB + q0 * 16), 16, 0, 0);
;     __builtin_amdgcn_global_load_lds((const unsigned*)(b1 + j * 32), (__attribute__((address_space(3))) unsigned*)(SB + q1 * 16), 16, 0, 0);
;   };
;   __syncthreads();
;   stage(0);
;   if (nk > 1) stage(1);
;   if (nk > 2) stage(2);
;   for (int i = 0; i < nk; ++i) {
;     if (i + 2 < nk) asm volatile("s_waitcnt vmcnt(8)" ::: "memory");
;     else if (i + 1 < nk) asm volatile("s_waitcnt vmcnt(4)" ::: "memory");
;     else asm volatile("s_waitcnt vmcnt(0)" ::: "memory");
;     __builtin_amdgcn_s_barrier();
;     const char* SA = shm + (i & 3) * 32768; const char* SB = SA + 16384;
;     bf16x8 At[8], Bt[4];
; #pragma unroll
;     for (int n = 0; n < 4; ++n) { const int rb = wc * 64 + n * 16 + fr; Bt[n] = *reinterpret_cast<const bf16x8*>(SB + rb * 64 + ((fq ^ ((rb >> 2) & 3)) * 16)); }
; #pragma unroll
; DI void phase1(const Params& P, char* smem) {
;     ...
;   for (int q = RBLK >> 3; q < 128; q += RGRID >> 3) {
;     const int brow = q * 256, bcol = (RBLK & 7) * 256;
;     gemm_tile256(xb + (long)brow * 1024, 1024, WinT + (long)bcol * 1024, 1024, 32, smem, [&](int row, int col0, f32x4 v) {
.LBB0_107:
	v_lshl_add_u64 v[176:177], v[138:139], 0, 64
	v_lshl_add_u64 v[178:179], v[140:141], 0, 64
	v_lshl_add_u64 v[180:181], v[138:139], 0, s[0:1]
	v_lshl_add_u64 v[182:183], v[140:141], 0, s[0:1]
	s_lshl_b32 s30, s27, 8
	s_ashr_i32 s29, s28, 31
	s_ashr_i32 s31, s30, 31
	s_lshl_b64 s[6:7], s[28:29], 11
	s_lshl_b64 s[4:5], s[30:31], 11
	s_add_u32 s4, s54, s4
	s_addc_u32 s5, s55, s5
	v_add_u32_e32 v6, 0, v209
	v_lshl_add_u64 v[0:1], s[4:5], 0, v[132:133]
	v_lshl_add_u64 v[2:3], s[4:5], 0, v[136:137]
	v_readfirstlane_b32 s4, v6
	v_add_u32_e32 v7, 0, v131
	v_lshl_add_u64 v[0:1], v[0:1], 0, v[134:135]
	s_mov_b32 m0, s4
	v_readfirstlane_b32 s4, v7
	v_add_u32_e32 v4, 0x4000, v6
	v_lshl_add_u64 v[2:3], v[2:3], 0, v[134:135]
	s_barrier
	global_load_lds_dwordx4 v[0:1], off
	s_mov_b32 m0, s4
	v_readfirstlane_b32 s4, v4
	v_add_u32_e32 v4, 0x4000, v7
	global_load_lds_dwordx4 v[2:3], off
	s_mov_b32 m0, s4
	v_readfirstlane_b32 s4, v4
	v_add_u32_e32 v8, 0x8000, v6
	global_load_lds_dwordx4 v[138:139], off
	s_mov_b32 m0, s4
	v_readfirstlane_b32 s4, v8
	v_add_u32_e32 v8, 0x8000, v7
	global_load_lds_dwordx4 v[140:141], off
	v_lshl_add_u64 v[4:5], v[0:1], 0, 64
	s_mov_b32 m0, s4
	v_readfirstlane_b32 s4, v8
	global_load_lds_dwordx4 v[4:5], off
	v_lshl_add_u64 v[4:5], v[2:3], 0, 64
	s_mov_b32 m0, s4
	v_lshl_add_u64 v[0:1], v[0:1], 0, s[0:1]
	global_load_lds_dwordx4 v[4:5], off
	v_add_u32_e32 v4, 0xc000, v6
	s_mov_b32 s8, 0x18000
	v_readfirstlane_b32 s4, v4
	v_add_u32_e32 v4, 0xc000, v7
	s_mov_b32 m0, s4
	v_readfirstlane_b32 s4, v4
	v_add_u32_e32 v4, s2, v209
	global_load_lds_dwordx4 v[176:177], off
	s_mov_b32 m0, s4
	v_readfirstlane_b32 s4, v4
	global_load_lds_dwordx4 v[178:179], off
	s_mov_b32 m0, s4
	v_mov_b32_e32 v4, 0
	global_load_lds_dwordx4 v[0:1], off
	v_lshl_add_u64 v[0:1], v[2:3], 0, s[0:1]
	v_add_u32_e32 v2, s2, v131
	v_mov_b32_e32 v3, v135
	v_readfirstlane_b32 s4, v2
	s_mov_b32 m0, s4
	v_mov_b32_e32 v2, v135
	global_load_lds_dwordx4 v[0:1], off
	v_add_u32_e32 v0, s15, v209
	v_mov_b32_e32 v1, v135
	v_readfirstlane_b32 s4, v0
	v_add_u32_e32 v0, s15, v131
	s_mov_b32 m0, s4
	v_readfirstlane_b32 s4, v0
	global_load_lds_dwordx4 v[180:181], off
	s_mov_b32 m0, s4
	s_mov_b64 s[4:5], 0
	global_load_lds_dwordx4 v[182:183], off
	v_mov_b32_e32 v0, 0
	v_mov_b32_e32 v5, v135
	v_mov_b32_e32 v6, v135
	v_mov_b32_e32 v7, v135
	v_mov_b32_e32 v8, 0
	v_mov_b32_e32 v9, v135
	v_mov_b32_e32 v10, v135
	v_mov_b32_e32 v11, v135
	v_mov_b32_e32 v12, 0
	v_mov_b32_e32 v13, v135
	v_mov_b32_e32 v14, v135
	v_mov_b32_e32 v15, v135
	v_mov_b32_e32 v16, 0
	v_mov_b32_e32 v17, v135
	v_mov_b32_e32 v18, v135
	v_mov_b32_e32 v19, v135
	v_mov_b32_e32 v20, 0
	v_mov_b32_e32 v21, v135
	v_mov_b32_e32 v22, v135
	v_mov_b32_e32 v23, v135
	v_mov_b32_e32 v24, 0
	v_mov_b32_e32 v25, v135
	v_mov_b32_e32 v26, v135
	v_mov_b32_e32 v27, v135
	v_mov_b32_e32 v28, 0
	v_mov_b32_e32 v29, v135
	v_mov_b32_e32 v30, v135
	v_mov_b32_e32 v31, v135
	v_mov_b32_e32 v32, 0
	v_mov_b32_e32 v33, v135
	v_mov_b32_e32 v34, v135
	v_mov_b32_e32 v35, v135
	v_mov_b32_e32 v36, 0
	v_mov_b32_e32 v37, v135
	v_mov_b32_e32 v38, v135
	v_mov_b32_e32 v39, v135
	v_mov_b32_e32 v40, 0
	v_mov_b32_e32 v41, v135
	v_mov_b32_e32 v42, v135
	v_mov_b32_e32 v43, v135
	v_mov_b32_e32 v44, 0
	v_mov_b32_e32 v45, v135
	v_mov_b32_e32 v46, v135
	v_mov_b32_e32 v47, v135
	v_mov_b32_e32 v48, 0
	v_mov_b32_e32 v49, v135
	v_mov_b32_e32 v50, v135
	v_mov_b32_e32 v51, v135
	v_mov_b32_e32 v52, 0
	v_mov_b32_e32 v53, v135
	v_mov_b32_e32 v54, v135
	v_mov_b32_e32 v55, v135
	v_mov_b32_e32 v56, 0
	v_mov_b32_e32 v57, v135
	v_mov_b32_e32 v58, v135
	v_mov_b32_e32 v59, v135
	v_mov_b32_e32 v60, 0
	v_mov_b32_e32 v61, v135
	v_mov_b32_e32 v62, v135
	v_mov_b32_e32 v63, v135
	v_mov_b32_e32 v64, 0
	v_mov_b32_e32 v65, v135
	v_mov_b32_e32 v66, v135
	v_mov_b32_e32 v67, v135
	v_mov_b32_e32 v68, 0
	v_mov_b32_e32 v69, v135
	v_mov_b32_e32 v70, v135
	v_mov_b32_e32 v71, v135
	v_mov_b32_e32 v72, 0
	v_mov_b32_e32 v73, v135
	v_mov_b32_e32 v74, v135
	v_mov_b32_e32 v75, v135
	v_mov_b32_e32 v76, 0
	v_mov_b32_e32 v77, v135
	v_mov_b32_e32 v78, v135
	v_mov_b32_e32 v79, v135
	v_mov_b32_e32 v80, 0
	v_mov_b32_e32 v81, v135
	v_mov_b32_e32 v82, v135
	v_mov_b32_e32 v83, v135
	v_mov_b32_e32 v84, 0
	v_mov_b32_e32 v85, v135
	v_mov_b32_e32 v86, v135
	v_mov_b32_e32 v87, v135
	v_mov_b32_e32 v88, 0
	v_mov_b32_e32 v89, v135
	v_mov_b32_e32 v90, v135
	v_mov_b32_e32 v91, v135
	v_mov_b32_e32 v92, 0
	v_mov_b32_e32 v93, v135
	v_mov_b32_e32 v94, v135
	v_mov_b32_e32 v95, v135
	v_mov_b32_e32 v96, 0
	v_mov_b32_e32 v97, v135
	v_mov_b32_e32 v98, v135
	v_mov_b32_e32 v99, v135
	v_mov_b32_e32 v100, 0
	v_mov_b32_e32 v101, v135
	v_mov_b32_e32 v102, v135
	v_mov_b32_e32 v103, v135
	v_mov_b32_e32 v104, 0
	v_mov_b32_e32 v105, v135
	v_mov_b32_e32 v106, v135
	v_mov_b32_e32 v107, v135
	v_mov_b32_e32 v108, 0
	v_mov_b32_e32 v109, v135
	v_mov_b32_e32 v110, v135
	v_mov_b32_e32 v111, v135
	v_mov_b32_e32 v112, 0
	v_mov_b32_e32 v113, v135
	v_mov_b32_e32 v114, v135
	v_mov_b32_e32 v115, v135
	v_mov_b32_e32 v116, 0
	v_mov_b32_e32 v117, v135
	v_mov_b32_e32 v118, v135
	v_mov_b32_e32 v119, v135
	v_mov_b32_e32 v120, 0
	v_mov_b32_e32 v121, v135
	v_mov_b32_e32 v122, v135
	v_mov_b32_e32 v123, v135
	v_mov_b32_e32 v124, 0
	v_mov_b32_e32 v125, v135
	v_mov_b32_e32 v126, v135
	v_mov_b32_e32 v127, v135
	v_lshl_add_u64 v[184:185], v[168:169], 0, s[6:7]
	v_lshl_add_u64 v[186:187], v[170:171], 0, s[6:7]
	v_readfirstlane_b32 s7, v209
	s_mov_b32 s8, 0
	s_mov_b64 s[4:5], 0
	s_and_b64 vcc, exec, s[24:25]
	s_cbranch_vccz .Lgemm_p1_n
	s_waitcnt vmcnt(8)
	s_barrier
	v_add3_u32 v252, v205, v147, s8
	v_add3_u32 v215, v205, v151, s8
	s_nop 0
	ds_read_b128 v[216:219], v252 offset:16384
	ds_read_b128 v[220:223], v252 offset:17408
	ds_read_b128 v[232:235], v252 offset:18432
	ds_read_b128 v[236:239], v252 offset:19456
	ds_read_b128 v[224:227], v215
	ds_read_b128 v[228:231], v215 offset:1024
	s_add_i32 s9, s7, 0x18000
	v_lshl_add_u64 v[206:207], v[184:185], 0, s[4:5]
	s_mov_b32 m0, s9
	s_add_i32 s9, s9, 0x2000
; template <class Epi>
; DI void gemm_tile256(const u16* __restrict__ Ag, long lda, const u16* __restrict__ Bg, long ldb, int nk, char* shm, Epi&& epi) {
;     ...
;   for (int i = 0; i < nk; ++i) {
;     if (i + 2 < nk) asm volatile("s_waitcnt vmcnt(8)" ::: "memory");
;     else if (i + 1 < nk) asm volatile("s_waitcnt vmcnt(4)" ::: "memory");
;     else asm volatile("s_waitcnt vmcnt(0)" ::: "memory");
;     __builtin_amdgcn_s_barrier();
;     const char* SA = shm + (i & 3) * 32768; const char* SB = SA + 16384;
;     bf16x8 At[8], Bt[4];
; #pragma unroll
;     for (int n = 0; n < 4; ++n) { const int rb = wc * 64 + n * 16 + fr; Bt[n] = *reinterpret_cast<const bf16x8*>(SB + rb * 64 + ((fq ^ ((rb >> 2) & 3)) * 16)); }
; #pragma unroll
;     for (int m = 0; m < 8; ++m) { const int ra = wr * 128 + m * 16 + fr; At[m] = *reinterpret_cast<const bf16x8*>(SA + ra * 64 + ((fq ^ ((ra >> 2) & 3)) * 16)); }
;     if (i + 3 < nk) stage(i + 3);
; #pragma unroll
;     for (int m = 0; m < 8; ++m)
; #pragma unroll
;       for (int n = 0; n < 4; ++n) acc[m][n] = __builtin_amdgcn_mfma_f32_16x16x32_bf16(Bt[n], At[m], acc[m][n], 0, 0, 0);
;   }
.Lgemm_p1_kloopv:
	ds_read_b128 v[180:183], v215 offset:2048
	ds_read_b128 v[210:213], v215 offset:3072
	s_waitcnt lgkmcnt(2)
	v_mfma_f32_16x16x32_bf16 v[124:127], v[224:227], v[216:219], v[124:127]
	global_load_lds_dwordx4 v[206:207], off
	v_mfma_f32_16x16x32_bf16 v[120:123], v[224:227], v[220:223], v[120:123]
	v_mfma_f32_16x16x32_bf16 v[116:119], v[224:227], v[232:235], v[116:119]
	v_mfma_f32_16x16x32_bf16 v[112:115], v[224:227], v[236:239], v[112:115]
	v_mfma_f32_16x16x32_bf16 v[108:111], v[228:231], v[216:219], v[108:111]
	v_mfma_f32_16x16x32_bf16 v[104:107], v[228:231], v[220:223], v[104:107]
	v_lshl_add_u64 v[206:207], v[186:187], 0, s[4:5]
	v_mfma_f32_16x16x32_bf16 v[100:103], v[228:231], v[232:235], v[100:103]
	s_mov_b32 m0, s9
	v_mfma_f32_16x16x32_bf16 v[96:99], v[228:231], v[236:239], v[96:99]
	s_add_i32 s9, s9, 0x2000
	ds_read_b128 v[224:227], v215 offset:4096
	ds_read_b128 v[228:231], v215 offset:5120
	s_waitcnt lgkmcnt(2)
	v_mfma_f32_16x16x32_bf16 v[92:95], v[180:183], v[216:219], v[92:95]
	global_load_lds_dwordx4 v[206:207], off
	v_mfma_f32_16x16x32_bf16 v[88:91], v[180:183], v[220:223], v[88:91]
	v_mfma_f32_16x16x32_bf16 v[84:87], v[180:183], v[232:235], v[84:87]
	v_mfma_f32_16x16x32_bf16 v[80:83], v[180:183], v[236:239], v[80:83]
	v_mfma_f32_16x16x32_bf16 v[76:79], v[210:213], v[216:219], v[76:79]
	v_mfma_f32_16x16x32_bf16 v[72:75], v[210:213], v[220:223], v[72:75]
	v_lshl_add_u64 v[206:207], v[172:173], 0, s[4:5]
	v_mfma_f32_16x16x32_bf16 v[68:71], v[210:213], v[232:235], v[68:71]
	s_mov_b32 m0, s9
	v_mfma_f32_16x16x32_bf16 v[64:67], v[210:213], v[236:239], v[64:67]
	s_add_i32 s9, s9, 0x2000
	ds_read_b128 v[180:183], v215 offset:6144
	ds_read_b128 v[210:213], v215 offset:7168
	s_waitcnt lgkmcnt(2)
	v_mfma_f32_16x16x32_bf16 v[60:63], v[224:227], v[216:219], v[60:63]
	global_load_lds_dwordx4 v[206:207], off
	v_mfma_f32_16x16x32_bf16 v[56:59], v[224:227], v[220:223], v[56:59]
	v_mfma_f32_16x16x32_bf16 v[52:55], v[224:227], v[232:235], v[52:55]
	v_mfma_f32_16x16x32_bf16 v[48:51], v[224:227], v[236:239], v[48:51]
	v_mfma_f32_16x16x32_bf16 v[44:47], v[228:231], v[216:219], v[44:47]
	v_mfma_f32_16x16x32_bf16 v[40:43], v[228:231], v[220:223], v[40:43]
	v_lshl_add_u64 v[206:207], v[174:175], 0, s[4:5]
	v_mfma_f32_16x16x32_bf16 v[36:39], v[228:231], v[232:235], v[36:39]
	s_mov_b32 m0, s9
	v_mfma_f32_16x16x32_bf16 v[32:35], v[228:231], v[236:239], v[32:35]
	s_add_i32 s9, s9, 0x2000
	s_add_u32 s4, s4, 64
	s_addc_u32 s5, s5, 0
	s_add_i32 s8, s8, 0x8000
	s_and_b32 s8, s8, 0x18000
	s_waitcnt vmcnt(7) lgkmcnt(0)
	s_barrier
	v_add3_u32 v252, v205, v147, s8
	v_add3_u32 v215, v205, v151, s8
	s_nop 0
	ds_read_b128 v[240:243], v252 offset:16384
	ds_read_b128 v[244:247], v252 offset:17408
	ds_read_b128 v[248:251], v252 offset:18432
	ds_read_b128 v[176:179], v252 offset:19456
	ds_read_b128 v[224:227], v215
	ds_read_b128 v[228:231], v215 offset:1024
	v_mfma_f32_16x16x32_bf16 v[28:31], v[180:183], v[216:219], v[28:31]
	global_load_lds_dwordx4 v[206:207], off
	v_mfma_f32_16x16x32_bf16 v[24:27], v[180:183], v[220:223], v[24:27]
	v_mfma_f32_16x16x32_bf16 v[20:23], v[180:183], v[232:235], v[20:23]
	v_mfma_f32_16x16x32_bf16 v[16:19], v[180:183], v[236:239], v[16:19]
	v_mfma_f32_16x16x32_bf16 v[12:15], v[210:213], v[216:219], v[12:15]
	v_mfma_f32_16x16x32_bf16 v[8:11], v[210:213], v[220:223], v[8:11]
	s_add_i32 s6, s8, 0x18000
	v_mfma_f32_16x16x32_bf16 v[4:7], v[210:213], v[232:235], v[4:7]
	s_and_b32 s6, s6, 0x18000
	v_mfma_f32_16x16x32_bf16 v[0:3], v[210:213], v[236:239], v[0:3]
	s_add_i32 s9, s6, s7
	v_lshl_add_u64 v[206:207], v[184:185], 0, s[4:5]
	s_mov_b32 m0, s9
	s_add_i32 s9, s9, 0x2000
	ds_read_b128 v[180:183], v215 offset:2048
	ds_read_b128 v[210:213], v215 offset:3072
	s_waitcnt lgkmcnt(2)
	v_mfma_f32_16x16x32_bf16 v[124:127], v[224:227], v[240:243], v[124:127]
	global_load_lds_dwordx4 v[206:207], off
	v_mfma_f32_16x16x32_bf16 v[120:123], v[224:227], v[244:247], v[120:123]
	v_mfma_f32_16x16x32_bf16 v[116:119], v[224:227], v[248:251], v[116:119]
	v_mfma_f32_16x16x32_bf16 v[112:115], v[224:227], v[176:179], v[112:115]
	v_mfma_f32_16x16x32_bf16 v[108:111], v[228:231], v[240:243], v[108:111]
	v_mfma_f32_16x16x32_bf16 v[104:107], v[228:231], v[244:247], v[104:107]
	v_lshl_add_u64 v[206:207], v[186:187], 0, s[4:5]
	v_mfma_f32_16x16x32_bf16 v[100:103], v[228:231], v[248:251], v[100:103]
	s_mov_b32 m0, s9
	v_mfma_f32_16x16x32_bf16 v[96:99], v[228:231], v[176:179], v[96:99]
	s_add_i32 s9, s9, 0x2000
	ds_read_b128 v[224:227], v215 offset:4096
	ds_read_b128 v[228:231], v215 offset:5120
	s_waitcnt lgkmcnt(2)
	v_mfma_f32_16x16x32_bf16 v[92:95], v[180:183], v[240:243], v[92:95]
	global_load_lds_dwordx4 v[206:207], off
	v_mfma_f32_16x16x32_bf16 v[88:91], v[180:183], v[244:247], v[88:91]
	v_mfma_f32_16x16x32_bf16 v[84:87], v[180:183], v[248:251], v[84:87]
	v_mfma_f32_16x16x32_bf16 v[80:83], v[180:183], v[176:179], v[80:83]
	v_mfma_f32_16x16x32_bf16 v[76:79], v[210:213], v[240:243], v[76:79]
	v_mfma_f32_16x16x32_bf16 v[72:75], v[210:213], v[244:247], v[72:75]
	v_lshl_add_u64 v[206:207], v[172:173], 0, s[4:5]
	v_mfma_f32_16x16x32_bf16 v[68:71], v[210:213], v[248:251], v[68:71]
	s_mov_b32 m0, s9
	v_mfma_f32_16x16x32_bf16 v[64:67], v[210:213], v[176:179], v[64:67]
	s_add_i32 s9, s9, 0x2000
	ds_read_b128 v[180:183], v215 offset:6144
	ds_read_b128 v[210:213], v215 offset:7168
	s_waitcnt lgkmcnt(2)
	v_mfma_f32_16x16x32_bf16 v[60:63], v[224:227], v[240:243], v[60:63]
	global_load_lds_dwordx4 v[206:207], off
	v_mfma_f32_16x16x32_bf16 v[56:59], v[224:227], v[244:247], v[56:59]
	v_mfma_f32_16x16x32_bf16 v[52:55], v[224:227], v[248:251], v[52:55]
	v_mfma_f32_16x16x32_bf16 v[48:51], v[224:227], v[176:179], v[48:51]
	v_mfma_f32_16x16x32_bf16 v[44:47], v[228:231], v[240:243], v[44:47]
	v_mfma_f32_16x16x32_bf16 v[40:43], v[228:231], v[244:247], v[40:43]
	v_lshl_add_u64 v[206:207], v[174:175], 0, s[4:5]
	v_mfma_f32_16x16x32_bf16 v[36:39], v[228:231], v[248:251], v[36:39]
	s_mov_b32 m0, s9
	v_mfma_f32_16x16x32_bf16 v[32:35], v[228:231], v[176:179], v[32:35]
	s_add_i32 s9, s9, 0x2000
	s_add_u32 s4, s4, 64
	s_addc_u32 s5, s5, 0
	s_add_i32 s8, s8, 0x8000
	s_and_b32 s8, s8, 0x18000
	s_waitcnt vmcnt(7) lgkmcnt(0)
	s_barrier
; template <class Epi>
; DI void gemm_tile256(const u16* __restrict__ Ag, long lda, const u16* __restrict__ Bg, long ldb, int nk, char* shm, Epi&& epi) {
;     ...
;   for (int i = 0; i < nk; ++i) {
;     if (i + 2 < nk) asm volatile("s_waitcnt vmcnt(8)" ::: "memory");
;     else if (i + 1 < nk) asm volatile("s_waitcnt vmcnt(4)" ::: "memory");
;     else asm volatile("s_waitcnt vmcnt(0)" ::: "memory");
;     __builtin_amdgcn_s_barrier();
;     const char* SA = shm + (i & 3) * 32768; const char* SB = SA + 16384;
;     bf16x8 At[8], Bt[4];
; #pragma unroll
;     for (int n = 0; n < 4; ++n) { const int rb = wc * 64 + n * 16 + fr; Bt[n] = *reinterpret_cast<const bf16x8*>(SB + rb * 64 + ((fq ^ ((rb >> 2) & 3)) * 16)); }
; #pragma unroll
;     for (int m = 0; m < 8; ++m) { const int ra = wr * 128 + m * 16 + fr; At[m] = *reinterpret_cast<const bf16x8*>(SA + ra * 64 + ((fq ^ ((ra >> 2) & 3)) * 16)); }
;     if (i + 3 < nk) stage(i + 3);
; #pragma unroll
;     for (int m = 0; m < 8; ++m)
; #pragma unroll
;       for (int n = 0; n < 4; ++n) acc[m][n] = __builtin_amdgcn_mfma_f32_16x16x32_bf16(Bt[n], At[m], acc[m][n], 0, 0, 0);
;   }
	v_add3_u32 v252, v205, v147, s8
	v_add3_u32 v215, v205, v151, s8
	s_nop 0
	ds_read_b128 v[216:219], v252 offset:16384
	ds_read_b128 v[220:223], v252 offset:17408
	ds_read_b128 v[232:235], v252 offset:18432
	ds_read_b128 v[236:239], v252 offset:19456
	ds_read_b128 v[224:227], v215
	ds_read_b128 v[228:231], v215 offset:1024
	v_mfma_f32_16x16x32_bf16 v[28:31], v[180:183], v[240:243], v[28:31]
	global_load_lds_dwordx4 v[206:207], off
	v_mfma_f32_16x16x32_bf16 v[24:27], v[180:183], v[244:247], v[24:27]
	v_mfma_f32_16x16x32_bf16 v[20:23], v[180:183], v[248:251], v[20:23]
	v_mfma_f32_16x16x32_bf16 v[16:19], v[180:183], v[176:179], v[16:19]
	v_mfma_f32_16x16x32_bf16 v[12:15], v[210:213], v[240:243], v[12:15]
	v_mfma_f32_16x16x32_bf16 v[8:11], v[210:213], v[244:247], v[8:11]
	s_add_i32 s6, s8, 0x18000
	v_mfma_f32_16x16x32_bf16 v[4:7], v[210:213], v[248:251], v[4:7]
	s_and_b32 s6, s6, 0x18000
	v_mfma_f32_16x16x32_bf16 v[0:3], v[210:213], v[176:179], v[0:3]
	s_add_i32 s9, s6, s7
	v_lshl_add_u64 v[206:207], v[184:185], 0, s[4:5]
	s_mov_b32 m0, s9
	s_add_i32 s9, s9, 0x2000
	s_cmpk_lg_i32 s4, 0x700
	s_cbranch_scc1 .Lgemm_p1_kloopv
	ds_read_b128 v[180:183], v215 offset:2048
	ds_read_b128 v[210:213], v215 offset:3072
	s_waitcnt lgkmcnt(2)
	v_mfma_f32_16x16x32_bf16 v[124:127], v[224:227], v[216:219], v[124:127]
	global_load_lds_dwordx4 v[206:207], off
	v_mfma_f32_16x16x32_bf16 v[120:123], v[224:227], v[220:223], v[120:123]
	v_mfma_f32_16x16x32_bf16 v[116:119], v[224:227], v[232:235], v[116:119]
	v_mfma_f32_16x16x32_bf16 v[112:115], v[224:227], v[236:239], v[112:115]
	v_mfma_f32_16x16x32_bf16 v[108:111], v[228:231], v[216:219], v[108:111]
	v_mfma_f32_16x16x32_bf16 v[104:107], v[228:231], v[220:223], v[104:107]
	v_lshl_add_u64 v[206:207], v[186:187], 0, s[4:5]
	v_mfma_f32_16x16x32_bf16 v[100:103], v[228:231], v[232:235], v[100:103]
	s_mov_b32 m0, s9
	v_mfma_f32_16x16x32_bf16 v[96:99], v[228:231], v[236:239], v[96:99]
	s_add_i32 s9, s9, 0x2000
	ds_read_b128 v[224:227], v215 offset:4096
	ds_read_b128 v[228:231], v215 offset:5120
	s_waitcnt lgkmcnt(2)
	v_mfma_f32_16x16x32_bf16 v[92:95], v[180:183], v[216:219], v[92:95]
	global_load_lds_dwordx4 v[206:207], off
	v_mfma_f32_16x16x32_bf16 v[88:91], v[180:183], v[220:223], v[88:91]
	v_mfma_f32_16x16x32_bf16 v[84:87], v[180:183], v[232:235], v[84:87]
	v_mfma_f32_16x16x32_bf16 v[80:83], v[180:183], v[236:239], v[80:83]
	v_mfma_f32_16x16x32_bf16 v[76:79], v[210:213], v[216:219], v[76:79]
	v_mfma_f32_16x16x32_bf16 v[72:75], v[210:213], v[220:223], v[72:75]
	v_lshl_add_u64 v[206:207], v[172:173], 0, s[4:5]
	v_mfma_f32_16x16x32_bf16 v[68:71], v[210:213], v[232:235], v[68:71]
	s_mov_b32 m0, s9
	v_mfma_f32_16x16x32_bf16 v[64:67], v[210:213], v[236:239], v[64:67]
	s_add_i32 s9, s9, 0x2000
	ds_read_b128 v[180:183], v215 offset:6144
	ds_read_b128 v[210:213], v215 offset:7168
	s_waitcnt lgkmcnt(2)
	v_mfma_f32_16x16x32_bf16 v[60:63], v[224:227], v[216:219], v[60:63]
	global_load_lds_dwordx4 v[206:207], off
	v_mfma_f32_16x16x32_bf16 v[56:59], v[224:227], v[220:223], v[56:59]
	v_mfma_f32_16x16x32_bf16 v[52:55], v[224:227], v[232:235], v[52:55]
	v_mfma_f32_16x16x32_bf16 v[48:51], v[224:227], v[236:239], v[48:51]
	v_mfma_f32_16x16x32_bf16 v[44:47], v[228:231], v[216:219], v[44:47]
	v_mfma_f32_16x16x32_bf16 v[40:43], v[228:231], v[220:223], v[40:43]
	v_lshl_add_u64 v[206:207], v[174:175], 0, s[4:5]
	v_mfma_f32_16x16x32_bf16 v[36:39], v[228:231], v[232:235], v[36:39]
	s_mov_b32 m0, s9
	v_mfma_f32_16x16x32_bf16 v[32:35], v[228:231], v[236:239], v[32:35]
	s_add_i32 s9, s9, 0x2000
	s_add_u32 s4, s4, 64
	s_addc_u32 s5, s5, 0
	s_add_i32 s8, s8, 0x8000
	s_and_b32 s8, s8, 0x18000
	s_waitcnt vmcnt(7) lgkmcnt(0)
	s_barrier
	v_add3_u32 v252, v205, v147, s8
	v_add3_u32 v215, v205, v151, s8
	s_nop 0
	ds_read_b128 v[240:243], v252 offset:16384
	ds_read_b128 v[244:247], v252 offset:17408
	ds_read_b128 v[248:251], v252 offset:18432
	ds_read_b128 v[176:179], v252 offset:19456
	ds_read_b128 v[224:227], v215
	ds_read_b128 v[228:231], v215 offset:1024
	v_mfma_f32_16x16x32_bf16 v[28:31], v[180:183], v[216:219], v[28:31]
	global_load_lds_dwordx4 v[206:207], off
	v_mfma_f32_16x16x32_bf16 v[24:27], v[180:183], v[220:223], v[24:27]
	v_mfma_f32_16x16x32_bf16 v[20:23], v[180:183], v[232:235], v[20:23]
	v_mfma_f32_16x16x32_bf16 v[16:19], v[180:183], v[236:239], v[16:19]
	v_mfma_f32_16x16x32_bf16 v[12:15], v[210:213], v[216:219], v[12:15]
	v_mfma_f32_16x16x32_bf16 v[8:11], v[210:213], v[220:223], v[8:11]
	v_mfma_f32_16x16x32_bf16 v[4:7], v[210:213], v[232:235], v[4:7]
	v_mfma_f32_16x16x32_bf16 v[0:3], v[210:213], v[236:239], v[0:3]
	ds_read_b128 v[180:183], v215 offset:2048
	ds_read_b128 v[210:213], v215 offset:3072
	s_waitcnt lgkmcnt(2)
	v_mfma_f32_16x16x32_bf16 v[124:127], v[224:227], v[240:243], v[124:127]
	v_mfma_f32_16x16x32_bf16 v[120:123], v[224:227], v[244:247], v[120:123]
	v_mfma_f32_16x16x32_bf16 v[116:119], v[224:227], v[248:251], v[116:119]
	v_mfma_f32_16x16x32_bf16 v[112:115], v[224:227], v[176:179], v[112:115]
	v_mfma_f32_16x16x32_bf16 v[108:111], v[228:231], v[240:243], v[108:111]
	v_mfma_f32_16x16x32_bf16 v[104:107], v[228:231], v[244:247], v[104:107]
	v_mfma_f32_16x16x32_bf16 v[100:103], v[228:231], v[248:251], v[100:103]
	v_mfma_f32_16x16x32_bf16 v[96:99], v[228:231], v[176:179], v[96:99]
	ds_read_b128 v[224:227], v215 offset:4096
	ds_read_b128 v[228:231], v215 offset:5120
	s_waitcnt lgkmcnt(2)
	v_mfma_f32_16x16x32_bf16 v[92:95], v[180:183], v[240:243], v[92:95]
	v_mfma_f32_16x16x32_bf16 v[88:91], v[180:183], v[244:247], v[88:91]
	v_mfma_f32_16x16x32_bf16 v[84:87], v[180:183], v[248:251], v[84:87]
	v_mfma_f32_16x16x32_bf16 v[80:83], v[180:183], v[176:179], v[80:83]
	v_mfma_f32_16x16x32_bf16 v[76:79], v[210:213], v[240:243], v[76:79]
	v_mfma_f32_16x16x32_bf16 v[72:75], v[210:213], v[244:247], v[72:75]
	v_mfma_f32_16x16x32_bf16 v[68:71], v[210:213], v[248:251], v[68:71]
	v_mfma_f32_16x16x32_bf16 v[64:67], v[210:213], v[176:179], v[64:67]
	ds_read_b128 v[180:183], v215 offset:6144
	ds_read_b128 v[210:213], v215 offset:7168
	s_waitcnt lgkmcnt(2)
	v_mfma_f32_16x16x32_bf16 v[60:63], v[224:227], v[240:243], v[60:63]
	v_mfma_f32_16x16x32_bf16 v[56:59], v[224:227], v[244:247], v[56:59]
	v_mfma_f32_16x16x32_bf16 v[52:55], v[224:227], v[248:251], v[52:55]
	v_mfma_f32_16x16x32_bf16 v[48:51], v[224:227], v[176:179], v[48:51]
	v_mfma_f32_16x16x32_bf16 v[44:47], v[228:231], v[240:243], v[44:47]
	v_mfma_f32_16x16x32_bf16 v[40:43], v[228:231], v[244:247], v[40:43]
	v_mfma_f32_16x16x32_bf16 v[36:39], v[228:231], v[248:251], v[36:39]
	v_mfma_f32_16x16x32_bf16 v[32:35], v[228:231], v[176:179], v[32:35]
	s_add_i32 s8, s8, 0x8000
	s_and_b32 s8, s8, 0x18000
	s_waitcnt vmcnt(4) lgkmcnt(0)
	s_barrier
; template <class Epi>
; DI void gemm_tile256(const u16* __restrict__ Ag, long lda, const u16* __restrict__ Bg, long ldb, int nk, char* shm, Epi&& epi) {
;     ...
;   for (int i = 0; i < nk; ++i) {
;     if (i + 2 < nk) asm volatile("s_waitcnt vmcnt(8)" ::: "memory");
;     else if (i + 1 < nk) asm volatile("s_waitcnt vmcnt(4)" ::: "memory");
;     else asm volatile("s_waitcnt vmcnt(0)" ::: "memory");
;     __builtin_amdgcn_s_barrier();
;     const char* SA = shm + (i & 3) * 32768; const char* SB = SA + 16384;
;     bf16x8 At[8], Bt[4];
; #pragma unroll
;     for (int n = 0; n < 4; ++n) { const int rb = wc * 64 + n * 16 + fr; Bt[n] = *reinterpret_cast<const bf16x8*>(SB + rb * 64 + ((fq ^ ((rb >> 2) & 3)) * 16)); }
; #pragma unroll
;     for (int m = 0; m < 8; ++m) { const int ra = wr * 128 + m * 16 + fr; At[m] = *reinterpret_cast<const bf16x8*>(SA + ra * 64 + ((fq ^ ((ra >> 2) & 3)) * 16)); }
;     if (i + 3 < nk) stage(i + 3);
; #pragma unroll
;     for (int m = 0; m < 8; ++m)
; #pragma unroll
;       for (int n = 0; n < 4; ++n) acc[m][n] = __builtin_amdgcn_mfma_f32_16x16x32_bf16(Bt[n], At[m], acc[m][n], 0, 0, 0);
;   }
	v_add3_u32 v252, v205, v147, s8
	v_add3_u32 v215, v205, v151, s8
	s_nop 0
	ds_read_b128 v[216:219], v252 offset:16384
	ds_read_b128 v[220:223], v252 offset:17408
	ds_read_b128 v[232:235], v252 offset:18432
	ds_read_b128 v[236:239], v252 offset:19456
	ds_read_b128 v[224:227], v215
	ds_read_b128 v[228:231], v215 offset:1024
	v_mfma_f32_16x16x32_bf16 v[28:31], v[180:183], v[240:243], v[28:31]
	v_mfma_f32_16x16x32_bf16 v[24:27], v[180:183], v[244:247], v[24:27]
	v_mfma_f32_16x16x32_bf16 v[20:23], v[180:183], v[248:251], v[20:23]
	v_mfma_f32_16x16x32_bf16 v[16:19], v[180:183], v[176:179], v[16:19]
	v_mfma_f32_16x16x32_bf16 v[12:15], v[210:213], v[240:243], v[12:15]
	v_mfma_f32_16x16x32_bf16 v[8:11], v[210:213], v[244:247], v[8:11]
	s_add_i32 s6, s8, 0x18000
	v_mfma_f32_16x16x32_bf16 v[4:7], v[210:213], v[248:251], v[4:7]
	s_and_b32 s6, s6, 0x18000
	v_mfma_f32_16x16x32_bf16 v[0:3], v[210:213], v[176:179], v[0:3]
	s_add_i32 s9, s6, s7
	v_lshl_add_u64 v[206:207], v[184:185], 0, s[4:5]
	s_mov_b32 m0, s9
	s_add_i32 s9, s9, 0x2000
	ds_read_b128 v[180:183], v215 offset:2048
	ds_read_b128 v[210:213], v215 offset:3072
	s_waitcnt lgkmcnt(2)
	v_mfma_f32_16x16x32_bf16 v[124:127], v[224:227], v[216:219], v[124:127]
	v_mfma_f32_16x16x32_bf16 v[120:123], v[224:227], v[220:223], v[120:123]
	v_mfma_f32_16x16x32_bf16 v[116:119], v[224:227], v[232:235], v[116:119]
	v_mfma_f32_16x16x32_bf16 v[112:115], v[224:227], v[236:239], v[112:115]
	v_mfma_f32_16x16x32_bf16 v[108:111], v[228:231], v[216:219], v[108:111]
	v_mfma_f32_16x16x32_bf16 v[104:107], v[228:231], v[220:223], v[104:107]
	v_mfma_f32_16x16x32_bf16 v[100:103], v[228:231], v[232:235], v[100:103]
	v_mfma_f32_16x16x32_bf16 v[96:99], v[228:231], v[236:239], v[96:99]
	ds_read_b128 v[224:227], v215 offset:4096
	ds_read_b128 v[228:231], v215 offset:5120
	s_waitcnt lgkmcnt(2)
	v_mfma_f32_16x16x32_bf16 v[92:95], v[180:183], v[216:219], v[92:95]
	v_mfma_f32_16x16x32_bf16 v[88:91], v[180:183], v[220:223], v[88:91]
	v_mfma_f32_16x16x32_bf16 v[84:87], v[180:183], v[232:235], v[84:87]
	v_mfma_f32_16x16x32_bf16 v[80:83], v[180:183], v[236:239], v[80:83]
	v_mfma_f32_16x16x32_bf16 v[76:79], v[210:213], v[216:219], v[76:79]
	v_mfma_f32_16x16x32_bf16 v[72:75], v[210:213], v[220:223], v[72:75]
	v_mfma_f32_16x16x32_bf16 v[68:71], v[210:213], v[232:235], v[68:71]
	v_mfma_f32_16x16x32_bf16 v[64:67], v[210:213], v[236:239], v[64:67]
	ds_read_b128 v[180:183], v215 offset:6144
	ds_read_b128 v[210:213], v215 offset:7168
	s_waitcnt lgkmcnt(2)
	v_mfma_f32_16x16x32_bf16 v[60:63], v[224:227], v[216:219], v[60:63]
	v_mfma_f32_16x16x32_bf16 v[56:59], v[224:227], v[220:223], v[56:59]
	v_mfma_f32_16x16x32_bf16 v[52:55], v[224:227], v[232:235], v[52:55]
	v_mfma_f32_16x16x32_bf16 v[48:51], v[224:227], v[236:239], v[48:51]
	v_mfma_f32_16x16x32_bf16 v[44:47], v[228:231], v[216:219], v[44:47]
	v_mfma_f32_16x16x32_bf16 v[40:43], v[228:231], v[220:223], v[40:43]
	v_mfma_f32_16x16x32_bf16 v[36:39], v[228:231], v[232:235], v[36:39]
	v_mfma_f32_16x16x32_bf16 v[32:35], v[228:231], v[236:239], v[32:35]
	s_add_i32 s8, s8, 0x8000
	s_and_b32 s8, s8, 0x18000
	s_waitcnt vmcnt(0) lgkmcnt(0)
	s_barrier
	v_add3_u32 v252, v205, v147, s8
	v_add3_u32 v215, v205, v151, s8
	s_nop 0
	ds_read_b128 v[240:243], v252 offset:16384
	ds_read_b128 v[244:247], v252 offset:17408
	ds_read_b128 v[248:251], v252 offset:18432
	ds_read_b128 v[176:179], v252 offset:19456
	ds_read_b128 v[224:227], v215
	ds_read_b128 v[228:231], v215 offset:1024
	v_mfma_f32_16x16x32_bf16 v[28:31], v[180:183], v[216:219], v[28:31]
	v_mfma_f32_16x16x32_bf16 v[24:27], v[180:183], v[220:223], v[24:27]
	v_mfma_f32_16x16x32_bf16 v[20:23], v[180:183], v[232:235], v[20:23]
	v_mfma_f32_16x16x32_bf16 v[16:19], v[180:183], v[236:239], v[16:19]
	v_mfma_f32_16x16x32_bf16 v[12:15], v[210:213], v[216:219], v[12:15]
	v_mfma_f32_16x16x32_bf16 v[8:11], v[210:213], v[220:223], v[8:11]
	s_add_i32 s6, s8, 0x18000
	v_mfma_f32_16x16x32_bf16 v[4:7], v[210:213], v[232:235], v[4:7]
	s_and_b32 s6, s6, 0x18000
	v_mfma_f32_16x16x32_bf16 v[0:3], v[210:213], v[236:239], v[0:3]
	s_add_i32 s9, s6, s7
	v_lshl_add_u64 v[206:207], v[184:185], 0, s[4:5]
	s_mov_b32 m0, s9
	s_add_i32 s9, s9, 0x2000
	ds_read_b128 v[180:183], v215 offset:2048
	ds_read_b128 v[210:213], v215 offset:3072
	s_waitcnt lgkmcnt(2)
	v_mfma_f32_16x16x32_bf16 v[124:127], v[224:227], v[240:243], v[124:127]
	v_mfma_f32_16x16x32_bf16 v[120:123], v[224:227], v[244:247], v[120:123]
	v_mfma_f32_16x16x32_bf16 v[116:119], v[224:227], v[248:251], v[116:119]
	v_mfma_f32_16x16x32_bf16 v[112:115], v[224:227], v[176:179], v[112:115]
	v_mfma_f32_16x16x32_bf16 v[108:111], v[228:231], v[240:243], v[108:111]
	v_mfma_f32_16x16x32_bf16 v[104:107], v[228:231], v[244:247], v[104:107]
	v_mfma_f32_16x16x32_bf16 v[100:103], v[228:231], v[248:251], v[100:103]
	v_mfma_f32_16x16x32_bf16 v[96:99], v[228:231], v[176:179], v[96:99]
	ds_read_b128 v[224:227], v215 offset:4096
	ds_read_b128 v[228:231], v215 offset:5120
	s_waitcnt lgkmcnt(2)
	v_mfma_f32_16x16x32_bf16 v[92:95], v[180:183], v[240:243], v[92:95]
	v_mfma_f32_16x16x32_bf16 v[88:91], v[180:183], v[244:247], v[88:91]
	v_mfma_f32_16x16x32_bf16 v[84:87], v[180:183], v[248:251], v[84:87]
	v_mfma_f32_16x16x32_bf16 v[80:83], v[180:183], v[176:179], v[80:83]
	v_mfma_f32_16x16x32_bf16 v[76:79], v[210:213], v[240:243], v[76:79]
	v_mfma_f32_16x16x32_bf16 v[72:75], v[210:213], v[244:247], v[72:75]
	v_mfma_f32_16x16x32_bf16 v[68:71], v[210:213], v[248:251], v[68:71]
	v_mfma_f32_16x16x32_bf16 v[64:67], v[210:213], v[176:179], v[64:67]
	ds_read_b128 v[180:183], v215 offset:6144
	ds_read_b128 v[210:213], v215 offset:7168
	s_waitcnt lgkmcnt(2)
	v_mfma_f32_16x16x32_bf16 v[60:63], v[224:227], v[240:243], v[60:63]
	v_mfma_f32_16x16x32_bf16 v[56:59], v[224:227], v[244:247], v[56:59]
	v_mfma_f32_16x16x32_bf16 v[52:55], v[224:227], v[248:251], v[52:55]
	v_mfma_f32_16x16x32_bf16 v[48:51], v[224:227], v[176:179], v[48:51]
	v_mfma_f32_16x16x32_bf16 v[44:47], v[228:231], v[240:243], v[44:47]
	v_mfma_f32_16x16x32_bf16 v[40:43], v[228:231], v[244:247], v[40:43]
	v_mfma_f32_16x16x32_bf16 v[36:39], v[228:231], v[248:251], v[36:39]
	v_mfma_f32_16x16x32_bf16 v[32:35], v[228:231], v[176:179], v[32:35]
	s_waitcnt lgkmcnt(0)
	v_mfma_f32_16x16x32_bf16 v[28:31], v[180:183], v[240:243], v[28:31]
	v_mfma_f32_16x16x32_bf16 v[24:27], v[180:183], v[244:247], v[24:27]
	v_mfma_f32_16x16x32_bf16 v[20:23], v[180:183], v[248:251], v[20:23]
	v_mfma_f32_16x16x32_bf16 v[16:19], v[180:183], v[176:179], v[16:19]
	v_mfma_f32_16x16x32_bf16 v[12:15], v[210:213], v[240:243], v[12:15]
	v_mfma_f32_16x16x32_bf16 v[8:11], v[210:213], v[244:247], v[8:11]
	s_add_i32 s6, s8, 0x18000
	v_mfma_f32_16x16x32_bf16 v[4:7], v[210:213], v[248:251], v[4:7]
	s_and_b32 s6, s6, 0x18000
	v_mfma_f32_16x16x32_bf16 v[0:3], v[210:213], v[176:179], v[0:3]
	s_add_i32 s9, s6, s7
	v_lshl_add_u64 v[206:207], v[184:185], 0, s[4:5]
	s_mov_b32 m0, s9
	s_add_i32 s9, s9, 0x2000
	s_nop 7
	s_nop 3
	s_waitcnt vmcnt(0) lgkmcnt(0)
	s_barrier
; DI u16 f2bf(float x) { return (u16)(pack2bf(x, 0.f) & 0xffffu); }
; template <class Epi>
; DI void gemm_tile256(const u16* __restrict__ Ag, long lda, const u16* __restrict__ Bg, long ldb, int nk, char* shm, Epi&& epi) {
;     ...
;   for (int m = 0; m < 8; ++m)
; #pragma unroll
;     for (int n = 0; n < 4; ++n) epi(wr * 128 + m * 16 + fr, wc * 64 + n * 16 + fq * 4, acc[m][n]);
; DI void phase1(const Params& P, char* smem) {
;     ...
;         const int hd = c - 1536, b = r >> 13, l = r & 8191;
; #pragma unroll
;         for (int j = 0; j < 4; ++j) Vt[((long)(b * 512 + hd + j)) * 8192 + l] = f2bf(v[j]);
	v_and_b32_e32 v184, 15, v208
	v_lshrrev_b32_e32 v185, 4, v208
	v_lshrrev_b32_e32 v186, 6, v189
	v_lshlrev_b32_e32 v186, 14, v186
	v_lshrrev_b32_e32 v206, 1, v185
	v_and_b32_e32 v207, 1, v185
	v_lshl_add_u32 v215, v184, 8, v186
	v_lshl_add_u32 v215, v207, 3, v215
	v_or_b32_e32 v252, 0, v206
	v_xor_b32_e32 v252, v252, v184
	v_lshl_add_u32 v176, v252, 4, v215
	v_or_b32_e32 v252, 2, v206
	v_xor_b32_e32 v252, v252, v184
	v_lshl_add_u32 v177, v252, 4, v215
	v_or_b32_e32 v252, 4, v206
	v_xor_b32_e32 v252, v252, v184
	v_lshl_add_u32 v178, v252, 4, v215
	v_or_b32_e32 v252, 6, v206
	v_xor_b32_e32 v252, v252, v184
	v_lshl_add_u32 v179, v252, 4, v215
	v_or_b32_e32 v252, 8, v206
	v_xor_b32_e32 v252, v252, v184
	v_lshl_add_u32 v180, v252, 4, v215
	v_or_b32_e32 v252, 10, v206
	v_xor_b32_e32 v252, v252, v184
	v_lshl_add_u32 v181, v252, 4, v215
	v_or_b32_e32 v252, 12, v206
	v_xor_b32_e32 v252, v252, v184
	v_lshl_add_u32 v211, v252, 4, v215
	v_or_b32_e32 v252, 14, v206
	v_xor_b32_e32 v252, v252, v184
	v_lshl_add_u32 v242, v252, 4, v215
	v_add_u32_e32 v253, 0, v185
	v_xor_b32_e32 v252, v184, v253
	v_lshl_add_u32 v243, v253, 8, v186
	v_lshl_add_u32 v243, v252, 4, v243
	v_add_u32_e32 v253, 4, v185
	v_xor_b32_e32 v252, v184, v253
	v_lshl_add_u32 v212, v253, 8, v186
	v_lshl_add_u32 v212, v252, 4, v212
	v_add_u32_e32 v253, 8, v185
	v_xor_b32_e32 v252, v184, v253
	v_lshl_add_u32 v213, v253, 8, v186
	v_lshl_add_u32 v213, v252, 4, v213
	v_add_u32_e32 v253, 12, v185
	v_xor_b32_e32 v252, v184, v253
	v_lshl_add_u32 v187, v253, 8, v186
	v_lshl_add_u32 v187, v252, 4, v187
	v_bfe_u32 v252, v189, 6, 2
	v_lshl_add_u32 v252, v252, 6, v185
	s_lshr_b32 s36, s30, 13
	s_lshl_b32 s36, s36, 9
	s_and_b32 s37, s74, 1
	s_lshl_b32 s37, s37, 8
	s_add_i32 s36, s36, s37
	v_add_u32_e32 v252, s36, v252
	v_lshlrev_b32_e32 v182, 14, v252
	s_and_b32 s36, s30, 0x1fff
	v_lshl_add_u32 v252, v190, 7, s36
	v_lshl_add_u32 v182, v252, 1, v182
	v_lshl_add_u32 v182, v184, 4, v182
	v_mov_b32_e32 v183, 0
	v_lshl_add_u64 v[182:183], v[182:183], 0, s[62:63]
	s_mov_b32 s38, 0x10000
	s_mov_b32 s39, 0
	v_lshl_add_u64 v[240:241], v[182:183], 0, s[38:39]
	s_lshl_b32 s38, s38, 1
	v_cvt_pk_bf16_f32 v124, v124, v125
	v_cvt_pk_bf16_f32 v125, v126, v127
	ds_write_b64 v176, v[124:125] offset:0
	v_cvt_pk_bf16_f32 v120, v120, v121
	v_cvt_pk_bf16_f32 v121, v122, v123
	ds_write_b64 v176, v[120:121] offset:4096
	v_cvt_pk_bf16_f32 v116, v116, v117
	v_cvt_pk_bf16_f32 v117, v118, v119
	ds_write_b64 v176, v[116:117] offset:8192
	v_cvt_pk_bf16_f32 v112, v112, v113
	v_cvt_pk_bf16_f32 v113, v114, v115
	ds_write_b64 v176, v[112:113] offset:12288
	v_cvt_pk_bf16_f32 v108, v108, v109
	v_cvt_pk_bf16_f32 v109, v110, v111
	ds_write_b64 v177, v[108:109] offset:0
	v_cvt_pk_bf16_f32 v104, v104, v105
	v_cvt_pk_bf16_f32 v105, v106, v107
	ds_write_b64 v177, v[104:105] offset:4096
	v_cvt_pk_bf16_f32 v100, v100, v101
	v_cvt_pk_bf16_f32 v101, v102, v103
	ds_write_b64 v177, v[100:101] offset:8192
	v_cvt_pk_bf16_f32 v96, v96, v97
	v_cvt_pk_bf16_f32 v97, v98, v99
	ds_write_b64 v177, v[96:97] offset:12288
	v_cvt_pk_bf16_f32 v92, v92, v93
	v_cvt_pk_bf16_f32 v93, v94, v95
	ds_write_b64 v178, v[92:93] offset:0
	v_cvt_pk_bf16_f32 v88, v88, v89
	v_cvt_pk_bf16_f32 v89, v90, v91
	ds_write_b64 v178, v[88:89] offset:4096
	v_cvt_pk_bf16_f32 v84, v84, v85
	v_cvt_pk_bf16_f32 v85, v86, v87
	ds_write_b64 v178, v[84:85] offset:8192
	v_cvt_pk_bf16_f32 v80, v80, v81
	v_cvt_pk_bf16_f32 v81, v82, v83
	ds_write_b64 v178, v[80:81] offset:12288
	v_cvt_pk_bf16_f32 v76, v76, v77
	v_cvt_pk_bf16_f32 v77, v78, v79
	ds_write_b64 v179, v[76:77] offset:0
	v_cvt_pk_bf16_f32 v72, v72, v73
	v_cvt_pk_bf16_f32 v73, v74, v75
	ds_write_b64 v179, v[72:73] offset:4096
	v_cvt_pk_bf16_f32 v68, v68, v69
	v_cvt_pk_bf16_f32 v69, v70, v71
	ds_write_b64 v179, v[68:69] offset:8192
	v_cvt_pk_bf16_f32 v64, v64, v65
	v_cvt_pk_bf16_f32 v65, v66, v67
	ds_write_b64 v179, v[64:65] offset:12288
	v_cvt_pk_bf16_f32 v60, v60, v61
	v_cvt_pk_bf16_f32 v61, v62, v63
	ds_write_b64 v180, v[60:61] offset:0
	v_cvt_pk_bf16_f32 v56, v56, v57
	v_cvt_pk_bf16_f32 v57, v58, v59
	ds_write_b64 v180, v[56:57] offset:4096
	v_cvt_pk_bf16_f32 v52, v52, v53
	v_cvt_pk_bf16_f32 v53, v54, v55
	ds_write_b64 v180, v[52:53] offset:8192
	v_cvt_pk_bf16_f32 v48, v48, v49
	v_cvt_pk_bf16_f32 v49, v50, v51
	ds_write_b64 v180, v[48:49] offset:12288
	v_cvt_pk_bf16_f32 v44, v44, v45
	v_cvt_pk_bf16_f32 v45, v46, v47
	ds_write_b64 v181, v[44:45] offset:0
	v_cvt_pk_bf16_f32 v40, v40, v41
	v_cvt_pk_bf16_f32 v41, v42, v43
	ds_write_b64 v181, v[40:41] offset:4096
	v_cvt_pk_bf16_f32 v36, v36, v37
	v_cvt_pk_bf16_f32 v37, v38, v39
	ds_write_b64 v181, v[36:37] offset:8192
	v_cvt_pk_bf16_f32 v32, v32, v33
	v_cvt_pk_bf16_f32 v33, v34, v35
	ds_write_b64 v181, v[32:33] offset:12288
	v_cvt_pk_bf16_f32 v28, v28, v29
	v_cvt_pk_bf16_f32 v29, v30, v31
	ds_write_b64 v211, v[28:29] offset:0
	v_cvt_pk_bf16_f32 v24, v24, v25
	v_cvt_pk_bf16_f32 v25, v26, v27
	ds_write_b64 v211, v[24:25] offset:4096
	v_cvt_pk_bf16_f32 v20, v20, v21
	v_cvt_pk_bf16_f32 v21, v22, v23
	ds_write_b64 v211, v[20:21] offset:8192
	v_cvt_pk_bf16_f32 v16, v16, v17
	v_cvt_pk_bf16_f32 v17, v18, v19
	ds_write_b64 v211, v[16:17] offset:12288
	v_cvt_pk_bf16_f32 v12, v12, v13
	v_cvt_pk_bf16_f32 v13, v14, v15
	ds_write_b64 v242, v[12:13] offset:0
	v_cvt_pk_bf16_f32 v8, v8, v9
	v_cvt_pk_bf16_f32 v9, v10, v11
	ds_write_b64 v242, v[8:9] offset:4096
	v_cvt_pk_bf16_f32 v4, v4, v5
	v_cvt_pk_bf16_f32 v5, v6, v7
	ds_write_b64 v242, v[4:5] offset:8192
	v_cvt_pk_bf16_f32 v0, v0, v1
	v_cvt_pk_bf16_f32 v1, v2, v3
	ds_write_b64 v242, v[0:1] offset:12288
	s_waitcnt lgkmcnt(0)
; DI u16 f2bf(float x) { return (u16)(pack2bf(x, 0.f) & 0xffffu); }
; template <class Epi>
; DI void gemm_tile256(const u16* __restrict__ Ag, long lda, const u16* __restrict__ Bg, long ldb, int nk, char* shm, Epi&& epi) {
;     ...
;   for (int i = 0; i < nk; ++i) {
;     if (i + 2 < nk) asm volatile("s_waitcnt vmcnt(8)" ::: "memory");
;     else if (i + 1 < nk) asm volatile("s_waitcnt vmcnt(4)" ::: "memory");
;     else asm volatile("s_waitcnt vmcnt(0)" ::: "memory");
;     __builtin_amdgcn_s_barrier();
;     const char* SA = shm + (i & 3) * 32768; const char* SB = SA + 16384;
;     bf16x8 At[8], Bt[4];
; #pragma unroll
;     for (int n = 0; n < 4; ++n) { const int rb = wc * 64 + n * 16 + fr; Bt[n] = *reinterpret_cast<const bf16x8*>(SB + rb * 64 + ((fq ^ ((rb >> 2) & 3)) * 16)); }
; #pragma unroll
;     for (int m = 0; m < 8; ++m) { const int ra = wr * 128 + m * 16 + fr; At[m] = *reinterpret_cast<const bf16x8*>(SA + ra * 64 + ((fq ^ ((ra >> 2) & 3)) * 16)); }
;     if (i + 3 < nk) stage(i + 3);
; #pragma unroll
;     for (int m = 0; m < 8; ++m)
; #pragma unroll
;       for (int n = 0; n < 4; ++n) acc[m][n] = __builtin_amdgcn_mfma_f32_16x16x32_bf16(Bt[n], At[m], acc[m][n], 0, 0, 0);
;   }
; DI void phase1(const Params& P, char* smem) {
;     ...
;         const int hd = c - 1536, b = r >> 13, l = r & 8191;
; #pragma unroll
;         for (int j = 0; j < 4; ++j) Vt[((long)(b * 512 + hd + j)) * 8192 + l] = f2bf(v[j]);
	ds_read_b128 v[216:219], v243 offset:0
	ds_read_b128 v[220:223], v212 offset:0
	ds_read_b128 v[224:227], v213 offset:0
	ds_read_b128 v[228:231], v187 offset:0
	s_waitcnt lgkmcnt(3)
	global_store_dwordx4 v[182:183], v[216:219], off
	s_nop 0
	v_lshl_add_u64 v[182:183], v[182:183], 0, s[38:39]
	s_waitcnt lgkmcnt(2)
	global_store_dwordx4 v[240:241], v[220:223], off
	s_nop 0
	v_lshl_add_u64 v[240:241], v[240:241], 0, s[38:39]
	s_waitcnt lgkmcnt(1)
	global_store_dwordx4 v[182:183], v[224:227], off
	s_nop 0
	v_lshl_add_u64 v[182:183], v[182:183], 0, s[38:39]
	s_waitcnt lgkmcnt(0)
	global_store_dwordx4 v[240:241], v[228:231], off
	s_nop 0
	v_lshl_add_u64 v[240:241], v[240:241], 0, s[38:39]
	ds_read_b128 v[232:235], v243 offset:4096
	ds_read_b128 v[236:239], v212 offset:4096
	ds_read_b128 v[244:247], v213 offset:4096
	ds_read_b128 v[248:251], v187 offset:4096
	s_waitcnt lgkmcnt(3)
	global_store_dwordx4 v[182:183], v[232:235], off
	s_nop 0
	v_lshl_add_u64 v[182:183], v[182:183], 0, s[38:39]
	s_waitcnt lgkmcnt(2)
	global_store_dwordx4 v[240:241], v[236:239], off
	s_nop 0
	v_lshl_add_u64 v[240:241], v[240:241], 0, s[38:39]
	s_waitcnt lgkmcnt(1)
	global_store_dwordx4 v[182:183], v[244:247], off
	s_nop 0
	v_lshl_add_u64 v[182:183], v[182:183], 0, s[38:39]
	s_waitcnt lgkmcnt(0)
	global_store_dwordx4 v[240:241], v[248:251], off
	s_nop 0
	v_lshl_add_u64 v[240:241], v[240:241], 0, s[38:39]
	ds_read_b128 v[216:219], v243 offset:8192
	ds_read_b128 v[220:223], v212 offset:8192
	ds_read_b128 v[224:227], v213 offset:8192
	ds_read_b128 v[228:231], v187 offset:8192
	s_waitcnt lgkmcnt(3)
	global_store_dwordx4 v[182:183], v[216:219], off
	s_nop 0
	v_lshl_add_u64 v[182:183], v[182:183], 0, s[38:39]
	s_waitcnt lgkmcnt(2)
	global_store_dwordx4 v[240:241], v[220:223], off
	s_nop 0
	v_lshl_add_u64 v[240:241], v[240:241], 0, s[38:39]
	s_waitcnt lgkmcnt(1)
	global_store_dwordx4 v[182:183], v[224:227], off
	s_nop 0
	v_lshl_add_u64 v[182:183], v[182:183], 0, s[38:39]
	s_waitcnt lgkmcnt(0)
	global_store_dwordx4 v[240:241], v[228:231], off
	s_nop 0
	v_lshl_add_u64 v[240:241], v[240:241], 0, s[38:39]
	ds_read_b128 v[232:235], v243 offset:12288
	ds_read_b128 v[236:239], v212 offset:12288
	ds_read_b128 v[244:247], v213 offset:12288
	ds_read_b128 v[248:251], v187 offset:12288
	s_waitcnt lgkmcnt(3)
	global_store_dwordx4 v[182:183], v[232:235], off
	s_nop 0
	v_lshl_add_u64 v[182:183], v[182:183], 0, s[38:39]
	s_waitcnt lgkmcnt(2)
	global_store_dwordx4 v[240:241], v[236:239], off
	s_nop 0
	v_lshl_add_u64 v[240:241], v[240:241], 0, s[38:39]
	s_waitcnt lgkmcnt(1)
	global_store_dwordx4 v[182:183], v[244:247], off
	s_nop 0
	v_lshl_add_u64 v[182:183], v[182:183], 0, s[38:39]
	s_waitcnt lgkmcnt(0)
	global_store_dwordx4 v[240:241], v[248:251], off
	s_nop 0
	v_lshl_add_u64 v[240:241], v[240:241], 0, s[38:39]
	v_or_b32_e32 v212, 0x50, v153
	v_or_b32_e32 v213, 0x60, v153
	s_branch .LBB0_106
.Lgemm_p1_n:
	s_waitcnt vmcnt(8)
	s_barrier
	v_add3_u32 v252, v205, v147, s8
	v_add3_u32 v215, v205, v151, s8
	s_nop 0
	ds_read_b128 v[216:219], v252 offset:16384
	ds_read_b128 v[220:223], v252 offset:17408
	ds_read_b128 v[232:235], v252 offset:18432
	ds_read_b128 v[236:239], v252 offset:19456
	ds_read_b128 v[224:227], v215
	ds_read_b128 v[228:231], v215 offset:1024
	s_add_i32 s9, s7, 0x18000
	v_lshl_add_u64 v[206:207], v[184:185], 0, s[4:5]
	s_mov_b32 m0, s9
	s_add_i32 s9, s9, 0x2000
.Lgemm_p1_kloopn:
	ds_read_b128 v[180:183], v215 offset:2048
	ds_read_b128 v[210:213], v215 offset:3072
	s_waitcnt lgkmcnt(2)
	v_mfma_f32_16x16x32_bf16 v[124:127], v[216:219], v[224:227], v[124:127]
	global_load_lds_dwordx4 v[206:207], off
	v_mfma_f32_16x16x32_bf16 v[120:123], v[220:223], v[224:227], v[120:123]
	v_mfma_f32_16x16x32_bf16 v[116:119], v[232:235], v[224:227], v[116:119]
	v_mfma_f32_16x16x32_bf16 v[112:115], v[236:239], v[224:227], v[112:115]
	v_mfma_f32_16x16x32_bf16 v[108:111], v[216:219], v[228:231], v[108:111]
	v_mfma_f32_16x16x32_bf16 v[104:107], v[220:223], v[228:231], v[104:107]
	v_lshl_add_u64 v[206:207], v[186:187], 0, s[4:5]
	v_mfma_f32_16x16x32_bf16 v[100:103], v[232:235], v[228:231], v[100:103]
	s_mov_b32 m0, s9
	v_mfma_f32_16x16x32_bf16 v[96:99], v[236:239], v[228:231], v[96:99]
	s_add_i32 s9, s9, 0x2000
	ds_read_b128 v[224:227], v215 offset:4096
	ds_read_b128 v[228:231], v215 offset:5120
	s_waitcnt lgkmcnt(2)
	v_mfma_f32_16x16x32_bf16 v[92:95], v[216:219], v[180:183], v[92:95]
	global_load_lds_dwordx4 v[206:207], off
	v_mfma_f32_16x16x32_bf16 v[88:91], v[220:223], v[180:183], v[88:91]
	v_mfma_f32_16x16x32_bf16 v[84:87], v[232:235], v[180:183], v[84:87]
	v_mfma_f32_16x16x32_bf16 v[80:83], v[236:239], v[180:183], v[80:83]
	v_mfma_f32_16x16x32_bf16 v[76:79], v[216:219], v[210:213], v[76:79]
	v_mfma_f32_16x16x32_bf16 v[72:75], v[220:223], v[210:213], v[72:75]
	v_lshl_add_u64 v[206:207], v[172:173], 0, s[4:5]
	v_mfma_f32_16x16x32_bf16 v[68:71], v[232:235], v[210:213], v[68:71]
	s_mov_b32 m0, s9
	v_mfma_f32_16x16x32_bf16 v[64:67], v[236:239], v[210:213], v[64:67]
	s_add_i32 s9, s9, 0x2000
	ds_read_b128 v[180:183], v215 offset:6144
	ds_read_b128 v[210:213], v215 offset:7168
	s_waitcnt lgkmcnt(2)
	v_mfma_f32_16x16x32_bf16 v[60:63], v[216:219], v[224:227], v[60:63]
	global_load_lds_dwordx4 v[206:207], off
	v_mfma_f32_16x16x32_bf16 v[56:59], v[220:223], v[224:227], v[56:59]
	v_mfma_f32_16x16x32_bf16 v[52:55], v[232:235], v[224:227], v[52:55]
	v_mfma_f32_16x16x32_bf16 v[48:51], v[236:239], v[224:227], v[48:51]
	v_mfma_f32_16x16x32_bf16 v[44:47], v[216:219], v[228:231], v[44:47]
	v_mfma_f32_16x16x32_bf16 v[40:43], v[220:223], v[228:231], v[40:43]
	v_lshl_add_u64 v[206:207], v[174:175], 0, s[4:5]
	v_mfma_f32_16x16x32_bf16 v[36:39], v[232:235], v[228:231], v[36:39]
	s_mov_b32 m0, s9
	v_mfma_f32_16x16x32_bf16 v[32:35], v[236:239], v[228:231], v[32:35]
	s_add_i32 s9, s9, 0x2000
	s_add_u32 s4, s4, 64
	s_addc_u32 s5, s5, 0
	s_add_i32 s8, s8, 0x8000
	s_and_b32 s8, s8, 0x18000
	s_waitcnt vmcnt(7) lgkmcnt(0)
	s_barrier
; template <class Epi>
; DI void gemm_tile256(const u16* __restrict__ Ag, long lda, const u16* __restrict__ Bg, long ldb, int nk, char* shm, Epi&& epi) {
;     ...
;   for (int i = 0; i < nk; ++i) {
;     if (i + 2 < nk) asm volatile("s_waitcnt vmcnt(8)" ::: "memory");
;     else if (i + 1 < nk) asm volatile("s_waitcnt vmcnt(4)" ::: "memory");
;     else asm volatile("s_waitcnt vmcnt(0)" ::: "memory");
;     __builtin_amdgcn_s_barrier();
;     const char* SA = shm + (i & 3) * 32768; const char* SB = SA + 16384;
;     bf16x8 At[8], Bt[4];
; #pragma unroll
;     for (int n = 0; n < 4; ++n) { const int rb = wc * 64 + n * 16 + fr; Bt[n] = *reinterpret_cast<const bf16x8*>(SB + rb * 64 + ((fq ^ ((rb >> 2) & 3)) * 16)); }
; #pragma unroll
;     for (int m = 0; m < 8; ++m) { const int ra = wr * 128 + m * 16 + fr; At[m] = *reinterpret_cast<const bf16x8*>(SA + ra * 64 + ((fq ^ ((ra >> 2) & 3)) * 16)); }
;     if (i + 3 < nk) stage(i + 3);
; #pragma unroll
;     for (int m = 0; m < 8; ++m)
; #pragma unroll
;       for (int n = 0; n < 4; ++n) acc[m][n] = __builtin_amdgcn_mfma_f32_16x16x32_bf16(Bt[n], At[m], acc[m][n], 0, 0, 0);
;   }
	v_add3_u32 v252, v205, v147, s8
	v_add3_u32 v215, v205, v151, s8
	s_nop 0
	ds_read_b128 v[240:243], v252 offset:16384
	ds_read_b128 v[244:247], v252 offset:17408
	ds_read_b128 v[248:251], v252 offset:18432
	ds_read_b128 v[176:179], v252 offset:19456
	ds_read_b128 v[224:227], v215
	ds_read_b128 v[228:231], v215 offset:1024
	v_mfma_f32_16x16x32_bf16 v[28:31], v[216:219], v[180:183], v[28:31]
	global_load_lds_dwordx4 v[206:207], off
	v_mfma_f32_16x16x32_bf16 v[24:27], v[220:223], v[180:183], v[24:27]
	v_mfma_f32_16x16x32_bf16 v[20:23], v[232:235], v[180:183], v[20:23]
	v_mfma_f32_16x16x32_bf16 v[16:19], v[236:239], v[180:183], v[16:19]
	v_mfma_f32_16x16x32_bf16 v[12:15], v[216:219], v[210:213], v[12:15]
	v_mfma_f32_16x16x32_bf16 v[8:11], v[220:223], v[210:213], v[8:11]
	s_add_i32 s6, s8, 0x18000
	v_mfma_f32_16x16x32_bf16 v[4:7], v[232:235], v[210:213], v[4:7]
	s_and_b32 s6, s6, 0x18000
	v_mfma_f32_16x16x32_bf16 v[0:3], v[236:239], v[210:213], v[0:3]
	s_add_i32 s9, s6, s7
	v_lshl_add_u64 v[206:207], v[184:185], 0, s[4:5]
	s_mov_b32 m0, s9
	s_add_i32 s9, s9, 0x2000
	ds_read_b128 v[180:183], v215 offset:2048
	ds_read_b128 v[210:213], v215 offset:3072
	s_waitcnt lgkmcnt(2)
	v_mfma_f32_16x16x32_bf16 v[124:127], v[240:243], v[224:227], v[124:127]
	global_load_lds_dwordx4 v[206:207], off
	v_mfma_f32_16x16x32_bf16 v[120:123], v[244:247], v[224:227], v[120:123]
	v_mfma_f32_16x16x32_bf16 v[116:119], v[248:251], v[224:227], v[116:119]
	v_mfma_f32_16x16x32_bf16 v[112:115], v[176:179], v[224:227], v[112:115]
	v_mfma_f32_16x16x32_bf16 v[108:111], v[240:243], v[228:231], v[108:111]
	v_mfma_f32_16x16x32_bf16 v[104:107], v[244:247], v[228:231], v[104:107]
	v_lshl_add_u64 v[206:207], v[186:187], 0, s[4:5]
	v_mfma_f32_16x16x32_bf16 v[100:103], v[248:251], v[228:231], v[100:103]
	s_mov_b32 m0, s9
	v_mfma_f32_16x16x32_bf16 v[96:99], v[176:179], v[228:231], v[96:99]
	s_add_i32 s9, s9, 0x2000
	ds_read_b128 v[224:227], v215 offset:4096
	ds_read_b128 v[228:231], v215 offset:5120
	s_waitcnt lgkmcnt(2)
	v_mfma_f32_16x16x32_bf16 v[92:95], v[240:243], v[180:183], v[92:95]
	global_load_lds_dwordx4 v[206:207], off
	v_mfma_f32_16x16x32_bf16 v[88:91], v[244:247], v[180:183], v[88:91]
	v_mfma_f32_16x16x32_bf16 v[84:87], v[248:251], v[180:183], v[84:87]
	v_mfma_f32_16x16x32_bf16 v[80:83], v[176:179], v[180:183], v[80:83]
	v_mfma_f32_16x16x32_bf16 v[76:79], v[240:243], v[210:213], v[76:79]
	v_mfma_f32_16x16x32_bf16 v[72:75], v[244:247], v[210:213], v[72:75]
	v_lshl_add_u64 v[206:207], v[172:173], 0, s[4:5]
	v_mfma_f32_16x16x32_bf16 v[68:71], v[248:251], v[210:213], v[68:71]
	s_mov_b32 m0, s9
	v_mfma_f32_16x16x32_bf16 v[64:67], v[176:179], v[210:213], v[64:67]
	s_add_i32 s9, s9, 0x2000
	ds_read_b128 v[180:183], v215 offset:6144
	ds_read_b128 v[210:213], v215 offset:7168
	s_waitcnt lgkmcnt(2)
	v_mfma_f32_16x16x32_bf16 v[60:63], v[240:243], v[224:227], v[60:63]
	global_load_lds_dwordx4 v[206:207], off
	v_mfma_f32_16x16x32_bf16 v[56:59], v[244:247], v[224:227], v[56:59]
	v_mfma_f32_16x16x32_bf16 v[52:55], v[248:251], v[224:227], v[52:55]
	v_mfma_f32_16x16x32_bf16 v[48:51], v[176:179], v[224:227], v[48:51]
	v_mfma_f32_16x16x32_bf16 v[44:47], v[240:243], v[228:231], v[44:47]
	v_mfma_f32_16x16x32_bf16 v[40:43], v[244:247], v[228:231], v[40:43]
	v_lshl_add_u64 v[206:207], v[174:175], 0, s[4:5]
	v_mfma_f32_16x16x32_bf16 v[36:39], v[248:251], v[228:231], v[36:39]
	s_mov_b32 m0, s9
	v_mfma_f32_16x16x32_bf16 v[32:35], v[176:179], v[228:231], v[32:35]
	s_add_i32 s9, s9, 0x2000
	s_add_u32 s4, s4, 64
	s_addc_u32 s5, s5, 0
	s_add_i32 s8, s8, 0x8000
	s_and_b32 s8, s8, 0x18000
	s_waitcnt vmcnt(7) lgkmcnt(0)
	s_barrier
	v_add3_u32 v252, v205, v147, s8
	v_add3_u32 v215, v205, v151, s8
	s_nop 0
	ds_read_b128 v[216:219], v252 offset:16384
	ds_read_b128 v[220:223], v252 offset:17408
	ds_read_b128 v[232:235], v252 offset:18432
	ds_read_b128 v[236:239], v252 offset:19456
	ds_read_b128 v[224:227], v215
	ds_read_b128 v[228:231], v215 offset:1024
	v_mfma_f32_16x16x32_bf16 v[28:31], v[240:243], v[180:183], v[28:31]
	global_load_lds_dwordx4 v[206:207], off
	v_mfma_f32_16x16x32_bf16 v[24:27], v[244:247], v[180:183], v[24:27]
	v_mfma_f32_16x16x32_bf16 v[20:23], v[248:251], v[180:183], v[20:23]
	v_mfma_f32_16x16x32_bf16 v[16:19], v[176:179], v[180:183], v[16:19]
	v_mfma_f32_16x16x32_bf16 v[12:15], v[240:243], v[210:213], v[12:15]
	v_mfma_f32_16x16x32_bf16 v[8:11], v[244:247], v[210:213], v[8:11]
	s_add_i32 s6, s8, 0x18000
	v_mfma_f32_16x16x32_bf16 v[4:7], v[248:251], v[210:213], v[4:7]
	s_and_b32 s6, s6, 0x18000
	v_mfma_f32_16x16x32_bf16 v[0:3], v[176:179], v[210:213], v[0:3]
	s_add_i32 s9, s6, s7
	v_lshl_add_u64 v[206:207], v[184:185], 0, s[4:5]
	s_mov_b32 m0, s9
	s_add_i32 s9, s9, 0x2000
	s_cmpk_lg_i32 s4, 0x700
	s_cbranch_scc1 .Lgemm_p1_kloopn
; template <class Epi>
; DI void gemm_tile256(const u16* __restrict__ Ag, long lda, const u16* __restrict__ Bg, long ldb, int nk, char* shm, Epi&& epi) {
;     ...
;   for (int i = 0; i < nk; ++i) {
;     if (i + 2 < nk) asm volatile("s_waitcnt vmcnt(8)" ::: "memory");
;     else if (i + 1 < nk) asm volatile("s_waitcnt vmcnt(4)" ::: "memory");
;     else asm volatile("s_waitcnt vmcnt(0)" ::: "memory");
;     __builtin_amdgcn_s_barrier();
;     const char* SA = shm + (i & 3) * 32768; const char* SB = SA + 16384;
;     bf16x8 At[8], Bt[4];
; #pragma unroll
;     for (int n = 0; n < 4; ++n) { const int rb = wc * 64 + n * 16 + fr; Bt[n] = *reinterpret_cast<const bf16x8*>(SB + rb * 64 + ((fq ^ ((rb >> 2) & 3)) * 16)); }
; #pragma unroll
;     for (int m = 0; m < 8; ++m) { const int ra = wr * 128 + m * 16 + fr; At[m] = *reinterpret_cast<const bf16x8*>(SA + ra * 64 + ((fq ^ ((ra >> 2) & 3)) * 16)); }
;     if (i + 3 < nk) stage(i + 3);
; #pragma unroll
;     for (int m = 0; m < 8; ++m)
; #pragma unroll
;       for (int n = 0; n < 4; ++n) acc[m][n] = __builtin_amdgcn_mfma_f32_16x16x32_bf16(Bt[n], At[m], acc[m][n], 0, 0, 0);
;   }
	ds_read_b128 v[180:183], v215 offset:2048
	ds_read_b128 v[210:213], v215 offset:3072
	s_waitcnt lgkmcnt(2)
	v_mfma_f32_16x16x32_bf16 v[124:127], v[216:219], v[224:227], v[124:127]
	global_load_lds_dwordx4 v[206:207], off
	v_mfma_f32_16x16x32_bf16 v[120:123], v[220:223], v[224:227], v[120:123]
	v_mfma_f32_16x16x32_bf16 v[116:119], v[232:235], v[224:227], v[116:119]
	v_mfma_f32_16x16x32_bf16 v[112:115], v[236:239], v[224:227], v[112:115]
	v_mfma_f32_16x16x32_bf16 v[108:111], v[216:219], v[228:231], v[108:111]
	v_mfma_f32_16x16x32_bf16 v[104:107], v[220:223], v[228:231], v[104:107]
	v_lshl_add_u64 v[206:207], v[186:187], 0, s[4:5]
	v_mfma_f32_16x16x32_bf16 v[100:103], v[232:235], v[228:231], v[100:103]
	s_mov_b32 m0, s9
	v_mfma_f32_16x16x32_bf16 v[96:99], v[236:239], v[228:231], v[96:99]
	s_add_i32 s9, s9, 0x2000
	ds_read_b128 v[224:227], v215 offset:4096
	ds_read_b128 v[228:231], v215 offset:5120
	s_waitcnt lgkmcnt(2)
	v_mfma_f32_16x16x32_bf16 v[92:95], v[216:219], v[180:183], v[92:95]
	global_load_lds_dwordx4 v[206:207], off
	v_mfma_f32_16x16x32_bf16 v[88:91], v[220:223], v[180:183], v[88:91]
	v_mfma_f32_16x16x32_bf16 v[84:87], v[232:235], v[180:183], v[84:87]
	v_mfma_f32_16x16x32_bf16 v[80:83], v[236:239], v[180:183], v[80:83]
	v_mfma_f32_16x16x32_bf16 v[76:79], v[216:219], v[210:213], v[76:79]
	v_mfma_f32_16x16x32_bf16 v[72:75], v[220:223], v[210:213], v[72:75]
	v_lshl_add_u64 v[206:207], v[172:173], 0, s[4:5]
	v_mfma_f32_16x16x32_bf16 v[68:71], v[232:235], v[210:213], v[68:71]
	s_mov_b32 m0, s9
	v_mfma_f32_16x16x32_bf16 v[64:67], v[236:239], v[210:213], v[64:67]
	s_add_i32 s9, s9, 0x2000
	ds_read_b128 v[180:183], v215 offset:6144
	ds_read_b128 v[210:213], v215 offset:7168
	s_waitcnt lgkmcnt(2)
	v_mfma_f32_16x16x32_bf16 v[60:63], v[216:219], v[224:227], v[60:63]
	global_load_lds_dwordx4 v[206:207], off
	v_mfma_f32_16x16x32_bf16 v[56:59], v[220:223], v[224:227], v[56:59]
	v_mfma_f32_16x16x32_bf16 v[52:55], v[232:235], v[224:227], v[52:55]
	v_mfma_f32_16x16x32_bf16 v[48:51], v[236:239], v[224:227], v[48:51]
	v_mfma_f32_16x16x32_bf16 v[44:47], v[216:219], v[228:231], v[44:47]
	v_mfma_f32_16x16x32_bf16 v[40:43], v[220:223], v[228:231], v[40:43]
	v_lshl_add_u64 v[206:207], v[174:175], 0, s[4:5]
	v_mfma_f32_16x16x32_bf16 v[36:39], v[232:235], v[228:231], v[36:39]
	s_mov_b32 m0, s9
	v_mfma_f32_16x16x32_bf16 v[32:35], v[236:239], v[228:231], v[32:35]
	s_add_i32 s9, s9, 0x2000
	s_add_u32 s4, s4, 64
	s_addc_u32 s5, s5, 0
	s_add_i32 s8, s8, 0x8000
	s_and_b32 s8, s8, 0x18000
	s_waitcnt vmcnt(7) lgkmcnt(0)
	s_barrier
	v_add3_u32 v252, v205, v147, s8
	v_add3_u32 v215, v205, v151, s8
	s_nop 0
	ds_read_b128 v[240:243], v252 offset:16384
	ds_read_b128 v[244:247], v252 offset:17408
	ds_read_b128 v[248:251], v252 offset:18432
	ds_read_b128 v[176:179], v252 offset:19456
	ds_read_b128 v[224:227], v215
	ds_read_b128 v[228:231], v215 offset:1024
	v_mfma_f32_16x16x32_bf16 v[28:31], v[216:219], v[180:183], v[28:31]
	global_load_lds_dwordx4 v[206:207], off
	v_mfma_f32_16x16x32_bf16 v[24:27], v[220:223], v[180:183], v[24:27]
	v_mfma_f32_16x16x32_bf16 v[20:23], v[232:235], v[180:183], v[20:23]
	v_mfma_f32_16x16x32_bf16 v[16:19], v[236:239], v[180:183], v[16:19]
	v_mfma_f32_16x16x32_bf16 v[12:15], v[216:219], v[210:213], v[12:15]
	v_mfma_f32_16x16x32_bf16 v[8:11], v[220:223], v[210:213], v[8:11]
	v_mfma_f32_16x16x32_bf16 v[4:7], v[232:235], v[210:213], v[4:7]
	v_mfma_f32_16x16x32_bf16 v[0:3], v[236:239], v[210:213], v[0:3]
	ds_read_b128 v[180:183], v215 offset:2048
	ds_read_b128 v[210:213], v215 offset:3072
	s_waitcnt lgkmcnt(2)
	v_mfma_f32_16x16x32_bf16 v[124:127], v[240:243], v[224:227], v[124:127]
	v_mfma_f32_16x16x32_bf16 v[120:123], v[244:247], v[224:227], v[120:123]
	v_mfma_f32_16x16x32_bf16 v[116:119], v[248:251], v[224:227], v[116:119]
	v_mfma_f32_16x16x32_bf16 v[112:115], v[176:179], v[224:227], v[112:115]
	v_mfma_f32_16x16x32_bf16 v[108:111], v[240:243], v[228:231], v[108:111]
	v_mfma_f32_16x16x32_bf16 v[104:107], v[244:247], v[228:231], v[104:107]
	v_mfma_f32_16x16x32_bf16 v[100:103], v[248:251], v[228:231], v[100:103]
	v_mfma_f32_16x16x32_bf16 v[96:99], v[176:179], v[228:231], v[96:99]
	ds_read_b128 v[224:227], v215 offset:4096
	ds_read_b128 v[228:231], v215 offset:5120
	s_waitcnt lgkmcnt(2)
	v_mfma_f32_16x16x32_bf16 v[92:95], v[240:243], v[180:183], v[92:95]
	v_mfma_f32_16x16x32_bf16 v[88:91], v[244:247], v[180:183], v[88:91]
	v_mfma_f32_16x16x32_bf16 v[84:87], v[248:251], v[180:183], v[84:87]
	v_mfma_f32_16x16x32_bf16 v[80:83], v[176:179], v[180:183], v[80:83]
	v_mfma_f32_16x16x32_bf16 v[76:79], v[240:243], v[210:213], v[76:79]
	v_mfma_f32_16x16x32_bf16 v[72:75], v[244:247], v[210:213], v[72:75]
	v_mfma_f32_16x16x32_bf16 v[68:71], v[248:251], v[210:213], v[68:71]
	v_mfma_f32_16x16x32_bf16 v[64:67], v[176:179], v[210:213], v[64:67]
	ds_read_b128 v[180:183], v215 offset:6144
	ds_read_b128 v[210:213], v215 offset:7168
	s_waitcnt lgkmcnt(2)
	v_mfma_f32_16x16x32_bf16 v[60:63], v[240:243], v[224:227], v[60:63]
	v_mfma_f32_16x16x32_bf16 v[56:59], v[244:247], v[224:227], v[56:59]
	v_mfma_f32_16x16x32_bf16 v[52:55], v[248:251], v[224:227], v[52:55]
	v_mfma_f32_16x16x32_bf16 v[48:51], v[176:179], v[224:227], v[48:51]
	v_mfma_f32_16x16x32_bf16 v[44:47], v[240:243], v[228:231], v[44:47]
	v_mfma_f32_16x16x32_bf16 v[40:43], v[244:247], v[228:231], v[40:43]
	v_mfma_f32_16x16x32_bf16 v[36:39], v[248:251], v[228:231], v[36:39]
	v_mfma_f32_16x16x32_bf16 v[32:35], v[176:179], v[228:231], v[32:35]
	s_add_i32 s8, s8, 0x8000
	s_and_b32 s8, s8, 0x18000
	s_waitcnt vmcnt(4) lgkmcnt(0)
	s_barrier
; template <class Epi>
; DI void gemm_tile256(const u16* __restrict__ Ag, long lda, const u16* __restrict__ Bg, long ldb, int nk, char* shm, Epi&& epi) {
;     ...
;   for (int i = 0; i < nk; ++i) {
;     if (i + 2 < nk) asm volatile("s_waitcnt vmcnt(8)" ::: "memory");
;     else if (i + 1 < nk) asm volatile("s_waitcnt vmcnt(4)" ::: "memory");
;     else asm volatile("s_waitcnt vmcnt(0)" ::: "memory");
;     __builtin_amdgcn_s_barrier();
;     const char* SA = shm + (i & 3) * 32768; const char* SB = SA + 16384;
;     bf16x8 At[8], Bt[4];
; #pragma unroll
;     for (int n = 0; n < 4; ++n) { const int rb = wc * 64 + n * 16 + fr; Bt[n] = *reinterpret_cast<const bf16x8*>(SB + rb * 64 + ((fq ^ ((rb >> 2) & 3)) * 16)); }
; #pragma unroll
;     for (int m = 0; m < 8; ++m) { const int ra = wr * 128 + m * 16 + fr; At[m] = *reinterpret_cast<const bf16x8*>(SA + ra * 64 + ((fq ^ ((ra >> 2) & 3)) * 16)); }
;     if (i + 3 < nk) stage(i + 3);
; #pragma unroll
;     for (int m = 0; m < 8; ++m)
; #pragma unroll
;       for (int n = 0; n < 4; ++n) acc[m][n] = __builtin_amdgcn_mfma_f32_16x16x32_bf16(Bt[n], At[m], acc[m][n], 0, 0, 0);
;   }
	v_add3_u32 v252, v205, v147, s8
	v_add3_u32 v215, v205, v151, s8
	s_nop 0
	ds_read_b128 v[216:219], v252 offset:16384
	ds_read_b128 v[220:223], v252 offset:17408
	ds_read_b128 v[232:235], v252 offset:18432
	ds_read_b128 v[236:239], v252 offset:19456
	ds_read_b128 v[224:227], v215
	ds_read_b128 v[228:231], v215 offset:1024
	v_mfma_f32_16x16x32_bf16 v[28:31], v[240:243], v[180:183], v[28:31]
	v_mfma_f32_16x16x32_bf16 v[24:27], v[244:247], v[180:183], v[24:27]
	v_mfma_f32_16x16x32_bf16 v[20:23], v[248:251], v[180:183], v[20:23]
	v_mfma_f32_16x16x32_bf16 v[16:19], v[176:179], v[180:183], v[16:19]
	v_mfma_f32_16x16x32_bf16 v[12:15], v[240:243], v[210:213], v[12:15]
	v_mfma_f32_16x16x32_bf16 v[8:11], v[244:247], v[210:213], v[8:11]
	s_add_i32 s6, s8, 0x18000
	v_mfma_f32_16x16x32_bf16 v[4:7], v[248:251], v[210:213], v[4:7]
	s_and_b32 s6, s6, 0x18000
	v_mfma_f32_16x16x32_bf16 v[0:3], v[176:179], v[210:213], v[0:3]
	s_add_i32 s9, s6, s7
	v_lshl_add_u64 v[206:207], v[184:185], 0, s[4:5]
	s_mov_b32 m0, s9
	s_add_i32 s9, s9, 0x2000
	ds_read_b128 v[180:183], v215 offset:2048
	ds_read_b128 v[210:213], v215 offset:3072
	s_waitcnt lgkmcnt(2)
	v_mfma_f32_16x16x32_bf16 v[124:127], v[216:219], v[224:227], v[124:127]
	v_mfma_f32_16x16x32_bf16 v[120:123], v[220:223], v[224:227], v[120:123]
	v_mfma_f32_16x16x32_bf16 v[116:119], v[232:235], v[224:227], v[116:119]
	v_mfma_f32_16x16x32_bf16 v[112:115], v[236:239], v[224:227], v[112:115]
	v_mfma_f32_16x16x32_bf16 v[108:111], v[216:219], v[228:231], v[108:111]
	v_mfma_f32_16x16x32_bf16 v[104:107], v[220:223], v[228:231], v[104:107]
	v_mfma_f32_16x16x32_bf16 v[100:103], v[232:235], v[228:231], v[100:103]
	v_mfma_f32_16x16x32_bf16 v[96:99], v[236:239], v[228:231], v[96:99]
	ds_read_b128 v[224:227], v215 offset:4096
	ds_read_b128 v[228:231], v215 offset:5120
	s_waitcnt lgkmcnt(2)
	v_mfma_f32_16x16x32_bf16 v[92:95], v[216:219], v[180:183], v[92:95]
	v_mfma_f32_16x16x32_bf16 v[88:91], v[220:223], v[180:183], v[88:91]
	v_mfma_f32_16x16x32_bf16 v[84:87], v[232:235], v[180:183], v[84:87]
	v_mfma_f32_16x16x32_bf16 v[80:83], v[236:239], v[180:183], v[80:83]
	v_mfma_f32_16x16x32_bf16 v[76:79], v[216:219], v[210:213], v[76:79]
	v_mfma_f32_16x16x32_bf16 v[72:75], v[220:223], v[210:213], v[72:75]
	v_mfma_f32_16x16x32_bf16 v[68:71], v[232:235], v[210:213], v[68:71]
	v_mfma_f32_16x16x32_bf16 v[64:67], v[236:239], v[210:213], v[64:67]
	ds_read_b128 v[180:183], v215 offset:6144
	ds_read_b128 v[210:213], v215 offset:7168
	s_waitcnt lgkmcnt(2)
	v_mfma_f32_16x16x32_bf16 v[60:63], v[216:219], v[224:227], v[60:63]
	v_mfma_f32_16x16x32_bf16 v[56:59], v[220:223], v[224:227], v[56:59]
	v_mfma_f32_16x16x32_bf16 v[52:55], v[232:235], v[224:227], v[52:55]
	v_mfma_f32_16x16x32_bf16 v[48:51], v[236:239], v[224:227], v[48:51]
	v_mfma_f32_16x16x32_bf16 v[44:47], v[216:219], v[228:231], v[44:47]
	v_mfma_f32_16x16x32_bf16 v[40:43], v[220:223], v[228:231], v[40:43]
	v_mfma_f32_16x16x32_bf16 v[36:39], v[232:235], v[228:231], v[36:39]
	v_mfma_f32_16x16x32_bf16 v[32:35], v[236:239], v[228:231], v[32:35]
	s_add_i32 s8, s8, 0x8000
	s_and_b32 s8, s8, 0x18000
	s_waitcnt vmcnt(0) lgkmcnt(0)
	s_barrier
	v_add3_u32 v252, v205, v147, s8
	v_add3_u32 v215, v205, v151, s8
	s_nop 0
	ds_read_b128 v[240:243], v252 offset:16384
	ds_read_b128 v[244:247], v252 offset:17408
	ds_read_b128 v[248:251], v252 offset:18432
	ds_read_b128 v[176:179], v252 offset:19456
	ds_read_b128 v[224:227], v215
	ds_read_b128 v[228:231], v215 offset:1024
	v_mfma_f32_16x16x32_bf16 v[28:31], v[216:219], v[180:183], v[28:31]
	v_mfma_f32_16x16x32_bf16 v[24:27], v[220:223], v[180:183], v[24:27]
	v_mfma_f32_16x16x32_bf16 v[20:23], v[232:235], v[180:183], v[20:23]
	v_mfma_f32_16x16x32_bf16 v[16:19], v[236:239], v[180:183], v[16:19]
	v_mfma_f32_16x16x32_bf16 v[12:15], v[216:219], v[210:213], v[12:15]
	v_mfma_f32_16x16x32_bf16 v[8:11], v[220:223], v[210:213], v[8:11]
	s_add_i32 s6, s8, 0x18000
	v_mfma_f32_16x16x32_bf16 v[4:7], v[232:235], v[210:213], v[4:7]
	s_and_b32 s6, s6, 0x18000
	v_mfma_f32_16x16x32_bf16 v[0:3], v[236:239], v[210:213], v[0:3]
	s_add_i32 s9, s6, s7
	v_lshl_add_u64 v[206:207], v[184:185], 0, s[4:5]
	s_mov_b32 m0, s9
	s_add_i32 s9, s9, 0x2000
	ds_read_b128 v[180:183], v215 offset:2048
	ds_read_b128 v[210:213], v215 offset:3072
	s_waitcnt lgkmcnt(2)
	v_mfma_f32_16x16x32_bf16 v[124:127], v[240:243], v[224:227], v[124:127]
	v_mfma_f32_16x16x32_bf16 v[120:123], v[244:247], v[224:227], v[120:123]
	v_mfma_f32_16x16x32_bf16 v[116:119], v[248:251], v[224:227], v[116:119]
	v_mfma_f32_16x16x32_bf16 v[112:115], v[176:179], v[224:227], v[112:115]
	v_mfma_f32_16x16x32_bf16 v[108:111], v[240:243], v[228:231], v[108:111]
	v_mfma_f32_16x16x32_bf16 v[104:107], v[244:247], v[228:231], v[104:107]
	v_mfma_f32_16x16x32_bf16 v[100:103], v[248:251], v[228:231], v[100:103]
	v_mfma_f32_16x16x32_bf16 v[96:99], v[176:179], v[228:231], v[96:99]
	ds_read_b128 v[224:227], v215 offset:4096
	ds_read_b128 v[228:231], v215 offset:5120
	s_waitcnt lgkmcnt(2)
	v_mfma_f32_16x16x32_bf16 v[92:95], v[240:243], v[180:183], v[92:95]
	v_mfma_f32_16x16x32_bf16 v[88:91], v[244:247], v[180:183], v[88:91]
	v_mfma_f32_16x16x32_bf16 v[84:87], v[248:251], v[180:183], v[84:87]
	v_mfma_f32_16x16x32_bf16 v[80:83], v[176:179], v[180:183], v[80:83]
	v_mfma_f32_16x16x32_bf16 v[76:79], v[240:243], v[210:213], v[76:79]
	v_mfma_f32_16x16x32_bf16 v[72:75], v[244:247], v[210:213], v[72:75]
	v_mfma_f32_16x16x32_bf16 v[68:71], v[248:251], v[210:213], v[68:71]
	v_mfma_f32_16x16x32_bf16 v[64:67], v[176:179], v[210:213], v[64:67]
	ds_read_b128 v[180:183], v215 offset:6144
	ds_read_b128 v[210:213], v215 offset:7168
	s_waitcnt lgkmcnt(2)
	v_mfma_f32_16x16x32_bf16 v[60:63], v[240:243], v[224:227], v[60:63]
	v_mfma_f32_16x16x32_bf16 v[56:59], v[244:247], v[224:227], v[56:59]
	v_mfma_f32_16x16x32_bf16 v[52:55], v[248:251], v[224:227], v[52:55]
	v_mfma_f32_16x16x32_bf16 v[48:51], v[176:179], v[224:227], v[48:51]
	v_mfma_f32_16x16x32_bf16 v[44:47], v[240:243], v[228:231], v[44:47]
	v_mfma_f32_16x16x32_bf16 v[40:43], v[244:247], v[228:231], v[40:43]
	v_mfma_f32_16x16x32_bf16 v[36:39], v[248:251], v[228:231], v[36:39]
	v_mfma_f32_16x16x32_bf16 v[32:35], v[176:179], v[228:231], v[32:35]
	s_waitcnt lgkmcnt(0)
	v_mfma_f32_16x16x32_bf16 v[28:31], v[240:243], v[180:183], v[28:31]
	v_mfma_f32_16x16x32_bf16 v[24:27], v[244:247], v[180:183], v[24:27]
	v_mfma_f32_16x16x32_bf16 v[20:23], v[248:251], v[180:183], v[20:23]
	v_mfma_f32_16x16x32_bf16 v[16:19], v[176:179], v[180:183], v[16:19]
	v_mfma_f32_16x16x32_bf16 v[12:15], v[240:243], v[210:213], v[12:15]
	v_mfma_f32_16x16x32_bf16 v[8:11], v[244:247], v[210:213], v[8:11]
	s_add_i32 s6, s8, 0x18000
	v_mfma_f32_16x16x32_bf16 v[4:7], v[248:251], v[210:213], v[4:7]
	s_and_b32 s6, s6, 0x18000
	v_mfma_f32_16x16x32_bf16 v[0:3], v[176:179], v[210:213], v[0:3]
	s_add_i32 s9, s6, s7
	v_lshl_add_u64 v[206:207], v[184:185], 0, s[4:5]
	s_mov_b32 m0, s9
	s_add_i32 s9, s9, 0x2000
	s_nop 7
	s_nop 3
	s_and_b64 vcc, exec, s[10:11]
	s_cbranch_vccz .Lgemm_p1_u
; template <class Epi>
; DI void gemm_tile256(const u16* __restrict__ Ag, long lda, const u16* __restrict__ Bg, long ldb, int nk, char* shm, Epi&& epi) {
;     ...
;   for (int m = 0; m < 8; ++m)
; #pragma unroll
;     for (int n = 0; n < 4; ++n) epi(wr * 128 + m * 16 + fr, wc * 64 + n * 16 + fq * 4, acc[m][n]);
; DI void phase1(const Params& P, char* smem) {
;     ...
;         *reinterpret_cast<uint2*>(Qb + (long)r * 512 + (c - 512)) = pk;
;       } else if (bcol < 1536) {
;         *reinterpret_cast<uint2*>(Kb + (long)r * 512 + (c - 1024)) = pk;
	s_waitcnt vmcnt(0) lgkmcnt(0)
	s_barrier
	v_and_b32_e32 v184, 15, v208
	v_lshrrev_b32_e32 v185, 4, v208
	v_lshrrev_b32_e32 v186, 6, v189
	v_lshlrev_b32_e32 v186, 14, v186
	v_and_b32_e32 v187, 7, v184
	v_lshrrev_b32_e32 v206, 1, v185
	v_and_b32_e32 v207, 1, v185
	v_lshl_add_u32 v215, v184, 7, v186
	v_lshl_add_u32 v215, v207, 3, v215
	v_or_b32_e32 v252, 0, v206
	v_xor_b32_e32 v252, v252, v187
	v_lshl_add_u32 v176, v252, 4, v215
	v_or_b32_e32 v252, 2, v206
	v_xor_b32_e32 v252, v252, v187
	v_lshl_add_u32 v177, v252, 4, v215
	v_or_b32_e32 v252, 4, v206
	v_xor_b32_e32 v252, v252, v187
	v_lshl_add_u32 v178, v252, 4, v215
	v_or_b32_e32 v252, 6, v206
	v_xor_b32_e32 v252, v252, v187
	v_lshl_add_u32 v179, v252, 4, v215
	v_lshrrev_b32_e32 v253, 3, v208
	v_and_b32_e32 v210, 7, v208
	v_xor_b32_e32 v252, v210, v253
	v_lshl_add_u32 v180, v253, 7, v186
	v_lshl_add_u32 v180, v252, 4, v180
	v_lshl_add_u32 v252, v190, 7, v253
	v_add_u32_e32 v252, s30, v252
	v_lshlrev_b32_e32 v182, 10, v252
	v_bfe_u32 v252, v189, 6, 2
	v_lshl_add_u32 v182, v252, 7, v182
	v_lshl_add_u32 v182, v210, 4, v182
	v_mov_b32_e32 v183, 0
	s_and_b32 s36, s74, 1
	s_lshl_b32 s36, s36, 9
	s_and_b32 s37, s74, 4
	s_lshl_b32 s37, s37, 23
	s_add_u32 s36, s36, s37
	s_add_u32 s36, s78, s36
	s_addc_u32 s37, s79, 0
	v_lshl_add_u64 v[182:183], v[182:183], 0, s[36:37]
	s_mov_b32 s38, 0x2000
	s_mov_b32 s39, 0
	v_lshl_add_u64 v[240:241], v[182:183], 0, s[38:39]
	s_lshl_b32 s38, s38, 1
	v_cvt_pk_bf16_f32 v124, v124, v125
	v_cvt_pk_bf16_f32 v125, v126, v127
	ds_write_b64 v176, v[124:125] offset:0
	v_cvt_pk_bf16_f32 v120, v120, v121
	v_cvt_pk_bf16_f32 v121, v122, v123
	ds_write_b64 v177, v[120:121] offset:0
	v_cvt_pk_bf16_f32 v116, v116, v117
	v_cvt_pk_bf16_f32 v117, v118, v119
	ds_write_b64 v178, v[116:117] offset:0
	v_cvt_pk_bf16_f32 v112, v112, v113
	v_cvt_pk_bf16_f32 v113, v114, v115
	ds_write_b64 v179, v[112:113] offset:0
	v_cvt_pk_bf16_f32 v108, v108, v109
	v_cvt_pk_bf16_f32 v109, v110, v111
	ds_write_b64 v176, v[108:109] offset:2048
	v_cvt_pk_bf16_f32 v104, v104, v105
	v_cvt_pk_bf16_f32 v105, v106, v107
	ds_write_b64 v177, v[104:105] offset:2048
	v_cvt_pk_bf16_f32 v100, v100, v101
	v_cvt_pk_bf16_f32 v101, v102, v103
	ds_write_b64 v178, v[100:101] offset:2048
	v_cvt_pk_bf16_f32 v96, v96, v97
	v_cvt_pk_bf16_f32 v97, v98, v99
	ds_write_b64 v179, v[96:97] offset:2048
	v_cvt_pk_bf16_f32 v92, v92, v93
	v_cvt_pk_bf16_f32 v93, v94, v95
	ds_write_b64 v176, v[92:93] offset:4096
	v_cvt_pk_bf16_f32 v88, v88, v89
	v_cvt_pk_bf16_f32 v89, v90, v91
	ds_write_b64 v177, v[88:89] offset:4096
	v_cvt_pk_bf16_f32 v84, v84, v85
	v_cvt_pk_bf16_f32 v85, v86, v87
	ds_write_b64 v178, v[84:85] offset:4096
	v_cvt_pk_bf16_f32 v80, v80, v81
	v_cvt_pk_bf16_f32 v81, v82, v83
	ds_write_b64 v179, v[80:81] offset:4096
	v_cvt_pk_bf16_f32 v76, v76, v77
	v_cvt_pk_bf16_f32 v77, v78, v79
	ds_write_b64 v176, v[76:77] offset:6144
	v_cvt_pk_bf16_f32 v72, v72, v73
	v_cvt_pk_bf16_f32 v73, v74, v75
	ds_write_b64 v177, v[72:73] offset:6144
	v_cvt_pk_bf16_f32 v68, v68, v69
	v_cvt_pk_bf16_f32 v69, v70, v71
	ds_write_b64 v178, v[68:69] offset:6144
	v_cvt_pk_bf16_f32 v64, v64, v65
	v_cvt_pk_bf16_f32 v65, v66, v67
	ds_write_b64 v179, v[64:65] offset:6144
	v_cvt_pk_bf16_f32 v60, v60, v61
	v_cvt_pk_bf16_f32 v61, v62, v63
	ds_write_b64 v176, v[60:61] offset:8192
	v_cvt_pk_bf16_f32 v56, v56, v57
	v_cvt_pk_bf16_f32 v57, v58, v59
	ds_write_b64 v177, v[56:57] offset:8192
	v_cvt_pk_bf16_f32 v52, v52, v53
	v_cvt_pk_bf16_f32 v53, v54, v55
	ds_write_b64 v178, v[52:53] offset:8192
	v_cvt_pk_bf16_f32 v48, v48, v49
	v_cvt_pk_bf16_f32 v49, v50, v51
	ds_write_b64 v179, v[48:49] offset:8192
	v_cvt_pk_bf16_f32 v44, v44, v45
	v_cvt_pk_bf16_f32 v45, v46, v47
	ds_write_b64 v176, v[44:45] offset:10240
	v_cvt_pk_bf16_f32 v40, v40, v41
	v_cvt_pk_bf16_f32 v41, v42, v43
	ds_write_b64 v177, v[40:41] offset:10240
	v_cvt_pk_bf16_f32 v36, v36, v37
	v_cvt_pk_bf16_f32 v37, v38, v39
	ds_write_b64 v178, v[36:37] offset:10240
	v_cvt_pk_bf16_f32 v32, v32, v33
	v_cvt_pk_bf16_f32 v33, v34, v35
	ds_write_b64 v179, v[32:33] offset:10240
	v_cvt_pk_bf16_f32 v28, v28, v29
	v_cvt_pk_bf16_f32 v29, v30, v31
	ds_write_b64 v176, v[28:29] offset:12288
	v_cvt_pk_bf16_f32 v24, v24, v25
	v_cvt_pk_bf16_f32 v25, v26, v27
	ds_write_b64 v177, v[24:25] offset:12288
	v_cvt_pk_bf16_f32 v20, v20, v21
	v_cvt_pk_bf16_f32 v21, v22, v23
	ds_write_b64 v178, v[20:21] offset:12288
	v_cvt_pk_bf16_f32 v16, v16, v17
	v_cvt_pk_bf16_f32 v17, v18, v19
	ds_write_b64 v179, v[16:17] offset:12288
	v_cvt_pk_bf16_f32 v12, v12, v13
	v_cvt_pk_bf16_f32 v13, v14, v15
	ds_write_b64 v176, v[12:13] offset:14336
	v_cvt_pk_bf16_f32 v8, v8, v9
	v_cvt_pk_bf16_f32 v9, v10, v11
	ds_write_b64 v177, v[8:9] offset:14336
	v_cvt_pk_bf16_f32 v4, v4, v5
	v_cvt_pk_bf16_f32 v5, v6, v7
	ds_write_b64 v178, v[4:5] offset:14336
	v_cvt_pk_bf16_f32 v0, v0, v1
	v_cvt_pk_bf16_f32 v1, v2, v3
	ds_write_b64 v179, v[0:1] offset:14336
	s_waitcnt lgkmcnt(0)
; DI void phase1(const Params& P, char* smem) {
;     ...
;         *reinterpret_cast<uint2*>(Qb + (long)r * 512 + (c - 512)) = pk;
;       } else if (bcol < 1536) {
;         *reinterpret_cast<uint2*>(Kb + (long)r * 512 + (c - 1024)) = pk;
	ds_read_b128 v[216:219], v180 offset:0
	ds_read_b128 v[220:223], v180 offset:1024
	ds_read_b128 v[224:227], v180 offset:2048
	ds_read_b128 v[228:231], v180 offset:3072
	s_waitcnt lgkmcnt(3)
	global_store_dwordx4 v[182:183], v[216:219], off
	s_nop 0
	v_lshl_add_u64 v[182:183], v[182:183], 0, s[38:39]
	s_waitcnt lgkmcnt(2)
	global_store_dwordx4 v[240:241], v[220:223], off
	s_nop 0
	v_lshl_add_u64 v[240:241], v[240:241], 0, s[38:39]
	s_waitcnt lgkmcnt(1)
	global_store_dwordx4 v[182:183], v[224:227], off
	s_nop 0
	v_lshl_add_u64 v[182:183], v[182:183], 0, s[38:39]
	s_waitcnt lgkmcnt(0)
	global_store_dwordx4 v[240:241], v[228:231], off
	s_nop 0
	v_lshl_add_u64 v[240:241], v[240:241], 0, s[38:39]
	ds_read_b128 v[232:235], v180 offset:4096
	ds_read_b128 v[236:239], v180 offset:5120
	ds_read_b128 v[244:247], v180 offset:6144
	ds_read_b128 v[248:251], v180 offset:7168
	s_waitcnt lgkmcnt(3)
	global_store_dwordx4 v[182:183], v[232:235], off
	s_nop 0
	v_lshl_add_u64 v[182:183], v[182:183], 0, s[38:39]
	s_waitcnt lgkmcnt(2)
	global_store_dwordx4 v[240:241], v[236:239], off
	s_nop 0
	v_lshl_add_u64 v[240:241], v[240:241], 0, s[38:39]
	s_waitcnt lgkmcnt(1)
	global_store_dwordx4 v[182:183], v[244:247], off
	s_nop 0
	v_lshl_add_u64 v[182:183], v[182:183], 0, s[38:39]
	s_waitcnt lgkmcnt(0)
	global_store_dwordx4 v[240:241], v[248:251], off
	s_nop 0
	v_lshl_add_u64 v[240:241], v[240:241], 0, s[38:39]
	ds_read_b128 v[216:219], v180 offset:8192
	ds_read_b128 v[220:223], v180 offset:9216
	ds_read_b128 v[224:227], v180 offset:10240
	ds_read_b128 v[228:231], v180 offset:11264
	s_waitcnt lgkmcnt(3)
	global_store_dwordx4 v[182:183], v[216:219], off
	s_nop 0
	v_lshl_add_u64 v[182:183], v[182:183], 0, s[38:39]
	s_waitcnt lgkmcnt(2)
	global_store_dwordx4 v[240:241], v[220:223], off
	s_nop 0
	v_lshl_add_u64 v[240:241], v[240:241], 0, s[38:39]
	s_waitcnt lgkmcnt(1)
	global_store_dwordx4 v[182:183], v[224:227], off
	s_nop 0
	v_lshl_add_u64 v[182:183], v[182:183], 0, s[38:39]
	s_waitcnt lgkmcnt(0)
	global_store_dwordx4 v[240:241], v[228:231], off
	s_nop 0
	v_lshl_add_u64 v[240:241], v[240:241], 0, s[38:39]
	ds_read_b128 v[232:235], v180 offset:12288
	ds_read_b128 v[236:239], v180 offset:13312
	ds_read_b128 v[244:247], v180 offset:14336
	ds_read_b128 v[248:251], v180 offset:15360
	s_waitcnt lgkmcnt(3)
	global_store_dwordx4 v[182:183], v[232:235], off
	s_nop 0
	v_lshl_add_u64 v[182:183], v[182:183], 0, s[38:39]
	s_waitcnt lgkmcnt(2)
	global_store_dwordx4 v[240:241], v[236:239], off
	s_nop 0
	v_lshl_add_u64 v[240:241], v[240:241], 0, s[38:39]
	s_waitcnt lgkmcnt(1)
	global_store_dwordx4 v[182:183], v[244:247], off
	s_nop 0
	v_lshl_add_u64 v[182:183], v[182:183], 0, s[38:39]
	s_waitcnt lgkmcnt(0)
	global_store_dwordx4 v[240:241], v[248:251], off
	s_nop 0
	v_lshl_add_u64 v[240:241], v[240:241], 0, s[38:39]
	v_or_b32_e32 v212, 0x50, v153
	v_or_b32_e32 v213, 0x60, v153
	s_branch .LBB0_106

; template <class Epi>
; DI void gemm_tile256(const u16* __restrict__ Ag, long lda, const u16* __restrict__ Bg, long ldb, int nk, char* shm, Epi&& epi) {
;   const int tid = RTID, wid = tid >> 6, lane = tid & 63, wr = wid >> 2, wc = wid & 3, fr = lane & 15, fq = lane >> 4;
;   f32x4 acc[8][4];
; #pragma unroll
;   for (int m = 0; m < 8; ++m)
; #pragma unroll
;     for (int n = 0; n < 4; ++n) acc[m][n] = f32x4{0.f, 0.f, 0.f, 0.f};
;   const int q0 = tid, q1 = 512 + tid;
;   const int r0 = q0 >> 2, r1 = q1 >> 2, c0 = (q0 & 3) ^ ((r0 >> 2) & 3), c1 = (q1 & 3) ^ ((r1 >> 2) & 3);
;   const u16* a0 = Ag + (long)r0 * lda + c0 * 8; const u16* a1 = Ag + (long)r1 * lda + c1 * 8;
;   const u16* b0 = Bg + (long)r0 * ldb + c0 * 8; const u16* b1 = Bg + (long)r1 * ldb + c1 * 8;
;   auto stage = [&](int j) {
;     char* SA = shm + (j & 3) * 32768; char* SB = SA + 16384;
;     __builtin_amdgcn_global_load_lds((const unsigned*)(a0 + j * 32), (__attribute__((address_space(3))) unsigned*)(SA + q0 * 16), 16, 0, 0);
;     __builtin_amdgcn_global_load_lds((const unsigned*)(a1 + j * 32), (__attribute__((address_space(3))) unsigned*)(SA + q1 * 16), 16, 0, 0);
;     __builtin_amdgcn_global_load_lds((const unsigned*)(b0 + j * 32), (__attribute__((address_space(3))) unsigned*)(SB + q0 * 16), 16, 0, 0);
;     __builtin_amdgcn_global_load_lds((const unsigned*)(b1 + j * 32), (__attribute__((address_space(3))) unsigned*)(SB + q1 * 16), 16, 0, 0);
;   };
;   __syncthreads();
;   stage(0);
;   if (nk > 1) stage(1);
;   if (nk > 2) stage(2);
; DI void phase6(const Params& P, char* smem) {
;     ...
;   for (int q = RBLK >> 3; q < 64; q += RGRID >> 3) {
;     const int brow = (q * 2 + ((RBLK & 7) >> 2)) * 256, bcol = (RBLK & 3) * 256;
;     gemm_tile256(cat + (long)brow * 1024, 1024, WoT + (long)bcol * 1024, 1024, 32, smem, [&](int row, int col0, f32x4 v) {
.LBB0_946:
	s_ashr_i32 s5, s4, 31
	s_lshl_b64 s[10:11], s[4:5], 11
	s_lshl_b32 s5, s15, 9
	v_lshl_add_u64 v[164:165], v[156:157], 0, s[10:11]
	v_lshl_add_u64 v[166:167], v[158:159], 0, s[10:11]
	s_or_b32 s10, s5, s2
	s_ashr_i32 s11, s10, 31
	s_lshl_b64 s[12:13], s[10:11], 11
	s_add_u32 s12, s62, s12
	s_addc_u32 s13, s63, s13
	v_add_u32_e32 v6, 0, v209
	v_lshl_add_u64 v[0:1], s[12:13], 0, v[130:131]
	v_readfirstlane_b32 s5, v6
	v_add_u32_e32 v7, 0, v149
	v_lshl_add_u64 v[0:1], v[0:1], 0, v[132:133]
	v_lshl_add_u64 v[2:3], s[12:13], 0, v[134:135]
	s_mov_b32 m0, s5
	v_readfirstlane_b32 s5, v7
	v_add_u32_e32 v4, 0x4000, v6
	v_lshl_add_u64 v[2:3], v[2:3], 0, v[132:133]
	s_barrier
	global_load_lds_dwordx4 v[0:1], off
	s_mov_b32 m0, s5
	v_readfirstlane_b32 s5, v4
	v_add_u32_e32 v4, 0x4000, v7
	global_load_lds_dwordx4 v[2:3], off
	s_mov_b32 m0, s5
	v_readfirstlane_b32 s5, v4
	v_add_u32_e32 v8, 0x8000, v6
	global_load_lds_dwordx4 v[136:137], off
	s_mov_b32 m0, s5
	v_readfirstlane_b32 s5, v8
	v_add_u32_e32 v8, 0x8000, v7
	global_load_lds_dwordx4 v[138:139], off
	v_lshl_add_u64 v[4:5], v[0:1], 0, 64
	s_mov_b32 m0, s5
	v_readfirstlane_b32 s5, v8
	global_load_lds_dwordx4 v[4:5], off
	v_lshl_add_u64 v[4:5], v[2:3], 0, 64
	s_mov_b32 m0, s5
	v_lshl_add_u64 v[0:1], v[0:1], 0, s[0:1]
	global_load_lds_dwordx4 v[4:5], off
	v_add_u32_e32 v4, 0xc000, v6
	s_mov_b64 s[12:13], 0
	v_readfirstlane_b32 s5, v4
	v_add_u32_e32 v4, 0xc000, v7
	s_mov_b32 m0, s5
	v_readfirstlane_b32 s5, v4
	v_add_u32_e32 v4, s7, v209
	global_load_lds_dwordx4 v[140:141], off
	s_mov_b32 m0, s5
	v_readfirstlane_b32 s5, v4
	global_load_lds_dwordx4 v[142:143], off
	s_mov_b32 m0, s5
	v_mov_b32_e32 v4, 0
	global_load_lds_dwordx4 v[0:1], off
	v_lshl_add_u64 v[0:1], v[2:3], 0, s[0:1]
	v_add_u32_e32 v2, s7, v149
	v_mov_b32_e32 v3, v133
	v_readfirstlane_b32 s5, v2
	s_mov_b32 m0, s5
	v_mov_b32_e32 v2, v133
	global_load_lds_dwordx4 v[0:1], off
	v_add_u32_e32 v0, s8, v209
	v_mov_b32_e32 v1, v133
	v_readfirstlane_b32 s5, v0
	v_add_u32_e32 v0, s8, v149
	s_mov_b32 m0, s5
	v_readfirstlane_b32 s5, v0
	global_load_lds_dwordx4 v[144:145], off
	s_mov_b32 m0, s5
	s_mov_b32 s5, 0x18000
	global_load_lds_dwordx4 v[146:147], off
	v_mov_b32_e32 v0, 0
	v_mov_b32_e32 v5, v133
	v_mov_b32_e32 v6, v133
	v_mov_b32_e32 v7, v133
	v_mov_b32_e32 v8, 0
	v_mov_b32_e32 v9, v133
	v_mov_b32_e32 v10, v133
	v_mov_b32_e32 v11, v133
	v_mov_b32_e32 v12, 0
	v_mov_b32_e32 v13, v133
	v_mov_b32_e32 v14, v133
	v_mov_b32_e32 v15, v133
	v_mov_b32_e32 v16, 0
	v_mov_b32_e32 v17, v133
	v_mov_b32_e32 v18, v133
	v_mov_b32_e32 v19, v133
	v_mov_b32_e32 v20, 0
	v_mov_b32_e32 v21, v133
	v_mov_b32_e32 v22, v133
	v_mov_b32_e32 v23, v133
	v_mov_b32_e32 v24, 0
	v_mov_b32_e32 v25, v133
	v_mov_b32_e32 v26, v133
	v_mov_b32_e32 v27, v133
	v_mov_b32_e32 v28, 0
	v_mov_b32_e32 v29, v133
	v_mov_b32_e32 v30, v133
	v_mov_b32_e32 v31, v133
	v_mov_b32_e32 v32, 0
	v_mov_b32_e32 v33, v133
	v_mov_b32_e32 v34, v133
	v_mov_b32_e32 v35, v133
	v_mov_b32_e32 v36, 0
	v_mov_b32_e32 v37, v133
	v_mov_b32_e32 v38, v133
	v_mov_b32_e32 v39, v133
	v_mov_b32_e32 v40, 0
	v_mov_b32_e32 v41, v133
	v_mov_b32_e32 v42, v133
	v_mov_b32_e32 v43, v133
	v_mov_b32_e32 v44, 0
	v_mov_b32_e32 v45, v133
	v_mov_b32_e32 v46, v133
	v_mov_b32_e32 v47, v133
	v_mov_b32_e32 v48, 0
	v_mov_b32_e32 v49, v133
	v_mov_b32_e32 v50, v133
	v_mov_b32_e32 v51, v133
	v_mov_b32_e32 v52, 0
	v_mov_b32_e32 v53, v133
	v_mov_b32_e32 v54, v133
	v_mov_b32_e32 v55, v133
	v_mov_b32_e32 v56, 0
	v_mov_b32_e32 v57, v133
	v_mov_b32_e32 v58, v133
	v_mov_b32_e32 v59, v133
	v_mov_b32_e32 v60, 0
	v_mov_b32_e32 v61, v133
	v_mov_b32_e32 v62, v133
	v_mov_b32_e32 v63, v133
	v_mov_b32_e32 v64, 0
	v_mov_b32_e32 v65, v133
	v_mov_b32_e32 v66, v133
	v_mov_b32_e32 v67, v133
	v_mov_b32_e32 v68, 0
	v_mov_b32_e32 v69, v133
	v_mov_b32_e32 v70, v133
	v_mov_b32_e32 v71, v133
	v_mov_b32_e32 v72, 0
	v_mov_b32_e32 v73, v133
	v_mov_b32_e32 v74, v133
	v_mov_b32_e32 v75, v133
	v_mov_b32_e32 v76, 0
	v_mov_b32_e32 v77, v133
	v_mov_b32_e32 v78, v133
	v_mov_b32_e32 v79, v133
	v_mov_b32_e32 v80, 0
	v_mov_b32_e32 v81, v133
	v_mov_b32_e32 v82, v133
	v_mov_b32_e32 v83, v133
	v_mov_b32_e32 v84, 0
	v_mov_b32_e32 v85, v133
	v_mov_b32_e32 v86, v133
	v_mov_b32_e32 v87, v133
	v_mov_b32_e32 v88, 0
	v_mov_b32_e32 v89, v133
	v_mov_b32_e32 v90, v133
	v_mov_b32_e32 v91, v133
	v_mov_b32_e32 v92, 0
	v_mov_b32_e32 v93, v133
	v_mov_b32_e32 v94, v133
	v_mov_b32_e32 v95, v133
	v_mov_b32_e32 v96, 0
	v_mov_b32_e32 v97, v133
	v_mov_b32_e32 v98, v133
	v_mov_b32_e32 v99, v133
	v_mov_b32_e32 v100, 0
	v_mov_b32_e32 v101, v133
	v_mov_b32_e32 v102, v133
	v_mov_b32_e32 v103, v133
	v_mov_b32_e32 v104, 0
	v_mov_b32_e32 v105, v133
	v_mov_b32_e32 v106, v133
	v_mov_b32_e32 v107, v133
	v_mov_b32_e32 v108, 0
	v_mov_b32_e32 v109, v133
	v_mov_b32_e32 v110, v133
	v_mov_b32_e32 v111, v133
	v_mov_b32_e32 v112, 0
	v_mov_b32_e32 v113, v133
	v_mov_b32_e32 v114, v133
	v_mov_b32_e32 v115, v133
	v_mov_b32_e32 v116, 0
	v_mov_b32_e32 v117, v133
	v_mov_b32_e32 v118, v133
	v_mov_b32_e32 v119, v133
	v_mov_b32_e32 v120, 0
	v_mov_b32_e32 v121, v133
	v_mov_b32_e32 v122, v133
	v_mov_b32_e32 v123, v133
	v_mov_b32_e32 v124, 0
	v_mov_b32_e32 v125, v133
	v_mov_b32_e32 v126, v133
	v_mov_b32_e32 v127, v133
	v_readfirstlane_b32 s16, v209
	s_mov_b32 s5, 0
	s_mov_b64 s[12:13], 0
	s_waitcnt vmcnt(8)
	s_barrier
	v_add3_u32 v231, v183, v151, s5
	v_add3_u32 v230, v183, v153, s5
	s_nop 0
	ds_read_b128 v[196:199], v231 offset:16384
	ds_read_b128 v[200:203], v231 offset:17408
	ds_read_b128 v[214:217], v231 offset:18432
	ds_read_b128 v[218:221], v231 offset:19456
	ds_read_b128 v[204:207], v230
	ds_read_b128 v[210:213], v230 offset:1024
	s_add_i32 s17, s16, 0x18000
	v_lshl_add_u64 v[226:227], v[164:165], 0, s[12:13]
	s_mov_b32 m0, s17
	s_add_i32 s17, s17, 0x2000
; template <class Epi>
; DI void gemm_tile256(const u16* __restrict__ Ag, long lda, const u16* __restrict__ Bg, long ldb, int nk, char* shm, Epi&& epi) {
;     ...
;   for (int i = 0; i < nk; ++i) {
;     if (i + 2 < nk) asm volatile("s_waitcnt vmcnt(8)" ::: "memory");
;     else if (i + 1 < nk) asm volatile("s_waitcnt vmcnt(4)" ::: "memory");
;     else asm volatile("s_waitcnt vmcnt(0)" ::: "memory");
;     __builtin_amdgcn_s_barrier();
;     const char* SA = shm + (i & 3) * 32768; const char* SB = SA + 16384;
;     bf16x8 At[8], Bt[4];
; #pragma unroll
;     for (int n = 0; n < 4; ++n) { const int rb = wc * 64 + n * 16 + fr; Bt[n] = *reinterpret_cast<const bf16x8*>(SB + rb * 64 + ((fq ^ ((rb >> 2) & 3)) * 16)); }
; #pragma unroll
;     for (int m = 0; m < 8; ++m) { const int ra = wr * 128 + m * 16 + fr; At[m] = *reinterpret_cast<const bf16x8*>(SA + ra * 64 + ((fq ^ ((ra >> 2) & 3)) * 16)); }
;     if (i + 3 < nk) stage(i + 3);
; #pragma unroll
;     for (int m = 0; m < 8; ++m)
; #pragma unroll
;       for (int n = 0; n < 4; ++n) acc[m][n] = __builtin_amdgcn_mfma_f32_16x16x32_bf16(Bt[n], At[m], acc[m][n], 0, 0, 0);
;   }
.Lgemm_p6_kloop0:
	ds_read_b128 v[248:251], v230 offset:2048
	ds_read_b128 v[222:225], v230 offset:3072
	s_waitcnt lgkmcnt(2)
	v_mfma_f32_16x16x32_bf16 v[124:127], v[196:199], v[204:207], v[124:127]
	global_load_lds_dwordx4 v[226:227], off
	v_mfma_f32_16x16x32_bf16 v[120:123], v[200:203], v[204:207], v[120:123]
	v_mfma_f32_16x16x32_bf16 v[116:119], v[214:217], v[204:207], v[116:119]
	v_mfma_f32_16x16x32_bf16 v[112:115], v[218:221], v[204:207], v[112:115]
	v_mfma_f32_16x16x32_bf16 v[108:111], v[196:199], v[210:213], v[108:111]
	v_mfma_f32_16x16x32_bf16 v[104:107], v[200:203], v[210:213], v[104:107]
	v_lshl_add_u64 v[226:227], v[166:167], 0, s[12:13]
	v_mfma_f32_16x16x32_bf16 v[100:103], v[214:217], v[210:213], v[100:103]
	s_mov_b32 m0, s17
	v_mfma_f32_16x16x32_bf16 v[96:99], v[218:221], v[210:213], v[96:99]
	s_add_i32 s17, s17, 0x2000
	ds_read_b128 v[204:207], v230 offset:4096
	ds_read_b128 v[210:213], v230 offset:5120
	s_waitcnt lgkmcnt(2)
	v_mfma_f32_16x16x32_bf16 v[92:95], v[196:199], v[248:251], v[92:95]
	global_load_lds_dwordx4 v[226:227], off
	v_mfma_f32_16x16x32_bf16 v[88:91], v[200:203], v[248:251], v[88:91]
	v_mfma_f32_16x16x32_bf16 v[84:87], v[214:217], v[248:251], v[84:87]
	v_mfma_f32_16x16x32_bf16 v[80:83], v[218:221], v[248:251], v[80:83]
	v_mfma_f32_16x16x32_bf16 v[76:79], v[196:199], v[222:225], v[76:79]
	v_mfma_f32_16x16x32_bf16 v[72:75], v[200:203], v[222:225], v[72:75]
	v_lshl_add_u64 v[226:227], v[160:161], 0, s[12:13]
	v_mfma_f32_16x16x32_bf16 v[68:71], v[214:217], v[222:225], v[68:71]
	s_mov_b32 m0, s17
	v_mfma_f32_16x16x32_bf16 v[64:67], v[218:221], v[222:225], v[64:67]
	s_add_i32 s17, s17, 0x2000
	ds_read_b128 v[248:251], v230 offset:6144
	ds_read_b128 v[222:225], v230 offset:7168
	s_waitcnt lgkmcnt(2)
	v_mfma_f32_16x16x32_bf16 v[60:63], v[196:199], v[204:207], v[60:63]
	global_load_lds_dwordx4 v[226:227], off
	v_mfma_f32_16x16x32_bf16 v[56:59], v[200:203], v[204:207], v[56:59]
	v_mfma_f32_16x16x32_bf16 v[52:55], v[214:217], v[204:207], v[52:55]
	v_mfma_f32_16x16x32_bf16 v[48:51], v[218:221], v[204:207], v[48:51]
	v_mfma_f32_16x16x32_bf16 v[44:47], v[196:199], v[210:213], v[44:47]
	v_mfma_f32_16x16x32_bf16 v[40:43], v[200:203], v[210:213], v[40:43]
	v_lshl_add_u64 v[226:227], v[162:163], 0, s[12:13]
	v_mfma_f32_16x16x32_bf16 v[36:39], v[214:217], v[210:213], v[36:39]
	s_mov_b32 m0, s17
	v_mfma_f32_16x16x32_bf16 v[32:35], v[218:221], v[210:213], v[32:35]
	s_add_i32 s17, s17, 0x2000
	s_add_u32 s12, s12, 64
	s_addc_u32 s13, s13, 0
	s_add_i32 s5, s5, 0x8000
	s_and_b32 s5, s5, 0x18000
	s_waitcnt vmcnt(7) lgkmcnt(0)
	s_barrier
	v_add3_u32 v231, v183, v151, s5
	v_add3_u32 v230, v183, v153, s5
	s_nop 0
	ds_read_b128 v[232:235], v231 offset:16384
	ds_read_b128 v[236:239], v231 offset:17408
	ds_read_b128 v[240:243], v231 offset:18432
	ds_read_b128 v[244:247], v231 offset:19456
	ds_read_b128 v[204:207], v230
	ds_read_b128 v[210:213], v230 offset:1024
	v_mfma_f32_16x16x32_bf16 v[28:31], v[196:199], v[248:251], v[28:31]
	global_load_lds_dwordx4 v[226:227], off
	v_mfma_f32_16x16x32_bf16 v[24:27], v[200:203], v[248:251], v[24:27]
	v_mfma_f32_16x16x32_bf16 v[20:23], v[214:217], v[248:251], v[20:23]
	v_mfma_f32_16x16x32_bf16 v[16:19], v[218:221], v[248:251], v[16:19]
	v_mfma_f32_16x16x32_bf16 v[12:15], v[196:199], v[222:225], v[12:15]
	v_mfma_f32_16x16x32_bf16 v[8:11], v[200:203], v[222:225], v[8:11]
	s_add_i32 s11, s5, 0x18000
	v_mfma_f32_16x16x32_bf16 v[4:7], v[214:217], v[222:225], v[4:7]
	s_and_b32 s11, s11, 0x18000
	v_mfma_f32_16x16x32_bf16 v[0:3], v[218:221], v[222:225], v[0:3]
	s_add_i32 s17, s11, s16
	v_lshl_add_u64 v[226:227], v[164:165], 0, s[12:13]
	s_mov_b32 m0, s17
	s_add_i32 s17, s17, 0x2000
	ds_read_b128 v[248:251], v230 offset:2048
	ds_read_b128 v[222:225], v230 offset:3072
	s_waitcnt lgkmcnt(2)
	v_mfma_f32_16x16x32_bf16 v[124:127], v[232:235], v[204:207], v[124:127]
	global_load_lds_dwordx4 v[226:227], off
	v_mfma_f32_16x16x32_bf16 v[120:123], v[236:239], v[204:207], v[120:123]
	v_mfma_f32_16x16x32_bf16 v[116:119], v[240:243], v[204:207], v[116:119]
	v_mfma_f32_16x16x32_bf16 v[112:115], v[244:247], v[204:207], v[112:115]
	v_mfma_f32_16x16x32_bf16 v[108:111], v[232:235], v[210:213], v[108:111]
	v_mfma_f32_16x16x32_bf16 v[104:107], v[236:239], v[210:213], v[104:107]
	v_lshl_add_u64 v[226:227], v[166:167], 0, s[12:13]
	v_mfma_f32_16x16x32_bf16 v[100:103], v[240:243], v[210:213], v[100:103]
	s_mov_b32 m0, s17
	v_mfma_f32_16x16x32_bf16 v[96:99], v[244:247], v[210:213], v[96:99]
	s_add_i32 s17, s17, 0x2000
	ds_read_b128 v[204:207], v230 offset:4096
	ds_read_b128 v[210:213], v230 offset:5120
	s_waitcnt lgkmcnt(2)
	v_mfma_f32_16x16x32_bf16 v[92:95], v[232:235], v[248:251], v[92:95]
	global_load_lds_dwordx4 v[226:227], off
	v_mfma_f32_16x16x32_bf16 v[88:91], v[236:239], v[248:251], v[88:91]
	v_mfma_f32_16x16x32_bf16 v[84:87], v[240:243], v[248:251], v[84:87]
	v_mfma_f32_16x16x32_bf16 v[80:83], v[244:247], v[248:251], v[80:83]
	v_mfma_f32_16x16x32_bf16 v[76:79], v[232:235], v[222:225], v[76:79]
	v_mfma_f32_16x16x32_bf16 v[72:75], v[236:239], v[222:225], v[72:75]
	v_lshl_add_u64 v[226:227], v[160:161], 0, s[12:13]
	v_mfma_f32_16x16x32_bf16 v[68:71], v[240:243], v[222:225], v[68:71]
	s_mov_b32 m0, s17
	v_mfma_f32_16x16x32_bf16 v[64:67], v[244:247], v[222:225], v[64:67]
	s_add_i32 s17, s17, 0x2000
	ds_read_b128 v[248:251], v230 offset:6144
	ds_read_b128 v[222:225], v230 offset:7168
	s_waitcnt lgkmcnt(2)
	v_mfma_f32_16x16x32_bf16 v[60:63], v[232:235], v[204:207], v[60:63]
	global_load_lds_dwordx4 v[226:227], off
	v_mfma_f32_16x16x32_bf16 v[56:59], v[236:239], v[204:207], v[56:59]
	v_mfma_f32_16x16x32_bf16 v[52:55], v[240:243], v[204:207], v[52:55]
	v_mfma_f32_16x16x32_bf16 v[48:51], v[244:247], v[204:207], v[48:51]
	v_mfma_f32_16x16x32_bf16 v[44:47], v[232:235], v[210:213], v[44:47]
	v_mfma_f32_16x16x32_bf16 v[40:43], v[236:239], v[210:213], v[40:43]
	v_lshl_add_u64 v[226:227], v[162:163], 0, s[12:13]
	v_mfma_f32_16x16x32_bf16 v[36:39], v[240:243], v[210:213], v[36:39]
	s_mov_b32 m0, s17
	v_mfma_f32_16x16x32_bf16 v[32:35], v[244:247], v[210:213], v[32:35]
	s_add_i32 s17, s17, 0x2000
	s_add_u32 s12, s12, 64
	s_addc_u32 s13, s13, 0
	s_add_i32 s5, s5, 0x8000
	s_and_b32 s5, s5, 0x18000
	s_waitcnt vmcnt(7) lgkmcnt(0)
	s_barrier
; template <class Epi>
; DI void gemm_tile256(const u16* __restrict__ Ag, long lda, const u16* __restrict__ Bg, long ldb, int nk, char* shm, Epi&& epi) {
;     ...
;   for (int i = 0; i < nk; ++i) {
;     if (i + 2 < nk) asm volatile("s_waitcnt vmcnt(8)" ::: "memory");
;     else if (i + 1 < nk) asm volatile("s_waitcnt vmcnt(4)" ::: "memory");
;     else asm volatile("s_waitcnt vmcnt(0)" ::: "memory");
;     __builtin_amdgcn_s_barrier();
;     const char* SA = shm + (i & 3) * 32768; const char* SB = SA + 16384;
;     bf16x8 At[8], Bt[4];
; #pragma unroll
;     for (int n = 0; n < 4; ++n) { const int rb = wc * 64 + n * 16 + fr; Bt[n] = *reinterpret_cast<const bf16x8*>(SB + rb * 64 + ((fq ^ ((rb >> 2) & 3)) * 16)); }
; #pragma unroll
;     for (int m = 0; m < 8; ++m) { const int ra = wr * 128 + m * 16 + fr; At[m] = *reinterpret_cast<const bf16x8*>(SA + ra * 64 + ((fq ^ ((ra >> 2) & 3)) * 16)); }
;     if (i + 3 < nk) stage(i + 3);
; #pragma unroll
;     for (int m = 0; m < 8; ++m)
; #pragma unroll
;       for (int n = 0; n < 4; ++n) acc[m][n] = __builtin_amdgcn_mfma_f32_16x16x32_bf16(Bt[n], At[m], acc[m][n], 0, 0, 0);
;   }
	v_add3_u32 v231, v183, v151, s5
	v_add3_u32 v230, v183, v153, s5
	s_nop 0
	ds_read_b128 v[196:199], v231 offset:16384
	ds_read_b128 v[200:203], v231 offset:17408
	ds_read_b128 v[214:217], v231 offset:18432
	ds_read_b128 v[218:221], v231 offset:19456
	ds_read_b128 v[204:207], v230
	ds_read_b128 v[210:213], v230 offset:1024
	v_mfma_f32_16x16x32_bf16 v[28:31], v[232:235], v[248:251], v[28:31]
	global_load_lds_dwordx4 v[226:227], off
	v_mfma_f32_16x16x32_bf16 v[24:27], v[236:239], v[248:251], v[24:27]
	v_mfma_f32_16x16x32_bf16 v[20:23], v[240:243], v[248:251], v[20:23]
	v_mfma_f32_16x16x32_bf16 v[16:19], v[244:247], v[248:251], v[16:19]
	v_mfma_f32_16x16x32_bf16 v[12:15], v[232:235], v[222:225], v[12:15]
	v_mfma_f32_16x16x32_bf16 v[8:11], v[236:239], v[222:225], v[8:11]
	s_add_i32 s11, s5, 0x18000
	v_mfma_f32_16x16x32_bf16 v[4:7], v[240:243], v[222:225], v[4:7]
	s_and_b32 s11, s11, 0x18000
	v_mfma_f32_16x16x32_bf16 v[0:3], v[244:247], v[222:225], v[0:3]
	s_add_i32 s17, s11, s16
	v_lshl_add_u64 v[226:227], v[164:165], 0, s[12:13]
	s_mov_b32 m0, s17
	s_add_i32 s17, s17, 0x2000
	s_cmpk_lg_i32 s12, 0x700
	s_cbranch_scc1 .Lgemm_p6_kloop0
	ds_read_b128 v[248:251], v230 offset:2048
	ds_read_b128 v[222:225], v230 offset:3072
	s_waitcnt lgkmcnt(2)
	v_mfma_f32_16x16x32_bf16 v[124:127], v[196:199], v[204:207], v[124:127]
	global_load_lds_dwordx4 v[226:227], off
	v_mfma_f32_16x16x32_bf16 v[120:123], v[200:203], v[204:207], v[120:123]
	v_mfma_f32_16x16x32_bf16 v[116:119], v[214:217], v[204:207], v[116:119]
	v_mfma_f32_16x16x32_bf16 v[112:115], v[218:221], v[204:207], v[112:115]
	v_mfma_f32_16x16x32_bf16 v[108:111], v[196:199], v[210:213], v[108:111]
	v_mfma_f32_16x16x32_bf16 v[104:107], v[200:203], v[210:213], v[104:107]
	v_lshl_add_u64 v[226:227], v[166:167], 0, s[12:13]
	v_mfma_f32_16x16x32_bf16 v[100:103], v[214:217], v[210:213], v[100:103]
	s_mov_b32 m0, s17
	v_mfma_f32_16x16x32_bf16 v[96:99], v[218:221], v[210:213], v[96:99]
	s_add_i32 s17, s17, 0x2000
	ds_read_b128 v[204:207], v230 offset:4096
	ds_read_b128 v[210:213], v230 offset:5120
	s_waitcnt lgkmcnt(2)
	v_mfma_f32_16x16x32_bf16 v[92:95], v[196:199], v[248:251], v[92:95]
	global_load_lds_dwordx4 v[226:227], off
	v_mfma_f32_16x16x32_bf16 v[88:91], v[200:203], v[248:251], v[88:91]
	v_mfma_f32_16x16x32_bf16 v[84:87], v[214:217], v[248:251], v[84:87]
	v_mfma_f32_16x16x32_bf16 v[80:83], v[218:221], v[248:251], v[80:83]
	v_mfma_f32_16x16x32_bf16 v[76:79], v[196:199], v[222:225], v[76:79]
	v_mfma_f32_16x16x32_bf16 v[72:75], v[200:203], v[222:225], v[72:75]
	v_lshl_add_u64 v[226:227], v[160:161], 0, s[12:13]
	v_mfma_f32_16x16x32_bf16 v[68:71], v[214:217], v[222:225], v[68:71]
	s_mov_b32 m0, s17
	v_mfma_f32_16x16x32_bf16 v[64:67], v[218:221], v[222:225], v[64:67]
	s_add_i32 s17, s17, 0x2000
	ds_read_b128 v[248:251], v230 offset:6144
	ds_read_b128 v[222:225], v230 offset:7168
	s_waitcnt lgkmcnt(2)
	v_mfma_f32_16x16x32_bf16 v[60:63], v[196:199], v[204:207], v[60:63]
	global_load_lds_dwordx4 v[226:227], off
	v_mfma_f32_16x16x32_bf16 v[56:59], v[200:203], v[204:207], v[56:59]
	v_mfma_f32_16x16x32_bf16 v[52:55], v[214:217], v[204:207], v[52:55]
	v_mfma_f32_16x16x32_bf16 v[48:51], v[218:221], v[204:207], v[48:51]
	v_mfma_f32_16x16x32_bf16 v[44:47], v[196:199], v[210:213], v[44:47]
	v_mfma_f32_16x16x32_bf16 v[40:43], v[200:203], v[210:213], v[40:43]
	v_lshl_add_u64 v[226:227], v[162:163], 0, s[12:13]
	v_mfma_f32_16x16x32_bf16 v[36:39], v[214:217], v[210:213], v[36:39]
	s_mov_b32 m0, s17
	v_mfma_f32_16x16x32_bf16 v[32:35], v[218:221], v[210:213], v[32:35]
	s_add_i32 s17, s17, 0x2000
	s_add_u32 s12, s12, 64
	s_addc_u32 s13, s13, 0
	s_add_i32 s5, s5, 0x8000
	s_and_b32 s5, s5, 0x18000
	s_waitcnt vmcnt(7) lgkmcnt(0)
	s_barrier
	v_add3_u32 v231, v183, v151, s5
	v_add3_u32 v230, v183, v153, s5
	s_nop 0
	ds_read_b128 v[232:235], v231 offset:16384
	ds_read_b128 v[236:239], v231 offset:17408
	ds_read_b128 v[240:243], v231 offset:18432
	ds_read_b128 v[244:247], v231 offset:19456
	ds_read_b128 v[204:207], v230
	ds_read_b128 v[210:213], v230 offset:1024
	v_mfma_f32_16x16x32_bf16 v[28:31], v[196:199], v[248:251], v[28:31]
	global_load_lds_dwordx4 v[226:227], off
	v_mfma_f32_16x16x32_bf16 v[24:27], v[200:203], v[248:251], v[24:27]
	v_mfma_f32_16x16x32_bf16 v[20:23], v[214:217], v[248:251], v[20:23]
	v_mfma_f32_16x16x32_bf16 v[16:19], v[218:221], v[248:251], v[16:19]
	v_mfma_f32_16x16x32_bf16 v[12:15], v[196:199], v[222:225], v[12:15]
	v_mfma_f32_16x16x32_bf16 v[8:11], v[200:203], v[222:225], v[8:11]
	v_mfma_f32_16x16x32_bf16 v[4:7], v[214:217], v[222:225], v[4:7]
	v_mfma_f32_16x16x32_bf16 v[0:3], v[218:221], v[222:225], v[0:3]
	ds_read_b128 v[248:251], v230 offset:2048
	ds_read_b128 v[222:225], v230 offset:3072
	s_waitcnt lgkmcnt(2)
	v_mfma_f32_16x16x32_bf16 v[124:127], v[232:235], v[204:207], v[124:127]
	v_mfma_f32_16x16x32_bf16 v[120:123], v[236:239], v[204:207], v[120:123]
	v_mfma_f32_16x16x32_bf16 v[116:119], v[240:243], v[204:207], v[116:119]
	v_mfma_f32_16x16x32_bf16 v[112:115], v[244:247], v[204:207], v[112:115]
	v_mfma_f32_16x16x32_bf16 v[108:111], v[232:235], v[210:213], v[108:111]
	v_mfma_f32_16x16x32_bf16 v[104:107], v[236:239], v[210:213], v[104:107]
	v_mfma_f32_16x16x32_bf16 v[100:103], v[240:243], v[210:213], v[100:103]
	v_mfma_f32_16x16x32_bf16 v[96:99], v[244:247], v[210:213], v[96:99]
	ds_read_b128 v[204:207], v230 offset:4096
	ds_read_b128 v[210:213], v230 offset:5120
	s_waitcnt lgkmcnt(2)
	v_mfma_f32_16x16x32_bf16 v[92:95], v[232:235], v[248:251], v[92:95]
	v_mfma_f32_16x16x32_bf16 v[88:91], v[236:239], v[248:251], v[88:91]
	v_mfma_f32_16x16x32_bf16 v[84:87], v[240:243], v[248:251], v[84:87]
	v_mfma_f32_16x16x32_bf16 v[80:83], v[244:247], v[248:251], v[80:83]
	v_mfma_f32_16x16x32_bf16 v[76:79], v[232:235], v[222:225], v[76:79]
	v_mfma_f32_16x16x32_bf16 v[72:75], v[236:239], v[222:225], v[72:75]
	v_mfma_f32_16x16x32_bf16 v[68:71], v[240:243], v[222:225], v[68:71]
	v_mfma_f32_16x16x32_bf16 v[64:67], v[244:247], v[222:225], v[64:67]
	ds_read_b128 v[248:251], v230 offset:6144
	ds_read_b128 v[222:225], v230 offset:7168
	s_waitcnt lgkmcnt(2)
	v_mfma_f32_16x16x32_bf16 v[60:63], v[232:235], v[204:207], v[60:63]
	v_mfma_f32_16x16x32_bf16 v[56:59], v[236:239], v[204:207], v[56:59]
	v_mfma_f32_16x16x32_bf16 v[52:55], v[240:243], v[204:207], v[52:55]
	v_mfma_f32_16x16x32_bf16 v[48:51], v[244:247], v[204:207], v[48:51]
	v_mfma_f32_16x16x32_bf16 v[44:47], v[232:235], v[210:213], v[44:47]
	v_mfma_f32_16x16x32_bf16 v[40:43], v[236:239], v[210:213], v[40:43]
	v_mfma_f32_16x16x32_bf16 v[36:39], v[240:243], v[210:213], v[36:39]
	v_mfma_f32_16x16x32_bf16 v[32:35], v[244:247], v[210:213], v[32:35]
	s_add_i32 s5, s5, 0x8000
	s_and_b32 s5, s5, 0x18000
	s_waitcnt vmcnt(4) lgkmcnt(0)
	s_barrier
; template <class Epi>
; DI void gemm_tile256(const u16* __restrict__ Ag, long lda, const u16* __restrict__ Bg, long ldb, int nk, char* shm, Epi&& epi) {
;     ...
;   for (int i = 0; i < nk; ++i) {
;     if (i + 2 < nk) asm volatile("s_waitcnt vmcnt(8)" ::: "memory");
;     else if (i + 1 < nk) asm volatile("s_waitcnt vmcnt(4)" ::: "memory");
;     else asm volatile("s_waitcnt vmcnt(0)" ::: "memory");
;     __builtin_amdgcn_s_barrier();
;     const char* SA = shm + (i & 3) * 32768; const char* SB = SA + 16384;
;     bf16x8 At[8], Bt[4];
; #pragma unroll
;     for (int n = 0; n < 4; ++n) { const int rb = wc * 64 + n * 16 + fr; Bt[n] = *reinterpret_cast<const bf16x8*>(SB + rb * 64 + ((fq ^ ((rb >> 2) & 3)) * 16)); }
; #pragma unroll
;     for (int m = 0; m < 8; ++m) { const int ra = wr * 128 + m * 16 + fr; At[m] = *reinterpret_cast<const bf16x8*>(SA + ra * 64 + ((fq ^ ((ra >> 2) & 3)) * 16)); }
;     if (i + 3 < nk) stage(i + 3);
; #pragma unroll
;     for (int m = 0; m < 8; ++m)
; #pragma unroll
;       for (int n = 0; n < 4; ++n) acc[m][n] = __builtin_amdgcn_mfma_f32_16x16x32_bf16(Bt[n], At[m], acc[m][n], 0, 0, 0);
;   }
	v_add3_u32 v231, v183, v151, s5
	v_add3_u32 v230, v183, v153, s5
	s_nop 0
	ds_read_b128 v[196:199], v231 offset:16384
	ds_read_b128 v[200:203], v231 offset:17408
	ds_read_b128 v[214:217], v231 offset:18432
	ds_read_b128 v[218:221], v231 offset:19456
	ds_read_b128 v[204:207], v230
	ds_read_b128 v[210:213], v230 offset:1024
	v_mfma_f32_16x16x32_bf16 v[28:31], v[232:235], v[248:251], v[28:31]
	v_mfma_f32_16x16x32_bf16 v[24:27], v[236:239], v[248:251], v[24:27]
	v_mfma_f32_16x16x32_bf16 v[20:23], v[240:243], v[248:251], v[20:23]
	v_mfma_f32_16x16x32_bf16 v[16:19], v[244:247], v[248:251], v[16:19]
	v_mfma_f32_16x16x32_bf16 v[12:15], v[232:235], v[222:225], v[12:15]
	v_mfma_f32_16x16x32_bf16 v[8:11], v[236:239], v[222:225], v[8:11]
	s_add_i32 s11, s5, 0x18000
	v_mfma_f32_16x16x32_bf16 v[4:7], v[240:243], v[222:225], v[4:7]
	s_and_b32 s11, s11, 0x18000
	v_mfma_f32_16x16x32_bf16 v[0:3], v[244:247], v[222:225], v[0:3]
	s_add_i32 s17, s11, s16
	v_lshl_add_u64 v[226:227], v[164:165], 0, s[12:13]
	s_mov_b32 m0, s17
	s_add_i32 s17, s17, 0x2000
	ds_read_b128 v[248:251], v230 offset:2048
	ds_read_b128 v[222:225], v230 offset:3072
	s_waitcnt lgkmcnt(2)
	v_mfma_f32_16x16x32_bf16 v[124:127], v[196:199], v[204:207], v[124:127]
	v_mfma_f32_16x16x32_bf16 v[120:123], v[200:203], v[204:207], v[120:123]
	v_mfma_f32_16x16x32_bf16 v[116:119], v[214:217], v[204:207], v[116:119]
	v_mfma_f32_16x16x32_bf16 v[112:115], v[218:221], v[204:207], v[112:115]
	v_mfma_f32_16x16x32_bf16 v[108:111], v[196:199], v[210:213], v[108:111]
	v_mfma_f32_16x16x32_bf16 v[104:107], v[200:203], v[210:213], v[104:107]
	v_mfma_f32_16x16x32_bf16 v[100:103], v[214:217], v[210:213], v[100:103]
	v_mfma_f32_16x16x32_bf16 v[96:99], v[218:221], v[210:213], v[96:99]
	ds_read_b128 v[204:207], v230 offset:4096
	ds_read_b128 v[210:213], v230 offset:5120
	s_waitcnt lgkmcnt(2)
	v_mfma_f32_16x16x32_bf16 v[92:95], v[196:199], v[248:251], v[92:95]
	v_mfma_f32_16x16x32_bf16 v[88:91], v[200:203], v[248:251], v[88:91]
	v_mfma_f32_16x16x32_bf16 v[84:87], v[214:217], v[248:251], v[84:87]
	v_mfma_f32_16x16x32_bf16 v[80:83], v[218:221], v[248:251], v[80:83]
	v_mfma_f32_16x16x32_bf16 v[76:79], v[196:199], v[222:225], v[76:79]
	v_mfma_f32_16x16x32_bf16 v[72:75], v[200:203], v[222:225], v[72:75]
	v_mfma_f32_16x16x32_bf16 v[68:71], v[214:217], v[222:225], v[68:71]
	v_mfma_f32_16x16x32_bf16 v[64:67], v[218:221], v[222:225], v[64:67]
	ds_read_b128 v[248:251], v230 offset:6144
	ds_read_b128 v[222:225], v230 offset:7168
	s_waitcnt lgkmcnt(2)
	v_mfma_f32_16x16x32_bf16 v[60:63], v[196:199], v[204:207], v[60:63]
	v_mfma_f32_16x16x32_bf16 v[56:59], v[200:203], v[204:207], v[56:59]
	v_mfma_f32_16x16x32_bf16 v[52:55], v[214:217], v[204:207], v[52:55]
	v_mfma_f32_16x16x32_bf16 v[48:51], v[218:221], v[204:207], v[48:51]
	v_mfma_f32_16x16x32_bf16 v[44:47], v[196:199], v[210:213], v[44:47]
	v_mfma_f32_16x16x32_bf16 v[40:43], v[200:203], v[210:213], v[40:43]
	v_mfma_f32_16x16x32_bf16 v[36:39], v[214:217], v[210:213], v[36:39]
	v_mfma_f32_16x16x32_bf16 v[32:35], v[218:221], v[210:213], v[32:35]
	s_add_i32 s5, s5, 0x8000
	s_and_b32 s5, s5, 0x18000
	s_waitcnt vmcnt(0) lgkmcnt(0)
	s_barrier
	v_add3_u32 v231, v183, v151, s5
	v_add3_u32 v230, v183, v153, s5
	s_nop 0
	ds_read_b128 v[232:235], v231 offset:16384
	ds_read_b128 v[236:239], v231 offset:17408
	ds_read_b128 v[240:243], v231 offset:18432
	ds_read_b128 v[244:247], v231 offset:19456
	ds_read_b128 v[204:207], v230
	ds_read_b128 v[210:213], v230 offset:1024
	v_mfma_f32_16x16x32_bf16 v[28:31], v[196:199], v[248:251], v[28:31]
	v_mfma_f32_16x16x32_bf16 v[24:27], v[200:203], v[248:251], v[24:27]
	v_mfma_f32_16x16x32_bf16 v[20:23], v[214:217], v[248:251], v[20:23]
	v_mfma_f32_16x16x32_bf16 v[16:19], v[218:221], v[248:251], v[16:19]
	v_mfma_f32_16x16x32_bf16 v[12:15], v[196:199], v[222:225], v[12:15]
	v_mfma_f32_16x16x32_bf16 v[8:11], v[200:203], v[222:225], v[8:11]
	s_add_i32 s11, s5, 0x18000
	v_mfma_f32_16x16x32_bf16 v[4:7], v[214:217], v[222:225], v[4:7]
	s_and_b32 s11, s11, 0x18000
	v_mfma_f32_16x16x32_bf16 v[0:3], v[218:221], v[222:225], v[0:3]
	s_add_i32 s17, s11, s16
	v_lshl_add_u64 v[226:227], v[164:165], 0, s[12:13]
	s_mov_b32 m0, s17
	s_add_i32 s17, s17, 0x2000
	ds_read_b128 v[248:251], v230 offset:2048
	ds_read_b128 v[222:225], v230 offset:3072
	s_waitcnt lgkmcnt(2)
	v_mfma_f32_16x16x32_bf16 v[124:127], v[232:235], v[204:207], v[124:127]
	v_mfma_f32_16x16x32_bf16 v[120:123], v[236:239], v[204:207], v[120:123]
	v_mfma_f32_16x16x32_bf16 v[116:119], v[240:243], v[204:207], v[116:119]
	v_mfma_f32_16x16x32_bf16 v[112:115], v[244:247], v[204:207], v[112:115]
	v_mfma_f32_16x16x32_bf16 v[108:111], v[232:235], v[210:213], v[108:111]
	v_mfma_f32_16x16x32_bf16 v[104:107], v[236:239], v[210:213], v[104:107]
	v_mfma_f32_16x16x32_bf16 v[100:103], v[240:243], v[210:213], v[100:103]
	v_mfma_f32_16x16x32_bf16 v[96:99], v[244:247], v[210:213], v[96:99]
	ds_read_b128 v[204:207], v230 offset:4096
	ds_read_b128 v[210:213], v230 offset:5120
	s_waitcnt lgkmcnt(2)
	v_mfma_f32_16x16x32_bf16 v[92:95], v[232:235], v[248:251], v[92:95]
	v_mfma_f32_16x16x32_bf16 v[88:91], v[236:239], v[248:251], v[88:91]
	v_mfma_f32_16x16x32_bf16 v[84:87], v[240:243], v[248:251], v[84:87]
	v_mfma_f32_16x16x32_bf16 v[80:83], v[244:247], v[248:251], v[80:83]
	v_mfma_f32_16x16x32_bf16 v[76:79], v[232:235], v[222:225], v[76:79]
	v_mfma_f32_16x16x32_bf16 v[72:75], v[236:239], v[222:225], v[72:75]
	v_mfma_f32_16x16x32_bf16 v[68:71], v[240:243], v[222:225], v[68:71]
	v_mfma_f32_16x16x32_bf16 v[64:67], v[244:247], v[222:225], v[64:67]
	ds_read_b128 v[248:251], v230 offset:6144
	ds_read_b128 v[222:225], v230 offset:7168
	s_waitcnt lgkmcnt(2)
	v_mfma_f32_16x16x32_bf16 v[60:63], v[232:235], v[204:207], v[60:63]
	v_mfma_f32_16x16x32_bf16 v[56:59], v[236:239], v[204:207], v[56:59]
	v_mfma_f32_16x16x32_bf16 v[52:55], v[240:243], v[204:207], v[52:55]
	v_mfma_f32_16x16x32_bf16 v[48:51], v[244:247], v[204:207], v[48:51]
	v_mfma_f32_16x16x32_bf16 v[44:47], v[232:235], v[210:213], v[44:47]
	v_mfma_f32_16x16x32_bf16 v[40:43], v[236:239], v[210:213], v[40:43]
	v_mfma_f32_16x16x32_bf16 v[36:39], v[240:243], v[210:213], v[36:39]
	v_mfma_f32_16x16x32_bf16 v[32:35], v[244:247], v[210:213], v[32:35]
	s_waitcnt lgkmcnt(0)
	v_mfma_f32_16x16x32_bf16 v[28:31], v[232:235], v[248:251], v[28:31]
	v_mfma_f32_16x16x32_bf16 v[24:27], v[236:239], v[248:251], v[24:27]
	v_mfma_f32_16x16x32_bf16 v[20:23], v[240:243], v[248:251], v[20:23]
	v_mfma_f32_16x16x32_bf16 v[16:19], v[244:247], v[248:251], v[16:19]
	v_mfma_f32_16x16x32_bf16 v[12:15], v[232:235], v[222:225], v[12:15]
	v_mfma_f32_16x16x32_bf16 v[8:11], v[236:239], v[222:225], v[8:11]
	s_add_i32 s11, s5, 0x18000
	v_mfma_f32_16x16x32_bf16 v[4:7], v[240:243], v[222:225], v[4:7]
	s_and_b32 s11, s11, 0x18000
	v_mfma_f32_16x16x32_bf16 v[0:3], v[244:247], v[222:225], v[0:3]
	s_add_i32 s17, s11, s16
	v_lshl_add_u64 v[226:227], v[164:165], 0, s[12:13]
	s_mov_b32 m0, s17
	s_add_i32 s17, s17, 0x2000

; template <class Epi>
; DI void gemm_tile256(const u16* __restrict__ Ag, long lda, const u16* __restrict__ Bg, long ldb, int nk, char* shm, Epi&& epi) {
;   const int tid = RTID, wid = tid >> 6, lane = tid & 63, wr = wid >> 2, wc = wid & 3, fr = lane & 15, fq = lane >> 4;
;   f32x4 acc[8][4];
; #pragma unroll
;   for (int m = 0; m < 8; ++m)
; #pragma unroll
;     for (int n = 0; n < 4; ++n) acc[m][n] = f32x4{0.f, 0.f, 0.f, 0.f};
;   const int q0 = tid, q1 = 512 + tid;
;   const int r0 = q0 >> 2, r1 = q1 >> 2, c0 = (q0 & 3) ^ ((r0 >> 2) & 3), c1 = (q1 & 3) ^ ((r1 >> 2) & 3);
;   const u16* a0 = Ag + (long)r0 * lda + c0 * 8; const u16* a1 = Ag + (long)r1 * lda + c1 * 8;
;   const u16* b0 = Bg + (long)r0 * ldb + c0 * 8; const u16* b1 = Bg + (long)r1 * ldb + c1 * 8;
;   auto stage = [&](int j) {
;     char* SA = shm + (j & 3) * 32768; char* SB = SA + 16384;
;     __builtin_amdgcn_global_load_lds((const unsigned*)(a0 + j * 32), (__attribute__((address_space(3))) unsigned*)(SA + q0 * 16), 16, 0, 0);
;     __builtin_amdgcn_global_load_lds((const unsigned*)(a1 + j * 32), (__attribute__((address_space(3))) unsigned*)(SA + q1 * 16), 16, 0, 0);
;     __builtin_amdgcn_global_load_lds((const unsigned*)(b0 + j * 32), (__attribute__((address_space(3))) unsigned*)(SB + q0 * 16), 16, 0, 0);
;     __builtin_amdgcn_global_load_lds((const unsigned*)(b1 + j * 32), (__attribute__((address_space(3))) unsigned*)(SB + q1 * 16), 16, 0, 0);
;   };
;   __syncthreads();
;   stage(0);
;   if (nk > 1) stage(1);
;   if (nk > 2) stage(2);
; DI void phase8(const Params& P, char* smem) {
;     ...
;   for (int q = RBLK >> 3; q < 128; q += RGRID >> 3) {
;     const int brow = q * 256, bcol = (RBLK & 7) * 256;
;     gemm_tile256(h1b + (long)brow * 1024, 1024, WqT + (long)bcol * 1024, 1024, 32, smem, [&](int row, int col0, f32x4 v) {
.LBB0_1068:
	s_ashr_i32 s7, s6, 31
	s_lshl_b64 s[10:11], s[6:7], 11
	v_lshl_add_u64 v[158:159], v[150:151], 0, s[10:11]
	v_lshl_add_u64 v[160:161], v[152:153], 0, s[10:11]
	s_lshl_b32 s10, s75, 8
	s_ashr_i32 s11, s10, 31
	s_lshl_b64 s[12:13], s[10:11], 11
	s_add_u32 s12, s40, s12
	s_addc_u32 s13, s41, s13
	v_add_u32_e32 v6, 0, v209
	v_lshl_add_u64 v[0:1], s[12:13], 0, v[130:131]
	v_readfirstlane_b32 s7, v6
	v_add_u32_e32 v7, 0, v162
	v_lshl_add_u64 v[0:1], v[0:1], 0, v[132:133]
	v_lshl_add_u64 v[2:3], s[12:13], 0, v[134:135]
	s_mov_b32 m0, s7
	v_readfirstlane_b32 s7, v7
	v_add_u32_e32 v4, 0x4000, v6
	v_lshl_add_u64 v[2:3], v[2:3], 0, v[132:133]
	s_barrier
	global_load_lds_dwordx4 v[0:1], off
	s_mov_b32 m0, s7
	v_readfirstlane_b32 s7, v4
	v_add_u32_e32 v4, 0x4000, v7
	global_load_lds_dwordx4 v[2:3], off
	s_mov_b32 m0, s7
	v_readfirstlane_b32 s7, v4
	v_add_u32_e32 v8, 0x8000, v6
	global_load_lds_dwordx4 v[136:137], off
	s_mov_b32 m0, s7
	v_readfirstlane_b32 s7, v8
	v_add_u32_e32 v8, 0x8000, v7
	global_load_lds_dwordx4 v[138:139], off
	v_lshl_add_u64 v[4:5], v[0:1], 0, 64
	s_mov_b32 m0, s7
	v_readfirstlane_b32 s7, v8
	global_load_lds_dwordx4 v[4:5], off
	v_lshl_add_u64 v[4:5], v[2:3], 0, 64
	s_mov_b32 m0, s7
	v_lshl_add_u64 v[0:1], v[0:1], 0, s[0:1]
	global_load_lds_dwordx4 v[4:5], off
	v_add_u32_e32 v4, 0xc000, v6
	s_mov_b64 s[12:13], 0
	v_readfirstlane_b32 s7, v4
	v_add_u32_e32 v4, 0xc000, v7
	s_mov_b32 m0, s7
	v_readfirstlane_b32 s7, v4
	v_add_u32_e32 v4, s2, v209
	global_load_lds_dwordx4 v[140:141], off
	s_mov_b32 m0, s7
	v_readfirstlane_b32 s7, v4
	global_load_lds_dwordx4 v[142:143], off
	s_mov_b32 m0, s7
	v_mov_b32_e32 v4, 0
	global_load_lds_dwordx4 v[0:1], off
	v_lshl_add_u64 v[0:1], v[2:3], 0, s[0:1]
	v_add_u32_e32 v2, s2, v162
	v_mov_b32_e32 v3, v133
	v_readfirstlane_b32 s7, v2
	s_mov_b32 m0, s7
	v_mov_b32_e32 v2, v133
	global_load_lds_dwordx4 v[0:1], off
	v_add_u32_e32 v0, s4, v209
	v_mov_b32_e32 v1, v133
	v_readfirstlane_b32 s7, v0
	v_add_u32_e32 v0, s4, v162
	s_mov_b32 m0, s7
	v_readfirstlane_b32 s7, v0
	global_load_lds_dwordx4 v[144:145], off
	s_mov_b32 m0, s7
	s_mov_b32 s7, 0x18000
	global_load_lds_dwordx4 v[146:147], off
	v_mov_b32_e32 v0, 0
	v_mov_b32_e32 v5, v133
	v_mov_b32_e32 v6, v133
	v_mov_b32_e32 v7, v133
	v_mov_b32_e32 v8, 0
	v_mov_b32_e32 v9, v133
	v_mov_b32_e32 v10, v133
	v_mov_b32_e32 v11, v133
	v_mov_b32_e32 v12, 0
	v_mov_b32_e32 v13, v133
	v_mov_b32_e32 v14, v133
	v_mov_b32_e32 v15, v133
	v_mov_b32_e32 v16, 0
	v_mov_b32_e32 v17, v133
	v_mov_b32_e32 v18, v133
	v_mov_b32_e32 v19, v133
	v_mov_b32_e32 v20, 0
	v_mov_b32_e32 v21, v133
	v_mov_b32_e32 v22, v133
	v_mov_b32_e32 v23, v133
	v_mov_b32_e32 v24, 0
	v_mov_b32_e32 v25, v133
	v_mov_b32_e32 v26, v133
	v_mov_b32_e32 v27, v133
	v_mov_b32_e32 v28, 0
	v_mov_b32_e32 v29, v133
	v_mov_b32_e32 v30, v133
	v_mov_b32_e32 v31, v133
	v_mov_b32_e32 v32, 0
	v_mov_b32_e32 v33, v133
	v_mov_b32_e32 v34, v133
	v_mov_b32_e32 v35, v133
	v_mov_b32_e32 v36, 0
	v_mov_b32_e32 v37, v133
	v_mov_b32_e32 v38, v133
	v_mov_b32_e32 v39, v133
	v_mov_b32_e32 v40, 0
	v_mov_b32_e32 v41, v133
	v_mov_b32_e32 v42, v133
	v_mov_b32_e32 v43, v133
	v_mov_b32_e32 v44, 0
	v_mov_b32_e32 v45, v133
	v_mov_b32_e32 v46, v133
	v_mov_b32_e32 v47, v133
	v_mov_b32_e32 v48, 0
	v_mov_b32_e32 v49, v133
	v_mov_b32_e32 v50, v133
	v_mov_b32_e32 v51, v133
	v_mov_b32_e32 v52, 0
	v_mov_b32_e32 v53, v133
	v_mov_b32_e32 v54, v133
	v_mov_b32_e32 v55, v133
	v_mov_b32_e32 v56, 0
	v_mov_b32_e32 v57, v133
	v_mov_b32_e32 v58, v133
	v_mov_b32_e32 v59, v133
	v_mov_b32_e32 v60, 0
	v_mov_b32_e32 v61, v133
	v_mov_b32_e32 v62, v133
	v_mov_b32_e32 v63, v133
	v_mov_b32_e32 v64, 0
	v_mov_b32_e32 v65, v133
	v_mov_b32_e32 v66, v133
	v_mov_b32_e32 v67, v133
	v_mov_b32_e32 v68, 0
	v_mov_b32_e32 v69, v133
	v_mov_b32_e32 v70, v133
	v_mov_b32_e32 v71, v133
	v_mov_b32_e32 v72, 0
	v_mov_b32_e32 v73, v133
	v_mov_b32_e32 v74, v133
	v_mov_b32_e32 v75, v133
	v_mov_b32_e32 v76, 0
	v_mov_b32_e32 v77, v133
	v_mov_b32_e32 v78, v133
	v_mov_b32_e32 v79, v133
	v_mov_b32_e32 v80, 0
	v_mov_b32_e32 v81, v133
	v_mov_b32_e32 v82, v133
	v_mov_b32_e32 v83, v133
	v_mov_b32_e32 v84, 0
	v_mov_b32_e32 v85, v133
	v_mov_b32_e32 v86, v133
	v_mov_b32_e32 v87, v133
	v_mov_b32_e32 v88, 0
	v_mov_b32_e32 v89, v133
	v_mov_b32_e32 v90, v133
	v_mov_b32_e32 v91, v133
	v_mov_b32_e32 v92, 0
	v_mov_b32_e32 v93, v133
	v_mov_b32_e32 v94, v133
	v_mov_b32_e32 v95, v133
	v_mov_b32_e32 v96, 0
	v_mov_b32_e32 v97, v133
	v_mov_b32_e32 v98, v133
	v_mov_b32_e32 v99, v133
	v_mov_b32_e32 v100, 0
	v_mov_b32_e32 v101, v133
	v_mov_b32_e32 v102, v133
	v_mov_b32_e32 v103, v133
	v_mov_b32_e32 v104, 0
	v_mov_b32_e32 v105, v133
	v_mov_b32_e32 v106, v133
	v_mov_b32_e32 v107, v133
	v_mov_b32_e32 v108, 0
	v_mov_b32_e32 v109, v133
	v_mov_b32_e32 v110, v133
	v_mov_b32_e32 v111, v133
	v_mov_b32_e32 v112, 0
	v_mov_b32_e32 v113, v133
	v_mov_b32_e32 v114, v133
	v_mov_b32_e32 v115, v133
	v_mov_b32_e32 v116, 0
	v_mov_b32_e32 v117, v133
	v_mov_b32_e32 v118, v133
	v_mov_b32_e32 v119, v133
	v_mov_b32_e32 v120, 0
	v_mov_b32_e32 v121, v133
	v_mov_b32_e32 v122, v133
	v_mov_b32_e32 v123, v133
	v_mov_b32_e32 v124, 0
	v_mov_b32_e32 v125, v133
	v_mov_b32_e32 v126, v133
	v_mov_b32_e32 v127, v133
	v_readfirstlane_b32 s11, v209
	s_mov_b32 s7, 0
	s_mov_b64 s[12:13], 0
	s_waitcnt vmcnt(8)
	s_barrier
	v_add3_u32 v187, v181, v163, s7
	v_add3_u32 v186, v181, v164, s7
	s_nop 0
	ds_read_b128 v[194:197], v187 offset:16384
	ds_read_b128 v[198:201], v187 offset:17408
	ds_read_b128 v[216:219], v187 offset:18432
	ds_read_b128 v[220:223], v187 offset:19456
	ds_read_b128 v[202:205], v186
	ds_read_b128 v[212:215], v186 offset:1024
	s_add_i32 s14, s11, 0x18000
	v_lshl_add_u64 v[206:207], v[158:159], 0, s[12:13]
	s_mov_b32 m0, s14
	s_add_i32 s14, s14, 0x2000
; template <class Epi>
; DI void gemm_tile256(const u16* __restrict__ Ag, long lda, const u16* __restrict__ Bg, long ldb, int nk, char* shm, Epi&& epi) {
;     ...
;   for (int i = 0; i < nk; ++i) {
;     if (i + 2 < nk) asm volatile("s_waitcnt vmcnt(8)" ::: "memory");
;     else if (i + 1 < nk) asm volatile("s_waitcnt vmcnt(4)" ::: "memory");
;     else asm volatile("s_waitcnt vmcnt(0)" ::: "memory");
;     __builtin_amdgcn_s_barrier();
;     const char* SA = shm + (i & 3) * 32768; const char* SB = SA + 16384;
;     bf16x8 At[8], Bt[4];
; #pragma unroll
;     for (int n = 0; n < 4; ++n) { const int rb = wc * 64 + n * 16 + fr; Bt[n] = *reinterpret_cast<const bf16x8*>(SB + rb * 64 + ((fq ^ ((rb >> 2) & 3)) * 16)); }
; #pragma unroll
;     for (int m = 0; m < 8; ++m) { const int ra = wr * 128 + m * 16 + fr; At[m] = *reinterpret_cast<const bf16x8*>(SA + ra * 64 + ((fq ^ ((ra >> 2) & 3)) * 16)); }
;     if (i + 3 < nk) stage(i + 3);
; #pragma unroll
;     for (int m = 0; m < 8; ++m)
; #pragma unroll
;       for (int n = 0; n < 4; ++n) acc[m][n] = __builtin_amdgcn_mfma_f32_16x16x32_bf16(Bt[n], At[m], acc[m][n], 0, 0, 0);
;   }
.Lgemm_p8_kloop0:
	ds_read_b128 v[246:249], v186 offset:2048
	ds_read_b128 v[250:253], v186 offset:3072
	s_waitcnt lgkmcnt(2)
	v_mfma_f32_16x16x32_bf16 v[124:127], v[194:197], v[202:205], v[124:127]
	global_load_lds_dwordx4 v[206:207], off
	v_mfma_f32_16x16x32_bf16 v[120:123], v[198:201], v[202:205], v[120:123]
	v_mfma_f32_16x16x32_bf16 v[116:119], v[216:219], v[202:205], v[116:119]
	v_mfma_f32_16x16x32_bf16 v[112:115], v[220:223], v[202:205], v[112:115]
	v_mfma_f32_16x16x32_bf16 v[108:111], v[194:197], v[212:215], v[108:111]
	v_mfma_f32_16x16x32_bf16 v[104:107], v[198:201], v[212:215], v[104:107]
	v_lshl_add_u64 v[224:225], v[160:161], 0, s[12:13]
	v_mfma_f32_16x16x32_bf16 v[100:103], v[216:219], v[212:215], v[100:103]
	s_mov_b32 m0, s14
	v_mfma_f32_16x16x32_bf16 v[96:99], v[220:223], v[212:215], v[96:99]
	s_add_i32 s14, s14, 0x2000
	ds_read_b128 v[202:205], v186 offset:4096
	ds_read_b128 v[212:215], v186 offset:5120
	s_waitcnt lgkmcnt(2)
	v_mfma_f32_16x16x32_bf16 v[92:95], v[194:197], v[246:249], v[92:95]
	global_load_lds_dwordx4 v[224:225], off
	v_mfma_f32_16x16x32_bf16 v[88:91], v[198:201], v[246:249], v[88:91]
	v_mfma_f32_16x16x32_bf16 v[84:87], v[216:219], v[246:249], v[84:87]
	v_mfma_f32_16x16x32_bf16 v[80:83], v[220:223], v[246:249], v[80:83]
	v_mfma_f32_16x16x32_bf16 v[76:79], v[194:197], v[250:253], v[76:79]
	v_mfma_f32_16x16x32_bf16 v[72:75], v[198:201], v[250:253], v[72:75]
	v_lshl_add_u64 v[226:227], v[154:155], 0, s[12:13]
	v_mfma_f32_16x16x32_bf16 v[68:71], v[216:219], v[250:253], v[68:71]
	s_mov_b32 m0, s14
	v_mfma_f32_16x16x32_bf16 v[64:67], v[220:223], v[250:253], v[64:67]
	s_add_i32 s14, s14, 0x2000
	ds_read_b128 v[246:249], v186 offset:6144
	ds_read_b128 v[250:253], v186 offset:7168
	s_waitcnt lgkmcnt(2)
	v_mfma_f32_16x16x32_bf16 v[60:63], v[194:197], v[202:205], v[60:63]
	global_load_lds_dwordx4 v[226:227], off
	v_mfma_f32_16x16x32_bf16 v[56:59], v[198:201], v[202:205], v[56:59]
	v_mfma_f32_16x16x32_bf16 v[52:55], v[216:219], v[202:205], v[52:55]
	v_mfma_f32_16x16x32_bf16 v[48:51], v[220:223], v[202:205], v[48:51]
	v_mfma_f32_16x16x32_bf16 v[44:47], v[194:197], v[212:215], v[44:47]
	v_mfma_f32_16x16x32_bf16 v[40:43], v[198:201], v[212:215], v[40:43]
	v_lshl_add_u64 v[228:229], v[156:157], 0, s[12:13]
	v_mfma_f32_16x16x32_bf16 v[36:39], v[216:219], v[212:215], v[36:39]
	s_mov_b32 m0, s14
	v_mfma_f32_16x16x32_bf16 v[32:35], v[220:223], v[212:215], v[32:35]
	s_add_i32 s14, s14, 0x2000
	s_add_u32 s12, s12, 64
	s_addc_u32 s13, s13, 0
	s_add_i32 s7, s7, 0x8000
	s_and_b32 s7, s7, 0x18000
	s_waitcnt vmcnt(7) lgkmcnt(0)
	s_barrier
	v_add3_u32 v187, v181, v163, s7
	v_add3_u32 v186, v181, v164, s7
	s_nop 0
	ds_read_b128 v[230:233], v187 offset:16384
	ds_read_b128 v[234:237], v187 offset:17408
	ds_read_b128 v[238:241], v187 offset:18432
	ds_read_b128 v[242:245], v187 offset:19456
	ds_read_b128 v[202:205], v186
	ds_read_b128 v[212:215], v186 offset:1024
	v_mfma_f32_16x16x32_bf16 v[28:31], v[194:197], v[246:249], v[28:31]
	global_load_lds_dwordx4 v[228:229], off
	v_mfma_f32_16x16x32_bf16 v[24:27], v[198:201], v[246:249], v[24:27]
	v_mfma_f32_16x16x32_bf16 v[20:23], v[216:219], v[246:249], v[20:23]
	v_mfma_f32_16x16x32_bf16 v[16:19], v[220:223], v[246:249], v[16:19]
	v_mfma_f32_16x16x32_bf16 v[12:15], v[194:197], v[250:253], v[12:15]
	v_mfma_f32_16x16x32_bf16 v[8:11], v[198:201], v[250:253], v[8:11]
	s_add_i32 s9, s7, 0x18000
	v_mfma_f32_16x16x32_bf16 v[4:7], v[216:219], v[250:253], v[4:7]
	s_and_b32 s9, s9, 0x18000
	v_mfma_f32_16x16x32_bf16 v[0:3], v[220:223], v[250:253], v[0:3]
	s_add_i32 s14, s9, s11
	v_lshl_add_u64 v[206:207], v[158:159], 0, s[12:13]
	s_mov_b32 m0, s14
	s_add_i32 s14, s14, 0x2000
	ds_read_b128 v[246:249], v186 offset:2048
	ds_read_b128 v[250:253], v186 offset:3072
	s_waitcnt lgkmcnt(2)
	v_mfma_f32_16x16x32_bf16 v[124:127], v[230:233], v[202:205], v[124:127]
	global_load_lds_dwordx4 v[206:207], off
	v_mfma_f32_16x16x32_bf16 v[120:123], v[234:237], v[202:205], v[120:123]
	v_mfma_f32_16x16x32_bf16 v[116:119], v[238:241], v[202:205], v[116:119]
	v_mfma_f32_16x16x32_bf16 v[112:115], v[242:245], v[202:205], v[112:115]
	v_mfma_f32_16x16x32_bf16 v[108:111], v[230:233], v[212:215], v[108:111]
	v_mfma_f32_16x16x32_bf16 v[104:107], v[234:237], v[212:215], v[104:107]
	v_lshl_add_u64 v[224:225], v[160:161], 0, s[12:13]
	v_mfma_f32_16x16x32_bf16 v[100:103], v[238:241], v[212:215], v[100:103]
	s_mov_b32 m0, s14
	v_mfma_f32_16x16x32_bf16 v[96:99], v[242:245], v[212:215], v[96:99]
	s_add_i32 s14, s14, 0x2000
	ds_read_b128 v[202:205], v186 offset:4096
	ds_read_b128 v[212:215], v186 offset:5120
	s_waitcnt lgkmcnt(2)
	v_mfma_f32_16x16x32_bf16 v[92:95], v[230:233], v[246:249], v[92:95]
	global_load_lds_dwordx4 v[224:225], off
	v_mfma_f32_16x16x32_bf16 v[88:91], v[234:237], v[246:249], v[88:91]
	v_mfma_f32_16x16x32_bf16 v[84:87], v[238:241], v[246:249], v[84:87]
	v_mfma_f32_16x16x32_bf16 v[80:83], v[242:245], v[246:249], v[80:83]
	v_mfma_f32_16x16x32_bf16 v[76:79], v[230:233], v[250:253], v[76:79]
	v_mfma_f32_16x16x32_bf16 v[72:75], v[234:237], v[250:253], v[72:75]
	v_lshl_add_u64 v[226:227], v[154:155], 0, s[12:13]
	v_mfma_f32_16x16x32_bf16 v[68:71], v[238:241], v[250:253], v[68:71]
	s_mov_b32 m0, s14
	v_mfma_f32_16x16x32_bf16 v[64:67], v[242:245], v[250:253], v[64:67]
	s_add_i32 s14, s14, 0x2000
	ds_read_b128 v[246:249], v186 offset:6144
	ds_read_b128 v[250:253], v186 offset:7168
	s_waitcnt lgkmcnt(2)
	v_mfma_f32_16x16x32_bf16 v[60:63], v[230:233], v[202:205], v[60:63]
	global_load_lds_dwordx4 v[226:227], off
	v_mfma_f32_16x16x32_bf16 v[56:59], v[234:237], v[202:205], v[56:59]
	v_mfma_f32_16x16x32_bf16 v[52:55], v[238:241], v[202:205], v[52:55]
	v_mfma_f32_16x16x32_bf16 v[48:51], v[242:245], v[202:205], v[48:51]
	v_mfma_f32_16x16x32_bf16 v[44:47], v[230:233], v[212:215], v[44:47]
	v_mfma_f32_16x16x32_bf16 v[40:43], v[234:237], v[212:215], v[40:43]
	v_lshl_add_u64 v[228:229], v[156:157], 0, s[12:13]
	v_mfma_f32_16x16x32_bf16 v[36:39], v[238:241], v[212:215], v[36:39]
	s_mov_b32 m0, s14
	v_mfma_f32_16x16x32_bf16 v[32:35], v[242:245], v[212:215], v[32:35]
	s_add_i32 s14, s14, 0x2000
	s_add_u32 s12, s12, 64
	s_addc_u32 s13, s13, 0
	s_add_i32 s7, s7, 0x8000
	s_and_b32 s7, s7, 0x18000
	s_waitcnt vmcnt(7) lgkmcnt(0)
	s_barrier
; template <class Epi>
; DI void gemm_tile256(const u16* __restrict__ Ag, long lda, const u16* __restrict__ Bg, long ldb, int nk, char* shm, Epi&& epi) {
;     ...
;   for (int i = 0; i < nk; ++i) {
;     if (i + 2 < nk) asm volatile("s_waitcnt vmcnt(8)" ::: "memory");
;     else if (i + 1 < nk) asm volatile("s_waitcnt vmcnt(4)" ::: "memory");
;     else asm volatile("s_waitcnt vmcnt(0)" ::: "memory");
;     __builtin_amdgcn_s_barrier();
;     const char* SA = shm + (i & 3) * 32768; const char* SB = SA + 16384;
;     bf16x8 At[8], Bt[4];
; #pragma unroll
;     for (int n = 0; n < 4; ++n) { const int rb = wc * 64 + n * 16 + fr; Bt[n] = *reinterpret_cast<const bf16x8*>(SB + rb * 64 + ((fq ^ ((rb >> 2) & 3)) * 16)); }
; #pragma unroll
;     for (int m = 0; m < 8; ++m) { const int ra = wr * 128 + m * 16 + fr; At[m] = *reinterpret_cast<const bf16x8*>(SA + ra * 64 + ((fq ^ ((ra >> 2) & 3)) * 16)); }
;     if (i + 3 < nk) stage(i + 3);
; #pragma unroll
;     for (int m = 0; m < 8; ++m)
; #pragma unroll
;       for (int n = 0; n < 4; ++n) acc[m][n] = __builtin_amdgcn_mfma_f32_16x16x32_bf16(Bt[n], At[m], acc[m][n], 0, 0, 0);
;   }
	v_add3_u32 v187, v181, v163, s7
	v_add3_u32 v186, v181, v164, s7
	s_nop 0
	ds_read_b128 v[194:197], v187 offset:16384
	ds_read_b128 v[198:201], v187 offset:17408
	ds_read_b128 v[216:219], v187 offset:18432
	ds_read_b128 v[220:223], v187 offset:19456
	ds_read_b128 v[202:205], v186
	ds_read_b128 v[212:215], v186 offset:1024
	v_mfma_f32_16x16x32_bf16 v[28:31], v[230:233], v[246:249], v[28:31]
	global_load_lds_dwordx4 v[228:229], off
	v_mfma_f32_16x16x32_bf16 v[24:27], v[234:237], v[246:249], v[24:27]
	v_mfma_f32_16x16x32_bf16 v[20:23], v[238:241], v[246:249], v[20:23]
	v_mfma_f32_16x16x32_bf16 v[16:19], v[242:245], v[246:249], v[16:19]
	v_mfma_f32_16x16x32_bf16 v[12:15], v[230:233], v[250:253], v[12:15]
	v_mfma_f32_16x16x32_bf16 v[8:11], v[234:237], v[250:253], v[8:11]
	s_add_i32 s9, s7, 0x18000
	v_mfma_f32_16x16x32_bf16 v[4:7], v[238:241], v[250:253], v[4:7]
	s_and_b32 s9, s9, 0x18000
	v_mfma_f32_16x16x32_bf16 v[0:3], v[242:245], v[250:253], v[0:3]
	s_add_i32 s14, s9, s11
	v_lshl_add_u64 v[206:207], v[158:159], 0, s[12:13]
	s_mov_b32 m0, s14
	s_add_i32 s14, s14, 0x2000
	s_cmpk_lg_i32 s12, 0x700
	s_cbranch_scc1 .Lgemm_p8_kloop0
	ds_read_b128 v[246:249], v186 offset:2048
	ds_read_b128 v[250:253], v186 offset:3072
	s_waitcnt lgkmcnt(2)
	v_mfma_f32_16x16x32_bf16 v[124:127], v[194:197], v[202:205], v[124:127]
	global_load_lds_dwordx4 v[206:207], off
	v_mfma_f32_16x16x32_bf16 v[120:123], v[198:201], v[202:205], v[120:123]
	v_mfma_f32_16x16x32_bf16 v[116:119], v[216:219], v[202:205], v[116:119]
	v_mfma_f32_16x16x32_bf16 v[112:115], v[220:223], v[202:205], v[112:115]
	v_mfma_f32_16x16x32_bf16 v[108:111], v[194:197], v[212:215], v[108:111]
	v_mfma_f32_16x16x32_bf16 v[104:107], v[198:201], v[212:215], v[104:107]
	v_lshl_add_u64 v[224:225], v[160:161], 0, s[12:13]
	v_mfma_f32_16x16x32_bf16 v[100:103], v[216:219], v[212:215], v[100:103]
	s_mov_b32 m0, s14
	v_mfma_f32_16x16x32_bf16 v[96:99], v[220:223], v[212:215], v[96:99]
	s_add_i32 s14, s14, 0x2000
	ds_read_b128 v[202:205], v186 offset:4096
	ds_read_b128 v[212:215], v186 offset:5120
	s_waitcnt lgkmcnt(2)
	v_mfma_f32_16x16x32_bf16 v[92:95], v[194:197], v[246:249], v[92:95]
	global_load_lds_dwordx4 v[224:225], off
	v_mfma_f32_16x16x32_bf16 v[88:91], v[198:201], v[246:249], v[88:91]
	v_mfma_f32_16x16x32_bf16 v[84:87], v[216:219], v[246:249], v[84:87]
	v_mfma_f32_16x16x32_bf16 v[80:83], v[220:223], v[246:249], v[80:83]
	v_mfma_f32_16x16x32_bf16 v[76:79], v[194:197], v[250:253], v[76:79]
	v_mfma_f32_16x16x32_bf16 v[72:75], v[198:201], v[250:253], v[72:75]
	v_lshl_add_u64 v[226:227], v[154:155], 0, s[12:13]
	v_mfma_f32_16x16x32_bf16 v[68:71], v[216:219], v[250:253], v[68:71]
	s_mov_b32 m0, s14
	v_mfma_f32_16x16x32_bf16 v[64:67], v[220:223], v[250:253], v[64:67]
	s_add_i32 s14, s14, 0x2000
	ds_read_b128 v[246:249], v186 offset:6144
	ds_read_b128 v[250:253], v186 offset:7168
	s_waitcnt lgkmcnt(2)
	v_mfma_f32_16x16x32_bf16 v[60:63], v[194:197], v[202:205], v[60:63]
	global_load_lds_dwordx4 v[226:227], off
	v_mfma_f32_16x16x32_bf16 v[56:59], v[198:201], v[202:205], v[56:59]
	v_mfma_f32_16x16x32_bf16 v[52:55], v[216:219], v[202:205], v[52:55]
	v_mfma_f32_16x16x32_bf16 v[48:51], v[220:223], v[202:205], v[48:51]
	v_mfma_f32_16x16x32_bf16 v[44:47], v[194:197], v[212:215], v[44:47]
	v_mfma_f32_16x16x32_bf16 v[40:43], v[198:201], v[212:215], v[40:43]
	v_lshl_add_u64 v[228:229], v[156:157], 0, s[12:13]
	v_mfma_f32_16x16x32_bf16 v[36:39], v[216:219], v[212:215], v[36:39]
	s_mov_b32 m0, s14
	v_mfma_f32_16x16x32_bf16 v[32:35], v[220:223], v[212:215], v[32:35]
	s_add_i32 s14, s14, 0x2000
	s_add_u32 s12, s12, 64
	s_addc_u32 s13, s13, 0
	s_add_i32 s7, s7, 0x8000
	s_and_b32 s7, s7, 0x18000
	s_waitcnt vmcnt(7) lgkmcnt(0)
	s_barrier
	v_add3_u32 v187, v181, v163, s7
	v_add3_u32 v186, v181, v164, s7
	s_nop 0
	ds_read_b128 v[230:233], v187 offset:16384
	ds_read_b128 v[234:237], v187 offset:17408
	ds_read_b128 v[238:241], v187 offset:18432
	ds_read_b128 v[242:245], v187 offset:19456
	ds_read_b128 v[202:205], v186
	ds_read_b128 v[212:215], v186 offset:1024
	v_mfma_f32_16x16x32_bf16 v[28:31], v[194:197], v[246:249], v[28:31]
	global_load_lds_dwordx4 v[228:229], off
	v_mfma_f32_16x16x32_bf16 v[24:27], v[198:201], v[246:249], v[24:27]
	v_mfma_f32_16x16x32_bf16 v[20:23], v[216:219], v[246:249], v[20:23]
	v_mfma_f32_16x16x32_bf16 v[16:19], v[220:223], v[246:249], v[16:19]
	v_mfma_f32_16x16x32_bf16 v[12:15], v[194:197], v[250:253], v[12:15]
	v_mfma_f32_16x16x32_bf16 v[8:11], v[198:201], v[250:253], v[8:11]
	v_mfma_f32_16x16x32_bf16 v[4:7], v[216:219], v[250:253], v[4:7]
	v_mfma_f32_16x16x32_bf16 v[0:3], v[220:223], v[250:253], v[0:3]
	ds_read_b128 v[246:249], v186 offset:2048
	ds_read_b128 v[250:253], v186 offset:3072
	s_waitcnt lgkmcnt(2)
	v_mfma_f32_16x16x32_bf16 v[124:127], v[230:233], v[202:205], v[124:127]
	v_mfma_f32_16x16x32_bf16 v[120:123], v[234:237], v[202:205], v[120:123]
	v_mfma_f32_16x16x32_bf16 v[116:119], v[238:241], v[202:205], v[116:119]
	v_mfma_f32_16x16x32_bf16 v[112:115], v[242:245], v[202:205], v[112:115]
	v_mfma_f32_16x16x32_bf16 v[108:111], v[230:233], v[212:215], v[108:111]
	v_mfma_f32_16x16x32_bf16 v[104:107], v[234:237], v[212:215], v[104:107]
	v_mfma_f32_16x16x32_bf16 v[100:103], v[238:241], v[212:215], v[100:103]
	v_mfma_f32_16x16x32_bf16 v[96:99], v[242:245], v[212:215], v[96:99]
	ds_read_b128 v[202:205], v186 offset:4096
	ds_read_b128 v[212:215], v186 offset:5120
	s_waitcnt lgkmcnt(2)
	v_mfma_f32_16x16x32_bf16 v[92:95], v[230:233], v[246:249], v[92:95]
	v_mfma_f32_16x16x32_bf16 v[88:91], v[234:237], v[246:249], v[88:91]
	v_mfma_f32_16x16x32_bf16 v[84:87], v[238:241], v[246:249], v[84:87]
	v_mfma_f32_16x16x32_bf16 v[80:83], v[242:245], v[246:249], v[80:83]
	v_mfma_f32_16x16x32_bf16 v[76:79], v[230:233], v[250:253], v[76:79]
	v_mfma_f32_16x16x32_bf16 v[72:75], v[234:237], v[250:253], v[72:75]
	v_mfma_f32_16x16x32_bf16 v[68:71], v[238:241], v[250:253], v[68:71]
	v_mfma_f32_16x16x32_bf16 v[64:67], v[242:245], v[250:253], v[64:67]
	ds_read_b128 v[246:249], v186 offset:6144
	ds_read_b128 v[250:253], v186 offset:7168
	s_waitcnt lgkmcnt(2)
	v_mfma_f32_16x16x32_bf16 v[60:63], v[230:233], v[202:205], v[60:63]
	v_mfma_f32_16x16x32_bf16 v[56:59], v[234:237], v[202:205], v[56:59]
	v_mfma_f32_16x16x32_bf16 v[52:55], v[238:241], v[202:205], v[52:55]
	v_mfma_f32_16x16x32_bf16 v[48:51], v[242:245], v[202:205], v[48:51]
	v_mfma_f32_16x16x32_bf16 v[44:47], v[230:233], v[212:215], v[44:47]
	v_mfma_f32_16x16x32_bf16 v[40:43], v[234:237], v[212:215], v[40:43]
	v_mfma_f32_16x16x32_bf16 v[36:39], v[238:241], v[212:215], v[36:39]
	v_mfma_f32_16x16x32_bf16 v[32:35], v[242:245], v[212:215], v[32:35]
	s_add_i32 s7, s7, 0x8000
	s_and_b32 s7, s7, 0x18000
	s_waitcnt vmcnt(4) lgkmcnt(0)
	s_barrier
; template <class Epi>
; DI void gemm_tile256(const u16* __restrict__ Ag, long lda, const u16* __restrict__ Bg, long ldb, int nk, char* shm, Epi&& epi) {
;     ...
;   for (int i = 0; i < nk; ++i) {
;     if (i + 2 < nk) asm volatile("s_waitcnt vmcnt(8)" ::: "memory");
;     else if (i + 1 < nk) asm volatile("s_waitcnt vmcnt(4)" ::: "memory");
;     else asm volatile("s_waitcnt vmcnt(0)" ::: "memory");
;     __builtin_amdgcn_s_barrier();
;     const char* SA = shm + (i & 3) * 32768; const char* SB = SA + 16384;
;     bf16x8 At[8], Bt[4];
; #pragma unroll
;     for (int n = 0; n < 4; ++n) { const int rb = wc * 64 + n * 16 + fr; Bt[n] = *reinterpret_cast<const bf16x8*>(SB + rb * 64 + ((fq ^ ((rb >> 2) & 3)) * 16)); }
; #pragma unroll
;     for (int m = 0; m < 8; ++m) { const int ra = wr * 128 + m * 16 + fr; At[m] = *reinterpret_cast<const bf16x8*>(SA + ra * 64 + ((fq ^ ((ra >> 2) & 3)) * 16)); }
;     if (i + 3 < nk) stage(i + 3);
; #pragma unroll
;     for (int m = 0; m < 8; ++m)
; #pragma unroll
;       for (int n = 0; n < 4; ++n) acc[m][n] = __builtin_amdgcn_mfma_f32_16x16x32_bf16(Bt[n], At[m], acc[m][n], 0, 0, 0);
;   }
	v_add3_u32 v187, v181, v163, s7
	v_add3_u32 v186, v181, v164, s7
	s_nop 0
	ds_read_b128 v[194:197], v187 offset:16384
	ds_read_b128 v[198:201], v187 offset:17408
	ds_read_b128 v[216:219], v187 offset:18432
	ds_read_b128 v[220:223], v187 offset:19456
	ds_read_b128 v[202:205], v186
	ds_read_b128 v[212:215], v186 offset:1024
	v_mfma_f32_16x16x32_bf16 v[28:31], v[230:233], v[246:249], v[28:31]
	v_mfma_f32_16x16x32_bf16 v[24:27], v[234:237], v[246:249], v[24:27]
	v_mfma_f32_16x16x32_bf16 v[20:23], v[238:241], v[246:249], v[20:23]
	v_mfma_f32_16x16x32_bf16 v[16:19], v[242:245], v[246:249], v[16:19]
	v_mfma_f32_16x16x32_bf16 v[12:15], v[230:233], v[250:253], v[12:15]
	v_mfma_f32_16x16x32_bf16 v[8:11], v[234:237], v[250:253], v[8:11]
	s_add_i32 s9, s7, 0x18000
	v_mfma_f32_16x16x32_bf16 v[4:7], v[238:241], v[250:253], v[4:7]
	s_and_b32 s9, s9, 0x18000
	v_mfma_f32_16x16x32_bf16 v[0:3], v[242:245], v[250:253], v[0:3]
	s_add_i32 s14, s9, s11
	v_lshl_add_u64 v[206:207], v[158:159], 0, s[12:13]
	s_mov_b32 m0, s14
	s_add_i32 s14, s14, 0x2000
	ds_read_b128 v[246:249], v186 offset:2048
	ds_read_b128 v[250:253], v186 offset:3072
	s_waitcnt lgkmcnt(2)
	v_mfma_f32_16x16x32_bf16 v[124:127], v[194:197], v[202:205], v[124:127]
	v_mfma_f32_16x16x32_bf16 v[120:123], v[198:201], v[202:205], v[120:123]
	v_mfma_f32_16x16x32_bf16 v[116:119], v[216:219], v[202:205], v[116:119]
	v_mfma_f32_16x16x32_bf16 v[112:115], v[220:223], v[202:205], v[112:115]
	v_mfma_f32_16x16x32_bf16 v[108:111], v[194:197], v[212:215], v[108:111]
	v_mfma_f32_16x16x32_bf16 v[104:107], v[198:201], v[212:215], v[104:107]
	v_mfma_f32_16x16x32_bf16 v[100:103], v[216:219], v[212:215], v[100:103]
	v_mfma_f32_16x16x32_bf16 v[96:99], v[220:223], v[212:215], v[96:99]
	ds_read_b128 v[202:205], v186 offset:4096
	ds_read_b128 v[212:215], v186 offset:5120
	s_waitcnt lgkmcnt(2)
	v_mfma_f32_16x16x32_bf16 v[92:95], v[194:197], v[246:249], v[92:95]
	v_mfma_f32_16x16x32_bf16 v[88:91], v[198:201], v[246:249], v[88:91]
	v_mfma_f32_16x16x32_bf16 v[84:87], v[216:219], v[246:249], v[84:87]
	v_mfma_f32_16x16x32_bf16 v[80:83], v[220:223], v[246:249], v[80:83]
	v_mfma_f32_16x16x32_bf16 v[76:79], v[194:197], v[250:253], v[76:79]
	v_mfma_f32_16x16x32_bf16 v[72:75], v[198:201], v[250:253], v[72:75]
	v_mfma_f32_16x16x32_bf16 v[68:71], v[216:219], v[250:253], v[68:71]
	v_mfma_f32_16x16x32_bf16 v[64:67], v[220:223], v[250:253], v[64:67]
	ds_read_b128 v[246:249], v186 offset:6144
	ds_read_b128 v[250:253], v186 offset:7168
	s_waitcnt lgkmcnt(2)
	v_mfma_f32_16x16x32_bf16 v[60:63], v[194:197], v[202:205], v[60:63]
	v_mfma_f32_16x16x32_bf16 v[56:59], v[198:201], v[202:205], v[56:59]
	v_mfma_f32_16x16x32_bf16 v[52:55], v[216:219], v[202:205], v[52:55]
	v_mfma_f32_16x16x32_bf16 v[48:51], v[220:223], v[202:205], v[48:51]
	v_mfma_f32_16x16x32_bf16 v[44:47], v[194:197], v[212:215], v[44:47]
	v_mfma_f32_16x16x32_bf16 v[40:43], v[198:201], v[212:215], v[40:43]
	v_mfma_f32_16x16x32_bf16 v[36:39], v[216:219], v[212:215], v[36:39]
	v_mfma_f32_16x16x32_bf16 v[32:35], v[220:223], v[212:215], v[32:35]
	s_add_i32 s7, s7, 0x8000
	s_and_b32 s7, s7, 0x18000
	s_waitcnt vmcnt(0) lgkmcnt(0)
	s_barrier
	v_add3_u32 v187, v181, v163, s7
	v_add3_u32 v186, v181, v164, s7
	s_nop 0
	ds_read_b128 v[230:233], v187 offset:16384
	ds_read_b128 v[234:237], v187 offset:17408
	ds_read_b128 v[238:241], v187 offset:18432
	ds_read_b128 v[242:245], v187 offset:19456
	ds_read_b128 v[202:205], v186
	ds_read_b128 v[212:215], v186 offset:1024
	v_mfma_f32_16x16x32_bf16 v[28:31], v[194:197], v[246:249], v[28:31]
	v_mfma_f32_16x16x32_bf16 v[24:27], v[198:201], v[246:249], v[24:27]
	v_mfma_f32_16x16x32_bf16 v[20:23], v[216:219], v[246:249], v[20:23]
	v_mfma_f32_16x16x32_bf16 v[16:19], v[220:223], v[246:249], v[16:19]
	v_mfma_f32_16x16x32_bf16 v[12:15], v[194:197], v[250:253], v[12:15]
	v_mfma_f32_16x16x32_bf16 v[8:11], v[198:201], v[250:253], v[8:11]
	s_add_i32 s9, s7, 0x18000
	v_mfma_f32_16x16x32_bf16 v[4:7], v[216:219], v[250:253], v[4:7]
	s_and_b32 s9, s9, 0x18000
	v_mfma_f32_16x16x32_bf16 v[0:3], v[220:223], v[250:253], v[0:3]
	s_add_i32 s14, s9, s11
	v_lshl_add_u64 v[206:207], v[158:159], 0, s[12:13]
	s_mov_b32 m0, s14
	s_add_i32 s14, s14, 0x2000
	ds_read_b128 v[246:249], v186 offset:2048
	ds_read_b128 v[250:253], v186 offset:3072
	s_waitcnt lgkmcnt(2)
	v_mfma_f32_16x16x32_bf16 v[124:127], v[230:233], v[202:205], v[124:127]
	v_mfma_f32_16x16x32_bf16 v[120:123], v[234:237], v[202:205], v[120:123]
	v_mfma_f32_16x16x32_bf16 v[116:119], v[238:241], v[202:205], v[116:119]
	v_mfma_f32_16x16x32_bf16 v[112:115], v[242:245], v[202:205], v[112:115]
	v_mfma_f32_16x16x32_bf16 v[108:111], v[230:233], v[212:215], v[108:111]
	v_mfma_f32_16x16x32_bf16 v[104:107], v[234:237], v[212:215], v[104:107]
	v_mfma_f32_16x16x32_bf16 v[100:103], v[238:241], v[212:215], v[100:103]
	v_mfma_f32_16x16x32_bf16 v[96:99], v[242:245], v[212:215], v[96:99]
	ds_read_b128 v[202:205], v186 offset:4096
	ds_read_b128 v[212:215], v186 offset:5120
	s_waitcnt lgkmcnt(2)
	v_mfma_f32_16x16x32_bf16 v[92:95], v[230:233], v[246:249], v[92:95]
	v_mfma_f32_16x16x32_bf16 v[88:91], v[234:237], v[246:249], v[88:91]
	v_mfma_f32_16x16x32_bf16 v[84:87], v[238:241], v[246:249], v[84:87]
	v_mfma_f32_16x16x32_bf16 v[80:83], v[242:245], v[246:249], v[80:83]
	v_mfma_f32_16x16x32_bf16 v[76:79], v[230:233], v[250:253], v[76:79]
	v_mfma_f32_16x16x32_bf16 v[72:75], v[234:237], v[250:253], v[72:75]
	v_mfma_f32_16x16x32_bf16 v[68:71], v[238:241], v[250:253], v[68:71]
	v_mfma_f32_16x16x32_bf16 v[64:67], v[242:245], v[250:253], v[64:67]
	ds_read_b128 v[246:249], v186 offset:6144
	ds_read_b128 v[250:253], v186 offset:7168
	s_waitcnt lgkmcnt(2)
	v_mfma_f32_16x16x32_bf16 v[60:63], v[230:233], v[202:205], v[60:63]
	v_mfma_f32_16x16x32_bf16 v[56:59], v[234:237], v[202:205], v[56:59]
	v_mfma_f32_16x16x32_bf16 v[52:55], v[238:241], v[202:205], v[52:55]
	v_mfma_f32_16x16x32_bf16 v[48:51], v[242:245], v[202:205], v[48:51]
	v_mfma_f32_16x16x32_bf16 v[44:47], v[230:233], v[212:215], v[44:47]
	v_mfma_f32_16x16x32_bf16 v[40:43], v[234:237], v[212:215], v[40:43]
	v_mfma_f32_16x16x32_bf16 v[36:39], v[238:241], v[212:215], v[36:39]
	v_mfma_f32_16x16x32_bf16 v[32:35], v[242:245], v[212:215], v[32:35]
	s_waitcnt lgkmcnt(0)
	v_mfma_f32_16x16x32_bf16 v[28:31], v[230:233], v[246:249], v[28:31]
	v_mfma_f32_16x16x32_bf16 v[24:27], v[234:237], v[246:249], v[24:27]
	v_mfma_f32_16x16x32_bf16 v[20:23], v[238:241], v[246:249], v[20:23]
	v_mfma_f32_16x16x32_bf16 v[16:19], v[242:245], v[246:249], v[16:19]
	v_mfma_f32_16x16x32_bf16 v[12:15], v[230:233], v[250:253], v[12:15]
	v_mfma_f32_16x16x32_bf16 v[8:11], v[234:237], v[250:253], v[8:11]
	s_add_i32 s9, s7, 0x18000
	v_mfma_f32_16x16x32_bf16 v[4:7], v[238:241], v[250:253], v[4:7]
	s_and_b32 s9, s9, 0x18000
	v_mfma_f32_16x16x32_bf16 v[0:3], v[242:245], v[250:253], v[0:3]
	s_add_i32 s14, s9, s11
	v_lshl_add_u64 v[206:207], v[158:159], 0, s[12:13]
	s_mov_b32 m0, s14
	s_add_i32 s14, s14, 0x2000
